# speedup vs baseline: 1.0346x; 1.0109x over previous
; #define PG8_STAGE(bufoff, gbase, voff) do { _Pragma("unroll") for (int _i = 0; _i < 2; ++_i) \
;         __builtin_amdgcn_global_load_lds((const unsigned*)((const char*)(gbase) + (voff)[_i]), (PG8_LAS unsigned*)(lds + (bufoff) + ldsw + _i * 8192), 16, 0, 0); } while (0)
; #define PG8_LDA(dst, b, h) do { _Pragma("unroll") for (int m = 0; m < 4; ++m) _Pragma("unroll") for (int k = 0; k < 2; ++k) dst[m][k] = *(const PG8_LAS bf16x8*)(lds + PG8_SA(b, h) + aoff + m * 2048 + k * 1024); } while (0)
; #define PG8_LDB(dst, b, h) do { _Pragma("unroll") for (int n = 0; n < 2; ++n) _Pragma("unroll") for (int k = 0; k < 2; ++k) dst[n][k] = *(const PG8_LAS bf16x8*)(lds + PG8_SB(b, h) + boff + n * 2048 + k * 1024); } while (0)
; #define PG8_SCHED __builtin_amdgcn_sched_barrier(0)
; template <class Epi, class Sched, bool ALIGN_EPI = false, bool SP2 = false>
; __device__ __forceinline__ void gemm_phase(PG8_LAS unsigned char* lds, const Gemm g, const Sched& S, const Epi& E, int wid_s_) {
;     ...
;         const bool has_next = S.next(ui + 1, nxt);
;         const char* nA = has_next ? (const char*)g.A + (size_t)nxt.pm * tstep : cA; const char* nB = has_next ? (const char*)g.Bt + (size_t)nxt.pn * tstep : cB;
;         for (int t = 0; t < nt; t += 2) {
;             const bool last = (t == nt - 2);
;             const char* a1 = cA + (size_t)(t + 1) * kstep;
;             const char* a2 = last ? nA : cA + (size_t)(t + 2) * kstep; const char* b2 = last ? nB : cB + (size_t)(t + 2) * kstep;
;             const char* a3 = a2 + kstep; const char* b3 = b2 + kstep;
;             if (last && has_next) S.a_ready(nxt);
;             if constexpr (SP2) {
;             PG8_LDB(B0, 0, 0); PG8_LDB(B1, 0, 1); PG8_SCHED; PG8_LDA(At, 0, 0); PG8_STAGE(PG8_SA(1, 1), a1 + hstep, voffA);
;     ...
; #pragma unroll
;         for (int a = 0; a < 2; ++a)
; #pragma unroll
;             for (int b = 0; b < 2; ++b)
; #pragma unroll
;                 for (int m = 0; m < 4; ++m)
; #pragma unroll
;                     for (int n = 0; n < 2; ++n) acc[a][b][m][n] = (f32x4){0.f, 0.f, 0.f, 0.f};
;         cur = nxt; cA = nA; cB = nB; ++ui;
.LBB0_261:
	s_add_u32 vcc_lo, s2, 0x100
	s_addc_u32 vcc_hi, s3, 0
	s_add_u32 s2, s24, 0x80
	v_mov_b32_e32 v0, 0
	s_addc_u32 s3, s25, 0
	s_mov_b32 s24, 0
	v_mov_b32_e32 v1, v0
	v_mov_b32_e32 v2, v0
	v_mov_b32_e32 v3, v0
	v_mov_b32_e32 v4, v0
	v_mov_b32_e32 v5, v0
	v_mov_b32_e32 v6, v0
	v_mov_b32_e32 v7, v0
	v_mov_b32_e32 v8, v0
	v_mov_b32_e32 v9, v0
	v_mov_b32_e32 v10, v0
	v_mov_b32_e32 v11, v0
	v_mov_b32_e32 v12, v0
	v_mov_b32_e32 v13, v0
	v_mov_b32_e32 v14, v0
	v_mov_b32_e32 v15, v0
	v_mov_b32_e32 v24, v0
	v_mov_b32_e32 v25, v0
	v_mov_b32_e32 v26, v0
	v_mov_b32_e32 v27, v0
	v_mov_b32_e32 v28, v0
	v_mov_b32_e32 v29, v0
	v_mov_b32_e32 v30, v0
	v_mov_b32_e32 v31, v0
	v_mov_b32_e32 v40, v0
	v_mov_b32_e32 v41, v0
	v_mov_b32_e32 v42, v0
	v_mov_b32_e32 v43, v0
	v_mov_b32_e32 v44, v0
	v_mov_b32_e32 v45, v0
	v_mov_b32_e32 v46, v0
	v_mov_b32_e32 v47, v0
	v_mov_b32_e32 v16, v0
	v_mov_b32_e32 v17, v0
	v_mov_b32_e32 v18, v0
	v_mov_b32_e32 v19, v0
	v_mov_b32_e32 v20, v0
	v_mov_b32_e32 v21, v0
	v_mov_b32_e32 v22, v0
	v_mov_b32_e32 v23, v0
	v_mov_b32_e32 v32, v0
	v_mov_b32_e32 v33, v0
	v_mov_b32_e32 v34, v0
	v_mov_b32_e32 v35, v0
	v_mov_b32_e32 v36, v0
	v_mov_b32_e32 v37, v0
	v_mov_b32_e32 v38, v0
	v_mov_b32_e32 v39, v0
	v_mov_b32_e32 v48, v0
	v_mov_b32_e32 v49, v0
	v_mov_b32_e32 v50, v0
	v_mov_b32_e32 v51, v0
	v_mov_b32_e32 v52, v0
	v_mov_b32_e32 v53, v0
	v_mov_b32_e32 v54, v0
	v_mov_b32_e32 v55, v0
	v_mov_b32_e32 v56, v0
	v_mov_b32_e32 v57, v0
	v_mov_b32_e32 v58, v0
	v_mov_b32_e32 v59, v0
	v_mov_b32_e32 v60, v0
	v_mov_b32_e32 v61, v0
	v_mov_b32_e32 v62, v0
	v_mov_b32_e32 v63, v0
	v_mov_b32_e32 v64, v0
	v_mov_b32_e32 v65, v0
	v_mov_b32_e32 v66, v0
	v_mov_b32_e32 v67, v0
	v_mov_b32_e32 v68, v0
	v_mov_b32_e32 v69, v0
	v_mov_b32_e32 v70, v0
	v_mov_b32_e32 v71, v0
	v_mov_b32_e32 v72, v0
	v_mov_b32_e32 v73, v0
	v_mov_b32_e32 v74, v0
	v_mov_b32_e32 v75, v0
	v_mov_b32_e32 v80, v0
	v_mov_b32_e32 v81, v0
	v_mov_b32_e32 v82, v0
	v_mov_b32_e32 v83, v0
	v_mov_b32_e32 v88, v0
	v_mov_b32_e32 v89, v0
	v_mov_b32_e32 v90, v0
	v_mov_b32_e32 v91, v0
	v_mov_b32_e32 v100, v0
	v_mov_b32_e32 v101, v0
	v_mov_b32_e32 v102, v0
	v_mov_b32_e32 v103, v0
	v_mov_b32_e32 v108, v0
	v_mov_b32_e32 v109, v0
	v_mov_b32_e32 v110, v0
	v_mov_b32_e32 v111, v0
	v_mov_b32_e32 v116, v0
	v_mov_b32_e32 v117, v0
	v_mov_b32_e32 v118, v0
	v_mov_b32_e32 v119, v0
	v_mov_b32_e32 v76, v0
	v_mov_b32_e32 v77, v0
	v_mov_b32_e32 v78, v0
	v_mov_b32_e32 v79, v0
	v_mov_b32_e32 v84, v0
	v_mov_b32_e32 v85, v0
	v_mov_b32_e32 v86, v0
	v_mov_b32_e32 v87, v0
	v_mov_b32_e32 v92, v0
	v_mov_b32_e32 v93, v0
	v_mov_b32_e32 v94, v0
	v_mov_b32_e32 v95, v0
	v_mov_b32_e32 v104, v0
	v_mov_b32_e32 v105, v0
	v_mov_b32_e32 v106, v0
	v_mov_b32_e32 v107, v0
	v_mov_b32_e32 v112, v0
	v_mov_b32_e32 v113, v0
	v_mov_b32_e32 v114, v0
	v_mov_b32_e32 v115, v0
	v_mov_b32_e32 v120, v0
	v_mov_b32_e32 v121, v0
	v_mov_b32_e32 v122, v0
	v_mov_b32_e32 v123, v0
	v_mov_b32_e32 v124, v0
	v_mov_b32_e32 v125, v0
	v_mov_b32_e32 v126, v0
	v_mov_b32_e32 v127, v0
	v_mov_b32_e32 v128, v0
	v_mov_b32_e32 v129, v0
	v_mov_b32_e32 v130, v0
	v_mov_b32_e32 v131, v0
	v_add_u32_e32 v150, s10, v142
	v_add_u32_e32 v151, s10, v152
	v_add_u32_e32 v158, s10, v140
	v_add_u32_e32 v159, s10, v144
	v_add_u32_e32 v188, s42, v142
	v_add_u32_e32 v189, s42, v152
	v_add_u32_e32 v226, s42, v140
	v_add_u32_e32 v227, s42, v144
	v_add_u32_e32 v192, s42, v150
	v_add_u32_e32 v193, s42, v151
.LBB0_262:
	s_add_i32 s91, s24, 2
	s_add_u32 s14, s2, 0x80
	s_addc_u32 s25, s3, 0
	s_add_i32 s41, 16, 0x10000
	s_cmp_eq_u32 s88, s24
	s_cselect_b32 s25, s21, s25
	s_cselect_b32 s24, s20, s14
	v_add_u32_e32 v96, s41, v147
	s_cselect_b32 s79, s23, vcc_hi
	s_cselect_b32 s78, s22, vcc_lo
	s_add_i32 s14, 16, 0x14000
	ds_read_b128 v[132:135], v96
	ds_read_b128 v[136:139], v96 offset:1024
	ds_read_b128 v[160:163], v96 offset:2048
	ds_read_b128 v[164:167], v96 offset:3072
	v_add_u32_e32 v96, s14, v147
	ds_read_b128 v[168:171], v96
	ds_read_b128 v[172:175], v96 offset:1024
	ds_read_b128 v[176:179], v96 offset:2048
	ds_read_b128 v[180:183], v96 offset:3072
	s_add_i32 m0, s51, 0xc000
	ds_read_b128 v[194:197], v149
	ds_read_b128 v[198:201], v149 offset:1024
	ds_read_b128 v[202:205], v149 offset:2048
	ds_read_b128 v[206:209], v149 offset:3072
	ds_read_b128 v[210:213], v149 offset:4096
	ds_read_b128 v[214:217], v149 offset:5120
	ds_read_b128 v[218:221], v149 offset:6144
	ds_read_b128 v[222:225], v149 offset:7168
	global_load_lds_dwordx4 v156, s[2:3]
	s_add_i32 m0, s51, 0xe000
	s_nop 0
	global_load_lds_dwordx4 v154, s[2:3]
	s_waitcnt vmcnt(8)
	s_waitcnt lgkmcnt(0)
	s_barrier
; #define PG8_STAGE(bufoff, gbase, voff) do { _Pragma("unroll") for (int _i = 0; _i < 2; ++_i) \
;         __builtin_amdgcn_global_load_lds((const unsigned*)((const char*)(gbase) + (voff)[_i]), (PG8_LAS unsigned*)(lds + (bufoff) + ldsw + _i * 8192), 16, 0, 0); } while (0)
; #define PG8_LDA(dst, b, h) do { _Pragma("unroll") for (int m = 0; m < 4; ++m) _Pragma("unroll") for (int k = 0; k < 2; ++k) dst[m][k] = *(const PG8_LAS bf16x8*)(lds + PG8_SA(b, h) + aoff + m * 2048 + k * 1024); } while (0)
; #define PG8_LDB(dst, b, h) do { _Pragma("unroll") for (int n = 0; n < 2; ++n) _Pragma("unroll") for (int k = 0; k < 2; ++k) dst[n][k] = *(const PG8_LAS bf16x8*)(lds + PG8_SB(b, h) + boff + n * 2048 + k * 1024); } while (0)
; #define PG8_MMA(ai, bj, At, Bt) do { __builtin_amdgcn_s_setprio(1); _Pragma("unroll") for (int m = 0; m < 4; ++m) _Pragma("unroll") for (int n = 0; n < 2; ++n) _Pragma("unroll") for (int k = 0; k < 2; ++k) \
;         acc[ai][bj][m][n] = __builtin_amdgcn_mfma_f32_16x16x32_bf16(Bt[n][k], At[m][k], acc[ai][bj][m][n], 0, 0, 0); __builtin_amdgcn_s_setprio(0); } while (0)
; #define PG8_WAIT_V(n) asm volatile("s_waitcnt vmcnt(" #n ")" ::: "memory")
; #define PG8_WAIT_L(n) asm volatile("s_waitcnt lgkmcnt(" #n ")" ::: "memory")
; #define PG8_BAR __builtin_amdgcn_s_barrier()
; #define PG8_SCHED __builtin_amdgcn_sched_barrier(0)
; template <class Epi, class Sched, bool ALIGN_EPI = false, bool SP2 = false>
; __device__ __forceinline__ void gemm_phase(PG8_LAS unsigned char* lds, const Gemm g, const Sched& S, const Epi& E, int wid_s_) {
;     ...
;             PG8_LDB(B0, 0, 0); PG8_LDB(B1, 0, 1); PG8_SCHED; PG8_LDA(At, 0, 0); PG8_STAGE(PG8_SA(1, 1), a1 + hstep, voffA);
;             PG8_WAIT_V(8); PG8_WAIT_L(0); PG8_BAR; PG8_MMA(0, 0, At, B0); PG8_MMA(0, 1, At, B1); PG8_BAR; PG8_SCHED;
;             PG8_LDA(At, 0, 1); PG8_STAGE(PG8_SB(0, 0), b2, voffB); PG8_STAGE(PG8_SB(0, 1), b2 + hstep, voffB); PG8_STAGE(PG8_SA(0, 0), a2, voffA);
;             PG8_WAIT_V(8); PG8_WAIT_L(0); PG8_BAR; PG8_MMA(1, 0, At, B0); PG8_MMA(1, 1, At, B1); PG8_BAR; PG8_SCHED;
	s_setprio 1
	s_waitcnt lgkmcnt(0)
	v_mfma_f32_16x16x32_bf16 v[128:131], v[132:135], v[194:197], v[128:131]
	v_mfma_f32_16x16x32_bf16 v[124:127], v[160:163], v[194:197], v[124:127]
	v_mfma_f32_16x16x32_bf16 v[120:123], v[132:135], v[202:205], v[120:123]
	v_mfma_f32_16x16x32_bf16 v[112:115], v[160:163], v[202:205], v[112:115]
	v_mfma_f32_16x16x32_bf16 v[104:107], v[132:135], v[210:213], v[104:107]
	v_mfma_f32_16x16x32_bf16 v[92:95], v[160:163], v[210:213], v[92:95]
	v_mfma_f32_16x16x32_bf16 v[84:87], v[132:135], v[218:221], v[84:87]
	v_mfma_f32_16x16x32_bf16 v[76:79], v[160:163], v[218:221], v[76:79]
	v_mfma_f32_16x16x32_bf16 v[128:131], v[136:139], v[198:201], v[128:131]
	v_mfma_f32_16x16x32_bf16 v[124:127], v[164:167], v[198:201], v[124:127]
	v_mfma_f32_16x16x32_bf16 v[120:123], v[136:139], v[206:209], v[120:123]
	v_mfma_f32_16x16x32_bf16 v[112:115], v[164:167], v[206:209], v[112:115]
	v_mfma_f32_16x16x32_bf16 v[104:107], v[136:139], v[214:217], v[104:107]
	v_mfma_f32_16x16x32_bf16 v[92:95], v[164:167], v[214:217], v[92:95]
	v_mfma_f32_16x16x32_bf16 v[84:87], v[136:139], v[222:225], v[84:87]
	v_mfma_f32_16x16x32_bf16 v[76:79], v[164:167], v[222:225], v[76:79]
	s_setprio 0
	s_setprio 1
	v_mfma_f32_16x16x32_bf16 v[116:119], v[168:171], v[194:197], v[116:119]
	v_mfma_f32_16x16x32_bf16 v[108:111], v[176:179], v[194:197], v[108:111]
	v_mfma_f32_16x16x32_bf16 v[98:101], v[168:171], v[202:205], v[100:103]
	v_mfma_f32_16x16x32_bf16 v[88:91], v[176:179], v[202:205], v[88:91]
	v_mfma_f32_16x16x32_bf16 v[80:83], v[168:171], v[210:213], v[80:83]
	v_mfma_f32_16x16x32_bf16 v[72:75], v[176:179], v[210:213], v[72:75]
	v_mfma_f32_16x16x32_bf16 v[68:71], v[168:171], v[218:221], v[68:71]
	v_mfma_f32_16x16x32_bf16 v[64:67], v[176:179], v[218:221], v[64:67]
	v_mfma_f32_16x16x32_bf16 v[116:119], v[172:175], v[198:201], v[116:119]
	v_mfma_f32_16x16x32_bf16 v[108:111], v[180:183], v[198:201], v[108:111]
	v_mfma_f32_16x16x32_bf16 v[98:101], v[172:175], v[206:209], v[98:101]
	v_mfma_f32_16x16x32_bf16 v[88:91], v[180:183], v[206:209], v[88:91]
	v_mfma_f32_16x16x32_bf16 v[80:83], v[172:175], v[214:217], v[80:83]
	v_mfma_f32_16x16x32_bf16 v[72:75], v[180:183], v[214:217], v[72:75]
	v_mfma_f32_16x16x32_bf16 v[68:71], v[172:175], v[222:225], v[68:71]
	v_mfma_f32_16x16x32_bf16 v[64:67], v[180:183], v[222:225], v[64:67]
	s_setprio 0
	s_barrier
	s_add_i32 s41, s41, s50
	s_mov_b32 m0, s41
	ds_read_b128 v[194:197], v149 offset:16384
	ds_read_b128 v[198:201], v149 offset:17408
	ds_read_b128 v[202:205], v149 offset:18432
	ds_read_b128 v[206:209], v149 offset:19456
	ds_read_b128 v[210:213], v149 offset:20480
	ds_read_b128 v[214:217], v149 offset:21504
	ds_read_b128 v[218:221], v149 offset:22528
	ds_read_b128 v[222:225], v149 offset:23552
	global_load_lds_dwordx4 v142, s[78:79]
	s_add_i32 m0, s41, 0x2000
	s_add_i32 s14, s14, s50
	global_load_lds_dwordx4 v152, s[78:79]
	s_mov_b32 m0, s14
	s_nop 0
	global_load_lds_dwordx4 v150, s[78:79]
	s_add_i32 m0, s14, 0x2000
	s_nop 0
	global_load_lds_dwordx4 v151, s[78:79]
	s_mov_b32 m0, s51
	s_nop 0
	global_load_lds_dwordx4 v140, s[24:25]
	s_mov_b32 m0, s80
	s_nop 0
	global_load_lds_dwordx4 v144, s[24:25]
	s_waitcnt vmcnt(8)
	s_waitcnt lgkmcnt(0)
	s_barrier
	s_setprio 1
	s_waitcnt lgkmcnt(0)
	v_mfma_f32_16x16x32_bf16 v[60:63], v[132:135], v[194:197], v[60:63]
	v_mfma_f32_16x16x32_bf16 v[56:59], v[160:163], v[194:197], v[56:59]
	v_mfma_f32_16x16x32_bf16 v[52:55], v[132:135], v[202:205], v[52:55]
	v_mfma_f32_16x16x32_bf16 v[48:51], v[160:163], v[202:205], v[48:51]
	v_mfma_f32_16x16x32_bf16 v[36:39], v[132:135], v[210:213], v[36:39]
	v_mfma_f32_16x16x32_bf16 v[32:35], v[160:163], v[210:213], v[32:35]
	v_mfma_f32_16x16x32_bf16 v[20:23], v[132:135], v[218:221], v[20:23]
	v_mfma_f32_16x16x32_bf16 v[16:19], v[160:163], v[218:221], v[16:19]
	v_mfma_f32_16x16x32_bf16 v[60:63], v[136:139], v[198:201], v[60:63]
	v_mfma_f32_16x16x32_bf16 v[56:59], v[164:167], v[198:201], v[56:59]
	v_mfma_f32_16x16x32_bf16 v[52:55], v[136:139], v[206:209], v[52:55]
	v_mfma_f32_16x16x32_bf16 v[48:51], v[164:167], v[206:209], v[48:51]
	v_mfma_f32_16x16x32_bf16 v[36:39], v[136:139], v[214:217], v[36:39]
	v_mfma_f32_16x16x32_bf16 v[32:35], v[164:167], v[214:217], v[32:35]
	v_mfma_f32_16x16x32_bf16 v[20:23], v[136:139], v[222:225], v[20:23]
	v_mfma_f32_16x16x32_bf16 v[16:19], v[164:167], v[222:225], v[16:19]
	s_setprio 0
	s_setprio 1
	v_mfma_f32_16x16x32_bf16 v[44:47], v[168:171], v[194:197], v[44:47]
	v_mfma_f32_16x16x32_bf16 v[40:43], v[176:179], v[194:197], v[40:43]
	v_mfma_f32_16x16x32_bf16 v[28:31], v[168:171], v[202:205], v[28:31]
	v_mfma_f32_16x16x32_bf16 v[24:27], v[176:179], v[202:205], v[24:27]
	v_mfma_f32_16x16x32_bf16 v[12:15], v[168:171], v[210:213], v[12:15]
	v_mfma_f32_16x16x32_bf16 v[8:11], v[176:179], v[210:213], v[8:11]
	v_mfma_f32_16x16x32_bf16 v[4:7], v[168:171], v[218:221], v[4:7]
	v_mfma_f32_16x16x32_bf16 v[0:3], v[176:179], v[218:221], v[0:3]
	v_mfma_f32_16x16x32_bf16 v[44:47], v[172:175], v[198:201], v[44:47]
	v_mfma_f32_16x16x32_bf16 v[40:43], v[180:183], v[198:201], v[40:43]
	v_mfma_f32_16x16x32_bf16 v[28:31], v[172:175], v[206:209], v[28:31]
	v_mfma_f32_16x16x32_bf16 v[24:27], v[180:183], v[206:209], v[24:27]
	v_mfma_f32_16x16x32_bf16 v[12:15], v[172:175], v[214:217], v[12:15]
	v_mfma_f32_16x16x32_bf16 v[8:11], v[180:183], v[214:217], v[8:11]
	v_mfma_f32_16x16x32_bf16 v[4:7], v[172:175], v[222:225], v[4:7]
	v_mfma_f32_16x16x32_bf16 v[0:3], v[180:183], v[222:225], v[0:3]
	s_setprio 0
	s_barrier
; #define PG8_STAGE(bufoff, gbase, voff) do { _Pragma("unroll") for (int _i = 0; _i < 2; ++_i) \
;         __builtin_amdgcn_global_load_lds((const unsigned*)((const char*)(gbase) + (voff)[_i]), (PG8_LAS unsigned*)(lds + (bufoff) + ldsw + _i * 8192), 16, 0, 0); } while (0)
; #define PG8_LDA(dst, b, h) do { _Pragma("unroll") for (int m = 0; m < 4; ++m) _Pragma("unroll") for (int k = 0; k < 2; ++k) dst[m][k] = *(const PG8_LAS bf16x8*)(lds + PG8_SA(b, h) + aoff + m * 2048 + k * 1024); } while (0)
; #define PG8_LDB(dst, b, h) do { _Pragma("unroll") for (int n = 0; n < 2; ++n) _Pragma("unroll") for (int k = 0; k < 2; ++k) dst[n][k] = *(const PG8_LAS bf16x8*)(lds + PG8_SB(b, h) + boff + n * 2048 + k * 1024); } while (0)
; #define PG8_MMA(ai, bj, At, Bt) do { __builtin_amdgcn_s_setprio(1); _Pragma("unroll") for (int m = 0; m < 4; ++m) _Pragma("unroll") for (int n = 0; n < 2; ++n) _Pragma("unroll") for (int k = 0; k < 2; ++k) \
;         acc[ai][bj][m][n] = __builtin_amdgcn_mfma_f32_16x16x32_bf16(Bt[n][k], At[m][k], acc[ai][bj][m][n], 0, 0, 0); __builtin_amdgcn_s_setprio(0); } while (0)
; #define PG8_WAIT_V(n) asm volatile("s_waitcnt vmcnt(" #n ")" ::: "memory")
; #define PG8_WAIT_L(n) asm volatile("s_waitcnt lgkmcnt(" #n ")" ::: "memory")
; #define PG8_BAR __builtin_amdgcn_s_barrier()
; #define PG8_SCHED __builtin_amdgcn_sched_barrier(0)
; template <class Epi, class Sched, bool ALIGN_EPI = false, bool SP2 = false>
; __device__ __forceinline__ void gemm_phase(PG8_LAS unsigned char* lds, const Gemm g, const Sched& S, const Epi& E, int wid_s_) {
;     ...
;         for (int t = 0; t < nt; t += 2) {
;     ...
;             PG8_LDB(B0, 1, 0); PG8_LDB(B1, 1, 1); PG8_SCHED; PG8_LDA(At, 1, 0); PG8_STAGE(PG8_SA(0, 1), a2 + hstep, voffA);
;             PG8_WAIT_V(8); PG8_WAIT_L(0); PG8_BAR; PG8_MMA(0, 0, At, B0); PG8_MMA(0, 1, At, B1); PG8_BAR; PG8_SCHED;
;             PG8_LDA(At, 1, 1); PG8_STAGE(PG8_SB(1, 0), b3, voffB); PG8_STAGE(PG8_SB(1, 1), b3 + hstep, voffB); PG8_STAGE(PG8_SA(1, 0), a3, voffA);
;             PG8_WAIT_V(8); PG8_WAIT_L(0); PG8_BAR; PG8_MMA(1, 0, At, B0); PG8_MMA(1, 1, At, B1); PG8_BAR; PG8_SCHED;
	s_add_i32 s14, 16, 0x18000
	v_add_u32_e32 v96, s14, v147
	s_add_i32 s41, 16, 0x1c000
	ds_read_b128 v[132:135], v96
	ds_read_b128 v[136:139], v96 offset:1024
	ds_read_b128 v[160:163], v96 offset:2048
	ds_read_b128 v[164:167], v96 offset:3072
	v_add_u32_e32 v96, s41, v147
	ds_read_b128 v[168:171], v96
	ds_read_b128 v[172:175], v96 offset:1024
	ds_read_b128 v[176:179], v96 offset:2048
	ds_read_b128 v[180:183], v96 offset:3072
	s_mov_b32 m0, s81
	ds_read_b128 v[194:197], v149 offset:32768
	ds_read_b128 v[198:201], v149 offset:33792
	ds_read_b128 v[202:205], v149 offset:34816
	ds_read_b128 v[206:209], v149 offset:35840
	ds_read_b128 v[210:213], v149 offset:36864
	ds_read_b128 v[214:217], v149 offset:37888
	ds_read_b128 v[218:221], v149 offset:38912
	ds_read_b128 v[222:225], v149 offset:39936
	global_load_lds_dwordx4 v158, s[24:25]
	s_mov_b32 m0, s82
	s_nop 0
	global_load_lds_dwordx4 v159, s[24:25]
	s_waitcnt vmcnt(8)
	s_waitcnt lgkmcnt(0)
	s_barrier
	s_setprio 1
	s_waitcnt lgkmcnt(0)
	v_mfma_f32_16x16x32_bf16 v[128:131], v[132:135], v[194:197], v[128:131]
	v_mfma_f32_16x16x32_bf16 v[124:127], v[160:163], v[194:197], v[124:127]
	v_mfma_f32_16x16x32_bf16 v[120:123], v[132:135], v[202:205], v[120:123]
	v_mfma_f32_16x16x32_bf16 v[112:115], v[160:163], v[202:205], v[112:115]
	v_mfma_f32_16x16x32_bf16 v[102:105], v[132:135], v[210:213], v[104:107]
	v_mfma_f32_16x16x32_bf16 v[92:95], v[160:163], v[210:213], v[92:95]
	v_mfma_f32_16x16x32_bf16 v[84:87], v[132:135], v[218:221], v[84:87]
	v_mfma_f32_16x16x32_bf16 v[76:79], v[160:163], v[218:221], v[76:79]
	v_mfma_f32_16x16x32_bf16 v[128:131], v[136:139], v[198:201], v[128:131]
	v_mfma_f32_16x16x32_bf16 v[124:127], v[164:167], v[198:201], v[124:127]
	v_mfma_f32_16x16x32_bf16 v[120:123], v[136:139], v[206:209], v[120:123]
	v_mfma_f32_16x16x32_bf16 v[112:115], v[164:167], v[206:209], v[112:115]
	v_mfma_f32_16x16x32_bf16 v[104:107], v[136:139], v[214:217], v[102:105]
	v_mfma_f32_16x16x32_bf16 v[92:95], v[164:167], v[214:217], v[92:95]
	v_mfma_f32_16x16x32_bf16 v[84:87], v[136:139], v[222:225], v[84:87]
	v_mfma_f32_16x16x32_bf16 v[76:79], v[164:167], v[222:225], v[76:79]
	s_setprio 0
	s_setprio 1
	v_mfma_f32_16x16x32_bf16 v[116:119], v[168:171], v[194:197], v[116:119]
	v_mfma_f32_16x16x32_bf16 v[108:111], v[176:179], v[194:197], v[108:111]
	v_mfma_f32_16x16x32_bf16 v[98:101], v[168:171], v[202:205], v[98:101]
	v_mfma_f32_16x16x32_bf16 v[88:91], v[176:179], v[202:205], v[88:91]
	v_mfma_f32_16x16x32_bf16 v[80:83], v[168:171], v[210:213], v[80:83]
	v_mfma_f32_16x16x32_bf16 v[72:75], v[176:179], v[210:213], v[72:75]
	v_mfma_f32_16x16x32_bf16 v[68:71], v[168:171], v[218:221], v[68:71]
	v_mfma_f32_16x16x32_bf16 v[64:67], v[176:179], v[218:221], v[64:67]
	v_mfma_f32_16x16x32_bf16 v[116:119], v[172:175], v[198:201], v[116:119]
	v_mfma_f32_16x16x32_bf16 v[108:111], v[180:183], v[198:201], v[108:111]
	v_mfma_f32_16x16x32_bf16 v[100:103], v[172:175], v[206:209], v[98:101]
	v_mfma_f32_16x16x32_bf16 v[88:91], v[180:183], v[206:209], v[88:91]
	v_mfma_f32_16x16x32_bf16 v[80:83], v[172:175], v[214:217], v[80:83]
	v_mfma_f32_16x16x32_bf16 v[72:75], v[180:183], v[214:217], v[72:75]
	v_mfma_f32_16x16x32_bf16 v[68:71], v[172:175], v[222:225], v[68:71]
	v_mfma_f32_16x16x32_bf16 v[64:67], v[180:183], v[222:225], v[64:67]
	s_setprio 0
	s_barrier
	s_add_i32 s14, s14, s50
	s_mov_b32 m0, s14
	ds_read_b128 v[194:197], v149 offset:49152
	ds_read_b128 v[198:201], v149 offset:50176
	ds_read_b128 v[202:205], v149 offset:51200
	ds_read_b128 v[206:209], v149 offset:52224
	ds_read_b128 v[210:213], v149 offset:53248
	ds_read_b128 v[214:217], v149 offset:54272
	ds_read_b128 v[218:221], v149 offset:55296
	ds_read_b128 v[222:225], v149 offset:56320
	global_load_lds_dwordx4 v188, s[78:79]
	s_add_i32 m0, s14, 0x2000
	s_add_i32 s14, s41, s50
	global_load_lds_dwordx4 v189, s[78:79]
	s_mov_b32 m0, s14
	s_nop 0
	global_load_lds_dwordx4 v192, s[78:79]
	s_add_i32 m0, s14, 0x2000
	s_nop 0
	global_load_lds_dwordx4 v193, s[78:79]
	s_mov_b32 m0, s85
	s_nop 0
	global_load_lds_dwordx4 v226, s[24:25]
	s_mov_b32 m0, s86
	s_nop 0
	global_load_lds_dwordx4 v227, s[24:25]
	s_waitcnt vmcnt(8)
	s_waitcnt lgkmcnt(0)
	s_barrier
	s_setprio 1
	s_waitcnt lgkmcnt(0)
	v_mfma_f32_16x16x32_bf16 v[60:63], v[132:135], v[194:197], v[60:63]
	v_mfma_f32_16x16x32_bf16 v[56:59], v[160:163], v[194:197], v[56:59]
	v_mfma_f32_16x16x32_bf16 v[52:55], v[132:135], v[202:205], v[52:55]
	v_mfma_f32_16x16x32_bf16 v[48:51], v[160:163], v[202:205], v[48:51]
	v_mfma_f32_16x16x32_bf16 v[36:39], v[132:135], v[210:213], v[36:39]
	v_mfma_f32_16x16x32_bf16 v[32:35], v[160:163], v[210:213], v[32:35]
	v_mfma_f32_16x16x32_bf16 v[20:23], v[132:135], v[218:221], v[20:23]
	v_mfma_f32_16x16x32_bf16 v[16:19], v[160:163], v[218:221], v[16:19]
	v_mfma_f32_16x16x32_bf16 v[60:63], v[136:139], v[198:201], v[60:63]
	v_mfma_f32_16x16x32_bf16 v[56:59], v[164:167], v[198:201], v[56:59]
	v_mfma_f32_16x16x32_bf16 v[52:55], v[136:139], v[206:209], v[52:55]
	v_mfma_f32_16x16x32_bf16 v[48:51], v[164:167], v[206:209], v[48:51]
	v_mfma_f32_16x16x32_bf16 v[36:39], v[136:139], v[214:217], v[36:39]
	v_mfma_f32_16x16x32_bf16 v[32:35], v[164:167], v[214:217], v[32:35]
	v_mfma_f32_16x16x32_bf16 v[20:23], v[136:139], v[222:225], v[20:23]
	v_mfma_f32_16x16x32_bf16 v[16:19], v[164:167], v[222:225], v[16:19]
	s_setprio 0
	s_setprio 1
	v_mfma_f32_16x16x32_bf16 v[44:47], v[168:171], v[194:197], v[44:47]
	v_mfma_f32_16x16x32_bf16 v[40:43], v[176:179], v[194:197], v[40:43]
	v_mfma_f32_16x16x32_bf16 v[28:31], v[168:171], v[202:205], v[28:31]
	v_mfma_f32_16x16x32_bf16 v[24:27], v[176:179], v[202:205], v[24:27]
	v_mfma_f32_16x16x32_bf16 v[12:15], v[168:171], v[210:213], v[12:15]
	v_mfma_f32_16x16x32_bf16 v[8:11], v[176:179], v[210:213], v[8:11]
	v_mfma_f32_16x16x32_bf16 v[4:7], v[168:171], v[218:221], v[4:7]
	v_mfma_f32_16x16x32_bf16 v[0:3], v[176:179], v[218:221], v[0:3]
	v_mfma_f32_16x16x32_bf16 v[44:47], v[172:175], v[198:201], v[44:47]
	v_mfma_f32_16x16x32_bf16 v[40:43], v[180:183], v[198:201], v[40:43]
	v_mfma_f32_16x16x32_bf16 v[28:31], v[172:175], v[206:209], v[28:31]
	v_mfma_f32_16x16x32_bf16 v[24:27], v[180:183], v[206:209], v[24:27]
	v_mfma_f32_16x16x32_bf16 v[12:15], v[172:175], v[214:217], v[12:15]
	v_mfma_f32_16x16x32_bf16 v[8:11], v[180:183], v[214:217], v[8:11]
	v_mfma_f32_16x16x32_bf16 v[4:7], v[172:175], v[222:225], v[4:7]
	v_mfma_f32_16x16x32_bf16 v[0:3], v[180:183], v[222:225], v[0:3]
	s_setprio 0
	s_barrier
	s_add_u32 vcc_lo, vcc_lo, 0x100
	s_addc_u32 vcc_hi, vcc_hi, 0
	s_add_u32 s2, s2, 0x100
	s_addc_u32 s3, s3, 0
	s_cmp_ge_i32 s91, s87
	s_mov_b32 s24, s91
	s_cbranch_scc0 .LBB0_262
	v_add_u32_e32 v192, 64, v191
	s_and_b64 vcc, exec, s[18:19]
	s_cbranch_vccnz .LBB0_267
	s_branch .LBB0_268

; template <class Epi, class Sched, bool ALIGN_EPI = false, bool SP2 = false>
; __device__ __forceinline__ void gemm_phase(PG8_LAS unsigned char* lds, const Gemm g, const Sched& S, const Epi& E, int wid_s_) {
;     ...
;     for (int i = 0; i < 2; ++i) { int R, C; stage_rc(tid * 16 + i * 8192, R, C); const int Rb = Epi::PERM ? ((R & ~31) + perm32(R & 31)) : R;
;         voffA[i] = (unsigned)(R * K + C) * 2u; voffB[i] = (unsigned)(Rb * K + C) * 2u; }
;     const size_t kstep = (size_t)(BK * 2);
;     const size_t hstep = (size_t)HALF * K * 2;
;     const size_t tstep = 2 * hstep;
;     ...
;     f32x4 acc[2][2][4][2];
; #pragma unroll
;     for (int a = 0; a < 2; ++a)
; #pragma unroll
;         for (int b = 0; b < 2; ++b)
; #pragma unroll
;             for (int m = 0; m < 4; ++m)
; #pragma unroll
;                 for (int n = 0; n < 2; ++n) acc[a][b][m][n] = (f32x4){0.f, 0.f, 0.f, 0.f};
.LBB0_464:
	v_mov_b32_e32 v125, 0
	s_andn2_b64 vcc, exec, s[18:19]
	v_mov_b32_e32 v124, v125
	v_mov_b32_e32 v123, v125
	v_mov_b32_e32 v122, v125
	v_mov_b32_e32 v129, v125
	v_mov_b32_e32 v128, v125
	v_mov_b32_e32 v127, v125
	v_mov_b32_e32 v126, v125
	v_mov_b32_e32 v121, v125
	v_mov_b32_e32 v120, v125
	v_mov_b32_e32 v119, v125
	v_mov_b32_e32 v118, v125
	v_mov_b32_e32 v117, v125
	v_mov_b32_e32 v116, v125
	v_mov_b32_e32 v115, v125
	v_mov_b32_e32 v114, v125
	v_mov_b32_e32 v113, v125
	v_mov_b32_e32 v112, v125
	v_mov_b32_e32 v111, v125
	v_mov_b32_e32 v110, v125
	v_mov_b32_e32 v109, v125
	v_mov_b32_e32 v108, v125
	v_mov_b32_e32 v107, v125
	v_mov_b32_e32 v106, v125
	v_mov_b32_e32 v105, v125
	v_mov_b32_e32 v104, v125
	v_mov_b32_e32 v103, v125
	v_mov_b32_e32 v102, v125
	v_mov_b32_e32 v101, v125
	v_mov_b32_e32 v100, v125
	v_mov_b32_e32 v99, v125
	v_mov_b32_e32 v98, v125
	v_mov_b32_e32 v63, v125
	v_mov_b32_e32 v62, v125
	v_mov_b32_e32 v61, v125
	v_mov_b32_e32 v60, v125
	v_mov_b32_e32 v59, v125
	v_mov_b32_e32 v58, v125
	v_mov_b32_e32 v57, v125
	v_mov_b32_e32 v56, v125
	v_mov_b32_e32 v55, v125
	v_mov_b32_e32 v54, v125
	v_mov_b32_e32 v53, v125
	v_mov_b32_e32 v52, v125
	v_mov_b32_e32 v51, v125
	v_mov_b32_e32 v50, v125
	v_mov_b32_e32 v49, v125
	v_mov_b32_e32 v48, v125
	v_mov_b32_e32 v47, v125
	v_mov_b32_e32 v46, v125
	v_mov_b32_e32 v45, v125
	v_mov_b32_e32 v44, v125
	v_mov_b32_e32 v43, v125
	v_mov_b32_e32 v42, v125
	v_mov_b32_e32 v41, v125
	v_mov_b32_e32 v40, v125
	v_mov_b32_e32 v39, v125
	v_mov_b32_e32 v38, v125
	v_mov_b32_e32 v37, v125
	v_mov_b32_e32 v36, v125
	v_mov_b32_e32 v35, v125
	v_mov_b32_e32 v34, v125
	v_mov_b32_e32 v33, v125
	v_mov_b32_e32 v32, v125
	v_mov_b32_e32 v95, v125
	v_mov_b32_e32 v94, v125
	v_mov_b32_e32 v93, v125
	v_mov_b32_e32 v92, v125
	v_mov_b32_e32 v91, v125
	v_mov_b32_e32 v90, v125
	v_mov_b32_e32 v89, v125
	v_mov_b32_e32 v88, v125
	v_mov_b32_e32 v87, v125
	v_mov_b32_e32 v86, v125
	v_mov_b32_e32 v85, v125
	v_mov_b32_e32 v84, v125
	v_mov_b32_e32 v83, v125
	v_mov_b32_e32 v82, v125
	v_mov_b32_e32 v81, v125
	v_mov_b32_e32 v80, v125
	v_mov_b32_e32 v79, v125
	v_mov_b32_e32 v78, v125
	v_mov_b32_e32 v77, v125
	v_mov_b32_e32 v76, v125
	v_mov_b32_e32 v75, v125
	v_mov_b32_e32 v74, v125
	v_mov_b32_e32 v73, v125
	v_mov_b32_e32 v72, v125
	v_mov_b32_e32 v71, v125
	v_mov_b32_e32 v70, v125
	v_mov_b32_e32 v69, v125
	v_mov_b32_e32 v68, v125
	v_mov_b32_e32 v67, v125
	v_mov_b32_e32 v66, v125
	v_mov_b32_e32 v65, v125
	v_mov_b32_e32 v64, v125
	v_mov_b32_e32 v31, v125
	v_mov_b32_e32 v30, v125
	v_mov_b32_e32 v29, v125
	v_mov_b32_e32 v28, v125
	v_mov_b32_e32 v27, v125
	v_mov_b32_e32 v26, v125
	v_mov_b32_e32 v25, v125
	v_mov_b32_e32 v24, v125
	v_mov_b32_e32 v23, v125
	v_mov_b32_e32 v22, v125
	v_mov_b32_e32 v21, v125
	v_mov_b32_e32 v20, v125
	v_mov_b32_e32 v19, v125
	v_mov_b32_e32 v18, v125
	v_mov_b32_e32 v17, v125
	v_mov_b32_e32 v16, v125
	v_mov_b32_e32 v15, v125
	v_mov_b32_e32 v14, v125
	v_mov_b32_e32 v13, v125
	v_mov_b32_e32 v12, v125
	v_mov_b32_e32 v11, v125
	v_mov_b32_e32 v10, v125
	v_mov_b32_e32 v9, v125
	v_mov_b32_e32 v8, v125
	v_mov_b32_e32 v7, v125
	v_mov_b32_e32 v6, v125
	v_mov_b32_e32 v5, v125
	v_mov_b32_e32 v4, v125
	v_mov_b32_e32 v3, v125
	v_mov_b32_e32 v2, v125
	v_mov_b32_e32 v1, v125
	v_mov_b32_e32 v0, v125
	s_cbranch_vccnz .LBB0_468
	s_add_u32 s91, s24, 0x100
	s_addc_u32 vcc_lo, s25, 0
	s_add_u32 s24, s48, 0x80
	v_mov_b32_e32 v0, 0
	s_addc_u32 s25, s49, 0
	s_mov_b32 s48, 0
	v_mov_b32_e32 v1, v0
	v_mov_b32_e32 v2, v0
	v_mov_b32_e32 v3, v0
	v_mov_b32_e32 v4, v0
	v_mov_b32_e32 v5, v0
	v_mov_b32_e32 v6, v0
	v_mov_b32_e32 v7, v0
	v_mov_b32_e32 v8, v0
	v_mov_b32_e32 v9, v0
	v_mov_b32_e32 v10, v0
	v_mov_b32_e32 v11, v0
	v_mov_b32_e32 v12, v0
	v_mov_b32_e32 v13, v0
	v_mov_b32_e32 v14, v0
	v_mov_b32_e32 v15, v0
	v_mov_b32_e32 v16, v0
	v_mov_b32_e32 v17, v0
	v_mov_b32_e32 v18, v0
	v_mov_b32_e32 v19, v0
	v_mov_b32_e32 v20, v0
	v_mov_b32_e32 v21, v0
	v_mov_b32_e32 v22, v0
	v_mov_b32_e32 v23, v0
	v_mov_b32_e32 v24, v0
	v_mov_b32_e32 v25, v0
	v_mov_b32_e32 v26, v0
	v_mov_b32_e32 v27, v0
	v_mov_b32_e32 v28, v0
	v_mov_b32_e32 v29, v0
	v_mov_b32_e32 v30, v0
	v_mov_b32_e32 v31, v0
	v_mov_b32_e32 v64, v0
	v_mov_b32_e32 v65, v0
	v_mov_b32_e32 v66, v0
	v_mov_b32_e32 v67, v0
	v_mov_b32_e32 v68, v0
	v_mov_b32_e32 v69, v0
	v_mov_b32_e32 v70, v0
	v_mov_b32_e32 v71, v0
	v_mov_b32_e32 v72, v0
	v_mov_b32_e32 v73, v0
	v_mov_b32_e32 v74, v0
	v_mov_b32_e32 v75, v0
	v_mov_b32_e32 v76, v0
	v_mov_b32_e32 v77, v0
	v_mov_b32_e32 v78, v0
	v_mov_b32_e32 v79, v0
	v_mov_b32_e32 v80, v0
	v_mov_b32_e32 v81, v0
	v_mov_b32_e32 v82, v0
	v_mov_b32_e32 v83, v0
	v_mov_b32_e32 v84, v0
	v_mov_b32_e32 v85, v0
	v_mov_b32_e32 v86, v0
	v_mov_b32_e32 v87, v0
	v_mov_b32_e32 v88, v0
	v_mov_b32_e32 v89, v0
	v_mov_b32_e32 v90, v0
	v_mov_b32_e32 v91, v0
	v_mov_b32_e32 v92, v0
	v_mov_b32_e32 v93, v0
	v_mov_b32_e32 v94, v0
	v_mov_b32_e32 v95, v0
	v_mov_b32_e32 v32, v0
	v_mov_b32_e32 v33, v0
	v_mov_b32_e32 v34, v0
	v_mov_b32_e32 v35, v0
	v_mov_b32_e32 v36, v0
	v_mov_b32_e32 v37, v0
	v_mov_b32_e32 v38, v0
	v_mov_b32_e32 v39, v0
	v_mov_b32_e32 v40, v0
	v_mov_b32_e32 v41, v0
	v_mov_b32_e32 v42, v0
	v_mov_b32_e32 v43, v0
	v_mov_b32_e32 v44, v0
	v_mov_b32_e32 v45, v0
	v_mov_b32_e32 v46, v0
	v_mov_b32_e32 v47, v0
	v_mov_b32_e32 v48, v0
	v_mov_b32_e32 v49, v0
	v_mov_b32_e32 v50, v0
	v_mov_b32_e32 v51, v0
	v_mov_b32_e32 v52, v0
	v_mov_b32_e32 v53, v0
	v_mov_b32_e32 v54, v0
	v_mov_b32_e32 v55, v0
	v_mov_b32_e32 v56, v0
	v_mov_b32_e32 v57, v0
	v_mov_b32_e32 v58, v0
	v_mov_b32_e32 v59, v0
	v_mov_b32_e32 v60, v0
	v_mov_b32_e32 v61, v0
	v_mov_b32_e32 v62, v0
	v_mov_b32_e32 v63, v0
	v_mov_b32_e32 v98, v0
	v_mov_b32_e32 v99, v0
	v_mov_b32_e32 v100, v0
	v_mov_b32_e32 v101, v0
	v_mov_b32_e32 v102, v0
	v_mov_b32_e32 v103, v0
	v_mov_b32_e32 v104, v0
	v_mov_b32_e32 v105, v0
	v_mov_b32_e32 v106, v0
	v_mov_b32_e32 v107, v0
	v_mov_b32_e32 v108, v0
	v_mov_b32_e32 v109, v0
	v_mov_b32_e32 v110, v0
	v_mov_b32_e32 v111, v0
	v_mov_b32_e32 v112, v0
	v_mov_b32_e32 v113, v0
	v_mov_b32_e32 v114, v0
	v_mov_b32_e32 v115, v0
	v_mov_b32_e32 v116, v0
	v_mov_b32_e32 v117, v0
	v_mov_b32_e32 v118, v0
	v_mov_b32_e32 v119, v0
	v_mov_b32_e32 v120, v0
	v_mov_b32_e32 v121, v0
	v_mov_b32_e32 v126, v0
	v_mov_b32_e32 v127, v0
	v_mov_b32_e32 v128, v0
	v_mov_b32_e32 v129, v0
	v_mov_b32_e32 v122, v0
	v_mov_b32_e32 v123, v0
	v_mov_b32_e32 v124, v0
	v_mov_b32_e32 v125, v0
	v_add_u32_e32 v150, s8, v134
	v_add_u32_e32 v151, s8, v130
	v_add_u32_e32 v188, s8, v136
	v_add_u32_e32 v189, s8, v132
	v_add_u32_e32 v192, s42, v134
	v_add_u32_e32 v193, s42, v130
	v_add_u32_e32 v232, s42, v136
	v_add_u32_e32 v233, s42, v132
	v_add_u32_e32 v230, s42, v150
	v_add_u32_e32 v231, s42, v151
; #define PG8_STAGE(bufoff, gbase, voff) do { _Pragma("unroll") for (int _i = 0; _i < 2; ++_i) \
;         __builtin_amdgcn_global_load_lds((const unsigned*)((const char*)(gbase) + (voff)[_i]), (PG8_LAS unsigned*)(lds + (bufoff) + ldsw + _i * 8192), 16, 0, 0); } while (0)
; #define PG8_LDA(dst, b, h) do { _Pragma("unroll") for (int m = 0; m < 4; ++m) _Pragma("unroll") for (int k = 0; k < 2; ++k) dst[m][k] = *(const PG8_LAS bf16x8*)(lds + PG8_SA(b, h) + aoff + m * 2048 + k * 1024); } while (0)
; #define PG8_LDB(dst, b, h) do { _Pragma("unroll") for (int n = 0; n < 2; ++n) _Pragma("unroll") for (int k = 0; k < 2; ++k) dst[n][k] = *(const PG8_LAS bf16x8*)(lds + PG8_SB(b, h) + boff + n * 2048 + k * 1024); } while (0)
; #define PG8_MMA(ai, bj, At, Bt) do { __builtin_amdgcn_s_setprio(1); _Pragma("unroll") for (int m = 0; m < 4; ++m) _Pragma("unroll") for (int n = 0; n < 2; ++n) _Pragma("unroll") for (int k = 0; k < 2; ++k) \
;         acc[ai][bj][m][n] = __builtin_amdgcn_mfma_f32_16x16x32_bf16(Bt[n][k], At[m][k], acc[ai][bj][m][n], 0, 0, 0); __builtin_amdgcn_s_setprio(0); } while (0)
; #define PG8_WAIT_V(n) asm volatile("s_waitcnt vmcnt(" #n ")" ::: "memory")
; #define PG8_BAR __builtin_amdgcn_s_barrier()
; template <class Epi, class Sched, bool ALIGN_EPI = false, bool SP2 = false>
; __device__ __forceinline__ void gemm_phase(PG8_LAS unsigned char* lds, const Gemm g, const Sched& S, const Epi& E, int wid_s_) {
;     ...
;         for (int t = 0; t < nt; t += 2) {
;             const bool last = (t == nt - 2);
;             const char* a1 = cA + (size_t)(t + 1) * kstep;
;             const char* a2 = last ? nA : cA + (size_t)(t + 2) * kstep; const char* b2 = last ? nB : cB + (size_t)(t + 2) * kstep;
;             const char* a3 = a2 + kstep; const char* b3 = b2 + kstep;
;             if (last && has_next) S.a_ready(nxt);
;             if constexpr (SP2) {
;             PG8_LDB(B0, 0, 0); PG8_LDB(B1, 0, 1); PG8_SCHED; PG8_LDA(At, 0, 0); PG8_STAGE(PG8_SA(1, 1), a1 + hstep, voffA);
;             PG8_WAIT_V(8); PG8_WAIT_L(0); PG8_BAR; PG8_MMA(0, 0, At, B0); PG8_MMA(0, 1, At, B1); PG8_BAR; PG8_SCHED;
;             PG8_LDA(At, 0, 1); PG8_STAGE(PG8_SB(0, 0), b2, voffB); PG8_STAGE(PG8_SB(0, 1), b2 + hstep, voffB); PG8_STAGE(PG8_SA(0, 0), a2, voffA);
;             PG8_WAIT_V(8); PG8_WAIT_L(0); PG8_BAR; PG8_MMA(1, 0, At, B0); PG8_MMA(1, 1, At, B1); PG8_BAR; PG8_SCHED;
.LBB0_466:
	s_add_i32 vcc_hi, s48, 2
	s_add_u32 s78, s24, 0x80
	s_addc_u32 s49, s25, 0
	s_add_i32 s26, 16, 0x10000
	s_cmp_eq_u32 s85, s48
	s_cselect_b32 s49, s3, s49
	s_cselect_b32 s48, s2, s78
	v_add_u32_e32 v96, s26, v146
	s_cselect_b32 s79, s23, vcc_lo
	s_cselect_b32 s78, s22, s91
	s_add_i32 s37, 16, 0x14000
	ds_read_b128 v[156:159], v96
	ds_read_b128 v[160:163], v96 offset:1024
	ds_read_b128 v[164:167], v96 offset:2048
	ds_read_b128 v[168:171], v96 offset:3072
	v_add_u32_e32 v96, s37, v146
	ds_read_b128 v[172:175], v96
	ds_read_b128 v[176:179], v96 offset:1024
	ds_read_b128 v[180:183], v96 offset:2048
	ds_read_b128 v[194:197], v96 offset:3072
	s_add_i32 m0, s50, 0xc000
	ds_read_b128 v[198:201], v148
	ds_read_b128 v[202:205], v148 offset:1024
	ds_read_b128 v[206:209], v148 offset:2048
	ds_read_b128 v[210:213], v148 offset:3072
	ds_read_b128 v[214:217], v148 offset:4096
	ds_read_b128 v[218:221], v148 offset:5120
	ds_read_b128 v[222:225], v148 offset:6144
	ds_read_b128 v[226:229], v148 offset:7168
	global_load_lds_dwordx4 v154, s[24:25]
	s_add_i32 m0, s50, 0xe000
	s_nop 0
	global_load_lds_dwordx4 v152, s[24:25]
	s_waitcnt vmcnt(8)
	s_waitcnt lgkmcnt(0)
	s_barrier
	s_setprio 1
	s_waitcnt lgkmcnt(0)
	v_mfma_f32_16x16x32_bf16 v[122:125], v[156:159], v[198:201], v[122:125]
	v_mfma_f32_16x16x32_bf16 v[126:129], v[164:167], v[198:201], v[126:129]
	v_mfma_f32_16x16x32_bf16 v[118:121], v[156:159], v[206:209], v[118:121]
	v_mfma_f32_16x16x32_bf16 v[114:117], v[164:167], v[206:209], v[114:117]
	v_mfma_f32_16x16x32_bf16 v[110:113], v[156:159], v[214:217], v[110:113]
	v_mfma_f32_16x16x32_bf16 v[106:109], v[164:167], v[214:217], v[106:109]
	v_mfma_f32_16x16x32_bf16 v[102:105], v[156:159], v[222:225], v[102:105]
	v_mfma_f32_16x16x32_bf16 v[98:101], v[164:167], v[222:225], v[98:101]
	v_mfma_f32_16x16x32_bf16 v[122:125], v[160:163], v[202:205], v[122:125]
	v_mfma_f32_16x16x32_bf16 v[126:129], v[168:171], v[202:205], v[126:129]
	v_mfma_f32_16x16x32_bf16 v[118:121], v[160:163], v[210:213], v[118:121]
	v_mfma_f32_16x16x32_bf16 v[114:117], v[168:171], v[210:213], v[114:117]
	v_mfma_f32_16x16x32_bf16 v[110:113], v[160:163], v[218:221], v[110:113]
	v_mfma_f32_16x16x32_bf16 v[106:109], v[168:171], v[218:221], v[106:109]
	v_mfma_f32_16x16x32_bf16 v[102:105], v[160:163], v[226:229], v[102:105]
	v_mfma_f32_16x16x32_bf16 v[98:101], v[168:171], v[226:229], v[98:101]
	s_setprio 0
	s_setprio 1
	v_mfma_f32_16x16x32_bf16 v[60:63], v[172:175], v[198:201], v[60:63]
	v_mfma_f32_16x16x32_bf16 v[56:59], v[180:183], v[198:201], v[56:59]
	v_mfma_f32_16x16x32_bf16 v[52:55], v[172:175], v[206:209], v[52:55]
	v_mfma_f32_16x16x32_bf16 v[48:51], v[180:183], v[206:209], v[48:51]
	v_mfma_f32_16x16x32_bf16 v[44:47], v[172:175], v[214:217], v[44:47]
	v_mfma_f32_16x16x32_bf16 v[40:43], v[180:183], v[214:217], v[40:43]
	v_mfma_f32_16x16x32_bf16 v[36:39], v[172:175], v[222:225], v[36:39]
	v_mfma_f32_16x16x32_bf16 v[32:35], v[180:183], v[222:225], v[32:35]
	v_mfma_f32_16x16x32_bf16 v[60:63], v[176:179], v[202:205], v[60:63]
	v_mfma_f32_16x16x32_bf16 v[56:59], v[194:197], v[202:205], v[56:59]
	v_mfma_f32_16x16x32_bf16 v[52:55], v[176:179], v[210:213], v[52:55]
	v_mfma_f32_16x16x32_bf16 v[48:51], v[194:197], v[210:213], v[48:51]
	v_mfma_f32_16x16x32_bf16 v[44:47], v[176:179], v[218:221], v[44:47]
	v_mfma_f32_16x16x32_bf16 v[40:43], v[194:197], v[218:221], v[40:43]
	v_mfma_f32_16x16x32_bf16 v[36:39], v[176:179], v[226:229], v[36:39]
	v_mfma_f32_16x16x32_bf16 v[32:35], v[194:197], v[226:229], v[32:35]
	s_setprio 0
	s_barrier
	s_add_i32 s26, s26, s40
	s_mov_b32 m0, s26
	ds_read_b128 v[198:201], v148 offset:16384
	ds_read_b128 v[202:205], v148 offset:17408
	ds_read_b128 v[206:209], v148 offset:18432
	ds_read_b128 v[210:213], v148 offset:19456
	ds_read_b128 v[214:217], v148 offset:20480
	ds_read_b128 v[218:221], v148 offset:21504
	ds_read_b128 v[222:225], v148 offset:22528
	ds_read_b128 v[226:229], v148 offset:23552
	global_load_lds_dwordx4 v134, s[78:79]
	s_add_i32 m0, s26, 0x2000
	s_add_i32 s26, s37, s40
	global_load_lds_dwordx4 v130, s[78:79]
	s_mov_b32 m0, s26
	s_nop 0
	global_load_lds_dwordx4 v150, s[78:79]
	s_add_i32 m0, s26, 0x2000
	s_nop 0
	global_load_lds_dwordx4 v151, s[78:79]
	s_mov_b32 m0, s50
	s_nop 0
	global_load_lds_dwordx4 v136, s[48:49]
	s_mov_b32 m0, s51
	s_nop 0
	global_load_lds_dwordx4 v132, s[48:49]
	s_waitcnt vmcnt(8)
	s_waitcnt lgkmcnt(0)
	s_barrier
	s_setprio 1
	s_waitcnt lgkmcnt(0)
	v_mfma_f32_16x16x32_bf16 v[92:95], v[156:159], v[198:201], v[92:95]
	v_mfma_f32_16x16x32_bf16 v[88:91], v[164:167], v[198:201], v[88:91]
	v_mfma_f32_16x16x32_bf16 v[84:87], v[156:159], v[206:209], v[84:87]
	v_mfma_f32_16x16x32_bf16 v[80:83], v[164:167], v[206:209], v[80:83]
	v_mfma_f32_16x16x32_bf16 v[76:79], v[156:159], v[214:217], v[76:79]
	v_mfma_f32_16x16x32_bf16 v[72:75], v[164:167], v[214:217], v[72:75]
	v_mfma_f32_16x16x32_bf16 v[68:71], v[156:159], v[222:225], v[68:71]
	v_mfma_f32_16x16x32_bf16 v[64:67], v[164:167], v[222:225], v[64:67]
	v_mfma_f32_16x16x32_bf16 v[92:95], v[160:163], v[202:205], v[92:95]
	v_mfma_f32_16x16x32_bf16 v[88:91], v[168:171], v[202:205], v[88:91]
	v_mfma_f32_16x16x32_bf16 v[84:87], v[160:163], v[210:213], v[84:87]
	v_mfma_f32_16x16x32_bf16 v[80:83], v[168:171], v[210:213], v[80:83]
	v_mfma_f32_16x16x32_bf16 v[76:79], v[160:163], v[218:221], v[76:79]
	v_mfma_f32_16x16x32_bf16 v[72:75], v[168:171], v[218:221], v[72:75]
	v_mfma_f32_16x16x32_bf16 v[68:71], v[160:163], v[226:229], v[68:71]
	v_mfma_f32_16x16x32_bf16 v[64:67], v[168:171], v[226:229], v[64:67]
	s_setprio 0
	s_setprio 1
	v_mfma_f32_16x16x32_bf16 v[28:31], v[172:175], v[198:201], v[28:31]
	v_mfma_f32_16x16x32_bf16 v[24:27], v[180:183], v[198:201], v[24:27]
	v_mfma_f32_16x16x32_bf16 v[20:23], v[172:175], v[206:209], v[20:23]
	v_mfma_f32_16x16x32_bf16 v[16:19], v[180:183], v[206:209], v[16:19]
	v_mfma_f32_16x16x32_bf16 v[12:15], v[172:175], v[214:217], v[12:15]
	v_mfma_f32_16x16x32_bf16 v[8:11], v[180:183], v[214:217], v[8:11]
	v_mfma_f32_16x16x32_bf16 v[4:7], v[172:175], v[222:225], v[4:7]
	v_mfma_f32_16x16x32_bf16 v[0:3], v[180:183], v[222:225], v[0:3]
	v_mfma_f32_16x16x32_bf16 v[28:31], v[176:179], v[202:205], v[28:31]
	v_mfma_f32_16x16x32_bf16 v[24:27], v[194:197], v[202:205], v[24:27]
	v_mfma_f32_16x16x32_bf16 v[20:23], v[176:179], v[210:213], v[20:23]
	v_mfma_f32_16x16x32_bf16 v[16:19], v[194:197], v[210:213], v[16:19]
	v_mfma_f32_16x16x32_bf16 v[12:15], v[176:179], v[218:221], v[12:15]
	v_mfma_f32_16x16x32_bf16 v[8:11], v[194:197], v[218:221], v[8:11]
	v_mfma_f32_16x16x32_bf16 v[4:7], v[176:179], v[226:229], v[4:7]
	v_mfma_f32_16x16x32_bf16 v[0:3], v[194:197], v[226:229], v[0:3]
	s_setprio 0
	s_barrier
; #define PG8_STAGE(bufoff, gbase, voff) do { _Pragma("unroll") for (int _i = 0; _i < 2; ++_i) \
;         __builtin_amdgcn_global_load_lds((const unsigned*)((const char*)(gbase) + (voff)[_i]), (PG8_LAS unsigned*)(lds + (bufoff) + ldsw + _i * 8192), 16, 0, 0); } while (0)
; #define PG8_LDA(dst, b, h) do { _Pragma("unroll") for (int m = 0; m < 4; ++m) _Pragma("unroll") for (int k = 0; k < 2; ++k) dst[m][k] = *(const PG8_LAS bf16x8*)(lds + PG8_SA(b, h) + aoff + m * 2048 + k * 1024); } while (0)
; #define PG8_LDB(dst, b, h) do { _Pragma("unroll") for (int n = 0; n < 2; ++n) _Pragma("unroll") for (int k = 0; k < 2; ++k) dst[n][k] = *(const PG8_LAS bf16x8*)(lds + PG8_SB(b, h) + boff + n * 2048 + k * 1024); } while (0)
; #define PG8_MMA(ai, bj, At, Bt) do { __builtin_amdgcn_s_setprio(1); _Pragma("unroll") for (int m = 0; m < 4; ++m) _Pragma("unroll") for (int n = 0; n < 2; ++n) _Pragma("unroll") for (int k = 0; k < 2; ++k) \
;         acc[ai][bj][m][n] = __builtin_amdgcn_mfma_f32_16x16x32_bf16(Bt[n][k], At[m][k], acc[ai][bj][m][n], 0, 0, 0); __builtin_amdgcn_s_setprio(0); } while (0)
; #define PG8_WAIT_V(n) asm volatile("s_waitcnt vmcnt(" #n ")" ::: "memory")
; #define PG8_WAIT_L(n) asm volatile("s_waitcnt lgkmcnt(" #n ")" ::: "memory")
; #define PG8_BAR __builtin_amdgcn_s_barrier()
; #define PG8_SCHED __builtin_amdgcn_sched_barrier(0)
; template <class Epi, class Sched, bool ALIGN_EPI = false, bool SP2 = false>
; __device__ __forceinline__ void gemm_phase(PG8_LAS unsigned char* lds, const Gemm g, const Sched& S, const Epi& E, int wid_s_) {
;     ...
;             PG8_LDB(B0, 1, 0); PG8_LDB(B1, 1, 1); PG8_SCHED; PG8_LDA(At, 1, 0); PG8_STAGE(PG8_SA(0, 1), a2 + hstep, voffA);
;             PG8_WAIT_V(8); PG8_WAIT_L(0); PG8_BAR; PG8_MMA(0, 0, At, B0); PG8_MMA(0, 1, At, B1); PG8_BAR; PG8_SCHED;
;             PG8_LDA(At, 1, 1); PG8_STAGE(PG8_SB(1, 0), b3, voffB); PG8_STAGE(PG8_SB(1, 1), b3 + hstep, voffB); PG8_STAGE(PG8_SA(1, 0), a3, voffA);
;             PG8_WAIT_V(8); PG8_WAIT_L(0); PG8_BAR; PG8_MMA(1, 0, At, B0); PG8_MMA(1, 1, At, B1); PG8_BAR; PG8_SCHED;
	s_add_i32 s26, 16, 0x18000
	v_add_u32_e32 v96, s26, v146
	s_add_i32 s37, 16, 0x1c000
	ds_read_b128 v[156:159], v96
	ds_read_b128 v[160:163], v96 offset:1024
	ds_read_b128 v[164:167], v96 offset:2048
	ds_read_b128 v[168:171], v96 offset:3072
	v_add_u32_e32 v96, s37, v146
	ds_read_b128 v[172:175], v96
	ds_read_b128 v[176:179], v96 offset:1024
	ds_read_b128 v[180:183], v96 offset:2048
	ds_read_b128 v[194:197], v96 offset:3072
	s_mov_b32 m0, s80
	ds_read_b128 v[198:201], v148 offset:32768
	ds_read_b128 v[202:205], v148 offset:33792
	ds_read_b128 v[206:209], v148 offset:34816
	ds_read_b128 v[210:213], v148 offset:35840
	ds_read_b128 v[214:217], v148 offset:36864
	ds_read_b128 v[218:221], v148 offset:37888
	ds_read_b128 v[222:225], v148 offset:38912
	ds_read_b128 v[226:229], v148 offset:39936
	global_load_lds_dwordx4 v188, s[48:49]
	s_mov_b32 m0, s81
	s_nop 0
	global_load_lds_dwordx4 v189, s[48:49]
	s_waitcnt vmcnt(8)
	s_waitcnt lgkmcnt(0)
	s_barrier
	s_setprio 1
	s_waitcnt lgkmcnt(0)
	v_mfma_f32_16x16x32_bf16 v[122:125], v[156:159], v[198:201], v[122:125]
	v_mfma_f32_16x16x32_bf16 v[126:129], v[164:167], v[198:201], v[126:129]
	v_mfma_f32_16x16x32_bf16 v[118:121], v[156:159], v[206:209], v[118:121]
	v_mfma_f32_16x16x32_bf16 v[114:117], v[164:167], v[206:209], v[114:117]
	v_mfma_f32_16x16x32_bf16 v[110:113], v[156:159], v[214:217], v[110:113]
	v_mfma_f32_16x16x32_bf16 v[106:109], v[164:167], v[214:217], v[106:109]
	v_mfma_f32_16x16x32_bf16 v[102:105], v[156:159], v[222:225], v[102:105]
	v_mfma_f32_16x16x32_bf16 v[98:101], v[164:167], v[222:225], v[98:101]
	v_mfma_f32_16x16x32_bf16 v[122:125], v[160:163], v[202:205], v[122:125]
	v_mfma_f32_16x16x32_bf16 v[126:129], v[168:171], v[202:205], v[126:129]
	v_mfma_f32_16x16x32_bf16 v[118:121], v[160:163], v[210:213], v[118:121]
	v_mfma_f32_16x16x32_bf16 v[114:117], v[168:171], v[210:213], v[114:117]
	v_mfma_f32_16x16x32_bf16 v[110:113], v[160:163], v[218:221], v[110:113]
	v_mfma_f32_16x16x32_bf16 v[106:109], v[168:171], v[218:221], v[106:109]
	v_mfma_f32_16x16x32_bf16 v[102:105], v[160:163], v[226:229], v[102:105]
	v_mfma_f32_16x16x32_bf16 v[98:101], v[168:171], v[226:229], v[98:101]
	s_setprio 0
	s_setprio 1
	v_mfma_f32_16x16x32_bf16 v[60:63], v[172:175], v[198:201], v[60:63]
	v_mfma_f32_16x16x32_bf16 v[56:59], v[180:183], v[198:201], v[56:59]
	v_mfma_f32_16x16x32_bf16 v[52:55], v[172:175], v[206:209], v[52:55]
	v_mfma_f32_16x16x32_bf16 v[48:51], v[180:183], v[206:209], v[48:51]
	v_mfma_f32_16x16x32_bf16 v[44:47], v[172:175], v[214:217], v[44:47]
	v_mfma_f32_16x16x32_bf16 v[40:43], v[180:183], v[214:217], v[40:43]
	v_mfma_f32_16x16x32_bf16 v[36:39], v[172:175], v[222:225], v[36:39]
	v_mfma_f32_16x16x32_bf16 v[32:35], v[180:183], v[222:225], v[32:35]
	v_mfma_f32_16x16x32_bf16 v[60:63], v[176:179], v[202:205], v[60:63]
	v_mfma_f32_16x16x32_bf16 v[56:59], v[194:197], v[202:205], v[56:59]
	v_mfma_f32_16x16x32_bf16 v[52:55], v[176:179], v[210:213], v[52:55]
	v_mfma_f32_16x16x32_bf16 v[48:51], v[194:197], v[210:213], v[48:51]
	v_mfma_f32_16x16x32_bf16 v[44:47], v[176:179], v[218:221], v[44:47]
	v_mfma_f32_16x16x32_bf16 v[40:43], v[194:197], v[218:221], v[40:43]
	v_mfma_f32_16x16x32_bf16 v[36:39], v[176:179], v[226:229], v[36:39]
	v_mfma_f32_16x16x32_bf16 v[32:35], v[194:197], v[226:229], v[32:35]
	s_setprio 0
	s_barrier
	s_add_i32 s26, s26, s40
	s_mov_b32 m0, s26
	ds_read_b128 v[198:201], v148 offset:49152
	ds_read_b128 v[202:205], v148 offset:50176
	ds_read_b128 v[206:209], v148 offset:51200
	ds_read_b128 v[210:213], v148 offset:52224
	ds_read_b128 v[214:217], v148 offset:53248
	ds_read_b128 v[218:221], v148 offset:54272
	ds_read_b128 v[222:225], v148 offset:55296
	ds_read_b128 v[226:229], v148 offset:56320
	global_load_lds_dwordx4 v192, s[78:79]
	s_add_i32 m0, s26, 0x2000
	s_add_i32 s26, s37, s40
	global_load_lds_dwordx4 v193, s[78:79]
	s_mov_b32 m0, s26
	s_nop 0
	global_load_lds_dwordx4 v230, s[78:79]
	s_add_i32 m0, s26, 0x2000
	s_nop 0
	global_load_lds_dwordx4 v231, s[78:79]
	s_mov_b32 m0, s82
	s_nop 0
	global_load_lds_dwordx4 v232, s[48:49]
	s_mov_b32 m0, s83
	s_nop 0
	global_load_lds_dwordx4 v233, s[48:49]
	s_waitcnt vmcnt(8)
	s_waitcnt lgkmcnt(0)
	s_barrier
	s_setprio 1
	s_waitcnt lgkmcnt(0)
	v_mfma_f32_16x16x32_bf16 v[92:95], v[156:159], v[198:201], v[92:95]
	v_mfma_f32_16x16x32_bf16 v[88:91], v[164:167], v[198:201], v[88:91]
	v_mfma_f32_16x16x32_bf16 v[84:87], v[156:159], v[206:209], v[84:87]
	v_mfma_f32_16x16x32_bf16 v[80:83], v[164:167], v[206:209], v[80:83]
	v_mfma_f32_16x16x32_bf16 v[76:79], v[156:159], v[214:217], v[76:79]
	v_mfma_f32_16x16x32_bf16 v[72:75], v[164:167], v[214:217], v[72:75]
	v_mfma_f32_16x16x32_bf16 v[68:71], v[156:159], v[222:225], v[68:71]
	v_mfma_f32_16x16x32_bf16 v[64:67], v[164:167], v[222:225], v[64:67]
	v_mfma_f32_16x16x32_bf16 v[92:95], v[160:163], v[202:205], v[92:95]
	v_mfma_f32_16x16x32_bf16 v[88:91], v[168:171], v[202:205], v[88:91]
	v_mfma_f32_16x16x32_bf16 v[84:87], v[160:163], v[210:213], v[84:87]
	v_mfma_f32_16x16x32_bf16 v[80:83], v[168:171], v[210:213], v[80:83]
	v_mfma_f32_16x16x32_bf16 v[76:79], v[160:163], v[218:221], v[76:79]
	v_mfma_f32_16x16x32_bf16 v[72:75], v[168:171], v[218:221], v[72:75]
	v_mfma_f32_16x16x32_bf16 v[68:71], v[160:163], v[226:229], v[68:71]
	v_mfma_f32_16x16x32_bf16 v[64:67], v[168:171], v[226:229], v[64:67]
	s_setprio 0
	s_setprio 1
	v_mfma_f32_16x16x32_bf16 v[28:31], v[172:175], v[198:201], v[28:31]
	v_mfma_f32_16x16x32_bf16 v[24:27], v[180:183], v[198:201], v[24:27]
	v_mfma_f32_16x16x32_bf16 v[20:23], v[172:175], v[206:209], v[20:23]
	v_mfma_f32_16x16x32_bf16 v[16:19], v[180:183], v[206:209], v[16:19]
	v_mfma_f32_16x16x32_bf16 v[12:15], v[172:175], v[214:217], v[12:15]
	v_mfma_f32_16x16x32_bf16 v[8:11], v[180:183], v[214:217], v[8:11]
	v_mfma_f32_16x16x32_bf16 v[4:7], v[172:175], v[222:225], v[4:7]
	v_mfma_f32_16x16x32_bf16 v[0:3], v[180:183], v[222:225], v[0:3]
	v_mfma_f32_16x16x32_bf16 v[28:31], v[176:179], v[202:205], v[28:31]
	v_mfma_f32_16x16x32_bf16 v[24:27], v[194:197], v[202:205], v[24:27]
	v_mfma_f32_16x16x32_bf16 v[20:23], v[176:179], v[210:213], v[20:23]
	v_mfma_f32_16x16x32_bf16 v[16:19], v[194:197], v[210:213], v[16:19]
	v_mfma_f32_16x16x32_bf16 v[12:15], v[176:179], v[218:221], v[12:15]
	v_mfma_f32_16x16x32_bf16 v[8:11], v[194:197], v[218:221], v[8:11]
	v_mfma_f32_16x16x32_bf16 v[4:7], v[176:179], v[226:229], v[4:7]
	v_mfma_f32_16x16x32_bf16 v[0:3], v[194:197], v[226:229], v[0:3]
	s_setprio 0
	s_barrier
	s_add_u32 s91, s91, 0x100
	s_addc_u32 vcc_lo, vcc_lo, 0
	s_add_u32 s24, s24, 0x100
	s_addc_u32 s25, s25, 0
	s_cmp_ge_i32 vcc_hi, s84
	s_mov_b32 s48, vcc_hi
	s_cbranch_scc0 .LBB0_466
	v_add_u32_e32 v192, 64, v191

; template <class Epi, class Sched, bool ALIGN_EPI = false, bool SP2 = false>
; __device__ __forceinline__ void gemm_phase(PG8_LAS unsigned char* lds, const Gemm g, const Sched& S, const Epi& E, int wid_s_) {
;     ...
;     for (int i = 0; i < 2; ++i) { int R, C; stage_rc(tid * 16 + i * 8192, R, C); const int Rb = Epi::PERM ? ((R & ~31) + perm32(R & 31)) : R;
;         voffA[i] = (unsigned)(R * K + C) * 2u; voffB[i] = (unsigned)(Rb * K + C) * 2u; }
;     const size_t kstep = (size_t)(BK * 2);
;     const size_t hstep = (size_t)HALF * K * 2;
;     const size_t tstep = 2 * hstep;
;     ...
;     f32x4 acc[2][2][4][2];
; #pragma unroll
;     for (int a = 0; a < 2; ++a)
; #pragma unroll
;         for (int b = 0; b < 2; ++b)
; #pragma unroll
;             for (int m = 0; m < 4; ++m)
; #pragma unroll
;                 for (int n = 0; n < 2; ++n) acc[a][b][m][n] = (f32x4){0.f, 0.f, 0.f, 0.f};
.LBB0_538:
	v_mov_b32_e32 v129, 0
	s_andn2_b64 vcc, exec, s[20:21]
	v_mov_b32_e32 v128, v129
	v_mov_b32_e32 v127, v129
	v_mov_b32_e32 v126, v129
	v_mov_b32_e32 v125, v129
	v_mov_b32_e32 v124, v129
	v_mov_b32_e32 v123, v129
	v_mov_b32_e32 v122, v129
	v_mov_b32_e32 v113, v129
	v_mov_b32_e32 v112, v129
	v_mov_b32_e32 v111, v129
	v_mov_b32_e32 v110, v129
	v_mov_b32_e32 v109, v129
	v_mov_b32_e32 v108, v129
	v_mov_b32_e32 v107, v129
	v_mov_b32_e32 v106, v129
	v_mov_b32_e32 v95, v129
	v_mov_b32_e32 v94, v129
	v_mov_b32_e32 v93, v129
	v_mov_b32_e32 v92, v129
	v_mov_b32_e32 v91, v129
	v_mov_b32_e32 v90, v129
	v_mov_b32_e32 v89, v129
	v_mov_b32_e32 v88, v129
	v_mov_b32_e32 v79, v129
	v_mov_b32_e32 v78, v129
	v_mov_b32_e32 v77, v129
	v_mov_b32_e32 v76, v129
	v_mov_b32_e32 v75, v129
	v_mov_b32_e32 v74, v129
	v_mov_b32_e32 v73, v129
	v_mov_b32_e32 v72, v129
	v_mov_b32_e32 v121, v129
	v_mov_b32_e32 v120, v129
	v_mov_b32_e32 v119, v129
	v_mov_b32_e32 v118, v129
	v_mov_b32_e32 v117, v129
	v_mov_b32_e32 v116, v129
	v_mov_b32_e32 v115, v129
	v_mov_b32_e32 v114, v129
	v_mov_b32_e32 v105, v129
	v_mov_b32_e32 v104, v129
	v_mov_b32_e32 v103, v129
	v_mov_b32_e32 v102, v129
	v_mov_b32_e32 v101, v129
	v_mov_b32_e32 v100, v129
	v_mov_b32_e32 v99, v129
	v_mov_b32_e32 v98, v129
	v_mov_b32_e32 v87, v129
	v_mov_b32_e32 v86, v129
	v_mov_b32_e32 v85, v129
	v_mov_b32_e32 v84, v129
	v_mov_b32_e32 v83, v129
	v_mov_b32_e32 v82, v129
	v_mov_b32_e32 v81, v129
	v_mov_b32_e32 v80, v129
	v_mov_b32_e32 v71, v129
	v_mov_b32_e32 v70, v129
	v_mov_b32_e32 v69, v129
	v_mov_b32_e32 v68, v129
	v_mov_b32_e32 v67, v129
	v_mov_b32_e32 v66, v129
	v_mov_b32_e32 v65, v129
	v_mov_b32_e32 v64, v129
	v_mov_b32_e32 v63, v129
	v_mov_b32_e32 v62, v129
	v_mov_b32_e32 v61, v129
	v_mov_b32_e32 v60, v129
	v_mov_b32_e32 v59, v129
	v_mov_b32_e32 v58, v129
	v_mov_b32_e32 v57, v129
	v_mov_b32_e32 v56, v129
	v_mov_b32_e32 v47, v129
	v_mov_b32_e32 v46, v129
	v_mov_b32_e32 v45, v129
	v_mov_b32_e32 v44, v129
	v_mov_b32_e32 v43, v129
	v_mov_b32_e32 v42, v129
	v_mov_b32_e32 v41, v129
	v_mov_b32_e32 v40, v129
	v_mov_b32_e32 v31, v129
	v_mov_b32_e32 v30, v129
	v_mov_b32_e32 v29, v129
	v_mov_b32_e32 v28, v129
	v_mov_b32_e32 v27, v129
	v_mov_b32_e32 v26, v129
	v_mov_b32_e32 v25, v129
	v_mov_b32_e32 v24, v129
	v_mov_b32_e32 v15, v129
	v_mov_b32_e32 v14, v129
	v_mov_b32_e32 v13, v129
	v_mov_b32_e32 v12, v129
	v_mov_b32_e32 v11, v129
	v_mov_b32_e32 v10, v129
	v_mov_b32_e32 v9, v129
	v_mov_b32_e32 v8, v129
	v_mov_b32_e32 v55, v129
	v_mov_b32_e32 v54, v129
	v_mov_b32_e32 v53, v129
	v_mov_b32_e32 v52, v129
	v_mov_b32_e32 v51, v129
	v_mov_b32_e32 v50, v129
	v_mov_b32_e32 v49, v129
	v_mov_b32_e32 v48, v129
	v_mov_b32_e32 v39, v129
	v_mov_b32_e32 v38, v129
	v_mov_b32_e32 v37, v129
	v_mov_b32_e32 v36, v129
	v_mov_b32_e32 v35, v129
	v_mov_b32_e32 v34, v129
	v_mov_b32_e32 v33, v129
	v_mov_b32_e32 v32, v129
	v_mov_b32_e32 v23, v129
	v_mov_b32_e32 v22, v129
	v_mov_b32_e32 v21, v129
	v_mov_b32_e32 v20, v129
	v_mov_b32_e32 v19, v129
	v_mov_b32_e32 v18, v129
	v_mov_b32_e32 v17, v129
	v_mov_b32_e32 v16, v129
	v_mov_b32_e32 v7, v129
	v_mov_b32_e32 v6, v129
	v_mov_b32_e32 v5, v129
	v_mov_b32_e32 v4, v129
	v_mov_b32_e32 v3, v129
	v_mov_b32_e32 v2, v129
	v_mov_b32_e32 v1, v129
	v_mov_b32_e32 v0, v129
	s_cbranch_vccnz .LBB0_542
	s_add_u32 s91, s2, 0x100
	s_addc_u32 vcc_lo, s3, 0
	s_add_u32 s2, s48, 0x80
	v_mov_b32_e32 v0, 0
	s_addc_u32 s3, s49, 0
	s_mov_b32 s48, 0
	v_mov_b32_e32 v1, v0
	v_mov_b32_e32 v2, v0
	v_mov_b32_e32 v3, v0
	v_mov_b32_e32 v4, v0
	v_mov_b32_e32 v5, v0
	v_mov_b32_e32 v6, v0
	v_mov_b32_e32 v7, v0
	v_mov_b32_e32 v16, v0
	v_mov_b32_e32 v17, v0
	v_mov_b32_e32 v18, v0
	v_mov_b32_e32 v19, v0
	v_mov_b32_e32 v20, v0
	v_mov_b32_e32 v21, v0
	v_mov_b32_e32 v22, v0
	v_mov_b32_e32 v23, v0
	v_mov_b32_e32 v32, v0
	v_mov_b32_e32 v33, v0
	v_mov_b32_e32 v34, v0
	v_mov_b32_e32 v35, v0
	v_mov_b32_e32 v36, v0
	v_mov_b32_e32 v37, v0
	v_mov_b32_e32 v38, v0
	v_mov_b32_e32 v39, v0
	v_mov_b32_e32 v48, v0
	v_mov_b32_e32 v49, v0
	v_mov_b32_e32 v50, v0
	v_mov_b32_e32 v51, v0
	v_mov_b32_e32 v52, v0
	v_mov_b32_e32 v53, v0
	v_mov_b32_e32 v54, v0
	v_mov_b32_e32 v55, v0
	v_mov_b32_e32 v8, v0
	v_mov_b32_e32 v9, v0
	v_mov_b32_e32 v10, v0
	v_mov_b32_e32 v11, v0
	v_mov_b32_e32 v12, v0
	v_mov_b32_e32 v13, v0
	v_mov_b32_e32 v14, v0
	v_mov_b32_e32 v15, v0
	v_mov_b32_e32 v24, v0
	v_mov_b32_e32 v25, v0
	v_mov_b32_e32 v26, v0
	v_mov_b32_e32 v27, v0
	v_mov_b32_e32 v28, v0
	v_mov_b32_e32 v29, v0
	v_mov_b32_e32 v30, v0
	v_mov_b32_e32 v31, v0
	v_mov_b32_e32 v40, v0
	v_mov_b32_e32 v41, v0
	v_mov_b32_e32 v42, v0
	v_mov_b32_e32 v43, v0
	v_mov_b32_e32 v44, v0
	v_mov_b32_e32 v45, v0
	v_mov_b32_e32 v46, v0
	v_mov_b32_e32 v47, v0
	v_mov_b32_e32 v56, v0
	v_mov_b32_e32 v57, v0
	v_mov_b32_e32 v58, v0
	v_mov_b32_e32 v59, v0
	v_mov_b32_e32 v60, v0
	v_mov_b32_e32 v61, v0
	v_mov_b32_e32 v62, v0
	v_mov_b32_e32 v63, v0
	v_mov_b32_e32 v64, v0
	v_mov_b32_e32 v65, v0
	v_mov_b32_e32 v66, v0
	v_mov_b32_e32 v67, v0
	v_mov_b32_e32 v68, v0
	v_mov_b32_e32 v69, v0
	v_mov_b32_e32 v70, v0
	v_mov_b32_e32 v71, v0
	v_mov_b32_e32 v80, v0
	v_mov_b32_e32 v81, v0
	v_mov_b32_e32 v82, v0
	v_mov_b32_e32 v83, v0
	v_mov_b32_e32 v84, v0
	v_mov_b32_e32 v85, v0
	v_mov_b32_e32 v86, v0
	v_mov_b32_e32 v87, v0
	v_mov_b32_e32 v98, v0
	v_mov_b32_e32 v99, v0
	v_mov_b32_e32 v100, v0
	v_mov_b32_e32 v101, v0
	v_mov_b32_e32 v102, v0
	v_mov_b32_e32 v103, v0
	v_mov_b32_e32 v104, v0
	v_mov_b32_e32 v105, v0
	v_mov_b32_e32 v114, v0
	v_mov_b32_e32 v115, v0
	v_mov_b32_e32 v116, v0
	v_mov_b32_e32 v117, v0
	v_mov_b32_e32 v118, v0
	v_mov_b32_e32 v119, v0
	v_mov_b32_e32 v120, v0
	v_mov_b32_e32 v121, v0
	v_mov_b32_e32 v72, v0
	v_mov_b32_e32 v73, v0
	v_mov_b32_e32 v74, v0
	v_mov_b32_e32 v75, v0
	v_mov_b32_e32 v76, v0
	v_mov_b32_e32 v77, v0
	v_mov_b32_e32 v78, v0
	v_mov_b32_e32 v79, v0
	v_mov_b32_e32 v88, v0
	v_mov_b32_e32 v89, v0
	v_mov_b32_e32 v90, v0
	v_mov_b32_e32 v91, v0
	v_mov_b32_e32 v92, v0
	v_mov_b32_e32 v93, v0
	v_mov_b32_e32 v94, v0
	v_mov_b32_e32 v95, v0
	v_mov_b32_e32 v106, v0
	v_mov_b32_e32 v107, v0
	v_mov_b32_e32 v108, v0
	v_mov_b32_e32 v109, v0
	v_mov_b32_e32 v110, v0
	v_mov_b32_e32 v111, v0
	v_mov_b32_e32 v112, v0
	v_mov_b32_e32 v113, v0
	v_mov_b32_e32 v122, v0
	v_mov_b32_e32 v123, v0
	v_mov_b32_e32 v124, v0
	v_mov_b32_e32 v125, v0
	v_mov_b32_e32 v126, v0
	v_mov_b32_e32 v127, v0
	v_mov_b32_e32 v128, v0
	v_mov_b32_e32 v129, v0
	v_add_u32_e32 v188, s14, v96
	v_add_u32_e32 v189, s14, v130
	v_add_u32_e32 v192, s14, v134
	v_add_u32_e32 v193, s14, v132
	v_add_u32_e32 v222, s42, v96
	v_add_u32_e32 v223, s42, v130
	v_add_u32_e32 v226, s42, v134
	v_add_u32_e32 v227, s42, v132
	v_add_u32_e32 v224, s42, v188
	v_add_u32_e32 v225, s42, v189
; #define PG8_STAGE(bufoff, gbase, voff) do { _Pragma("unroll") for (int _i = 0; _i < 2; ++_i) \
;         __builtin_amdgcn_global_load_lds((const unsigned*)((const char*)(gbase) + (voff)[_i]), (PG8_LAS unsigned*)(lds + (bufoff) + ldsw + _i * 8192), 16, 0, 0); } while (0)
; #define PG8_LDA(dst, b, h) do { _Pragma("unroll") for (int m = 0; m < 4; ++m) _Pragma("unroll") for (int k = 0; k < 2; ++k) dst[m][k] = *(const PG8_LAS bf16x8*)(lds + PG8_SA(b, h) + aoff + m * 2048 + k * 1024); } while (0)
; #define PG8_LDB(dst, b, h) do { _Pragma("unroll") for (int n = 0; n < 2; ++n) _Pragma("unroll") for (int k = 0; k < 2; ++k) dst[n][k] = *(const PG8_LAS bf16x8*)(lds + PG8_SB(b, h) + boff + n * 2048 + k * 1024); } while (0)
; #define PG8_MMA(ai, bj, At, Bt) do { __builtin_amdgcn_s_setprio(1); _Pragma("unroll") for (int m = 0; m < 4; ++m) _Pragma("unroll") for (int n = 0; n < 2; ++n) _Pragma("unroll") for (int k = 0; k < 2; ++k) \
;         acc[ai][bj][m][n] = __builtin_amdgcn_mfma_f32_16x16x32_bf16(Bt[n][k], At[m][k], acc[ai][bj][m][n], 0, 0, 0); __builtin_amdgcn_s_setprio(0); } while (0)
; #define PG8_WAIT_V(n) asm volatile("s_waitcnt vmcnt(" #n ")" ::: "memory")
; #define PG8_BAR __builtin_amdgcn_s_barrier()
; template <class Epi, class Sched, bool ALIGN_EPI = false, bool SP2 = false>
; __device__ __forceinline__ void gemm_phase(PG8_LAS unsigned char* lds, const Gemm g, const Sched& S, const Epi& E, int wid_s_) {
;     ...
;         for (int t = 0; t < nt; t += 2) {
;             const bool last = (t == nt - 2);
;             const char* a1 = cA + (size_t)(t + 1) * kstep;
;             const char* a2 = last ? nA : cA + (size_t)(t + 2) * kstep; const char* b2 = last ? nB : cB + (size_t)(t + 2) * kstep;
;             const char* a3 = a2 + kstep; const char* b3 = b2 + kstep;
;             if (last && has_next) S.a_ready(nxt);
;             if constexpr (SP2) {
;             PG8_LDB(B0, 0, 0); PG8_LDB(B1, 0, 1); PG8_SCHED; PG8_LDA(At, 0, 0); PG8_STAGE(PG8_SA(1, 1), a1 + hstep, voffA);
;             PG8_WAIT_V(8); PG8_WAIT_L(0); PG8_BAR; PG8_MMA(0, 0, At, B0); PG8_MMA(0, 1, At, B1); PG8_BAR; PG8_SCHED;
;             PG8_LDA(At, 0, 1); PG8_STAGE(PG8_SB(0, 0), b2, voffB); PG8_STAGE(PG8_SB(0, 1), b2 + hstep, voffB); PG8_STAGE(PG8_SA(0, 0), a2, voffA);
;             PG8_WAIT_V(8); PG8_WAIT_L(0); PG8_BAR; PG8_MMA(1, 0, At, B0); PG8_MMA(1, 1, At, B1); PG8_BAR; PG8_SCHED;
.LBB0_540:
	s_add_i32 vcc_hi, s48, 2
	s_add_u32 s78, s2, 0x80
	s_addc_u32 s49, s3, 0
	s_add_i32 s12, 16, 0x10000
	s_cmp_eq_u32 s87, s48
	s_cselect_b32 s49, s25, s49
	s_cselect_b32 s48, s24, s78
	v_add_u32_e32 v151, s12, v144
	s_cselect_b32 s79, s81, vcc_lo
	s_cselect_b32 s78, s80, s91
	s_add_i32 s13, 16, 0x14000
	ds_read_b128 v[140:143], v151
	ds_read_b128 v[152:155], v151 offset:1024
	ds_read_b128 v[156:159], v151 offset:2048
	ds_read_b128 v[160:163], v151 offset:3072
	v_add_u32_e32 v151, s13, v144
	ds_read_b128 v[164:167], v151
	ds_read_b128 v[168:171], v151 offset:1024
	ds_read_b128 v[172:175], v151 offset:2048
	ds_read_b128 v[176:179], v151 offset:3072
	s_add_i32 m0, s41, 0xc000
	ds_read_b128 v[180:183], v150
	ds_read_b128 v[194:197], v150 offset:1024
	ds_read_b128 v[198:201], v150 offset:2048
	ds_read_b128 v[202:205], v150 offset:3072
	ds_read_b128 v[206:209], v150 offset:4096
	ds_read_b128 v[210:213], v150 offset:5120
	ds_read_b128 v[214:217], v150 offset:6144
	ds_read_b128 v[218:221], v150 offset:7168
	global_load_lds_dwordx4 v138, s[2:3]
	s_add_i32 m0, s41, 0xe000
	s_nop 0
	global_load_lds_dwordx4 v136, s[2:3]
	s_waitcnt vmcnt(8)
	s_waitcnt lgkmcnt(0)
	s_barrier
	s_setprio 1
	s_waitcnt lgkmcnt(0)
	v_mfma_f32_16x16x32_bf16 v[126:129], v[140:143], v[180:183], v[126:129]
	v_mfma_f32_16x16x32_bf16 v[122:125], v[156:159], v[180:183], v[122:125]
	v_mfma_f32_16x16x32_bf16 v[110:113], v[140:143], v[198:201], v[110:113]
	v_mfma_f32_16x16x32_bf16 v[106:109], v[156:159], v[198:201], v[106:109]
	v_mfma_f32_16x16x32_bf16 v[92:95], v[140:143], v[206:209], v[92:95]
	v_mfma_f32_16x16x32_bf16 v[88:91], v[156:159], v[206:209], v[88:91]
	v_mfma_f32_16x16x32_bf16 v[76:79], v[140:143], v[214:217], v[76:79]
	v_mfma_f32_16x16x32_bf16 v[72:75], v[156:159], v[214:217], v[72:75]
	v_mfma_f32_16x16x32_bf16 v[126:129], v[152:155], v[194:197], v[126:129]
	v_mfma_f32_16x16x32_bf16 v[122:125], v[160:163], v[194:197], v[122:125]
	v_mfma_f32_16x16x32_bf16 v[110:113], v[152:155], v[202:205], v[110:113]
	v_mfma_f32_16x16x32_bf16 v[106:109], v[160:163], v[202:205], v[106:109]
	v_mfma_f32_16x16x32_bf16 v[92:95], v[152:155], v[210:213], v[92:95]
	v_mfma_f32_16x16x32_bf16 v[88:91], v[160:163], v[210:213], v[88:91]
	v_mfma_f32_16x16x32_bf16 v[76:79], v[152:155], v[218:221], v[76:79]
	v_mfma_f32_16x16x32_bf16 v[72:75], v[160:163], v[218:221], v[72:75]
	s_setprio 0
	s_setprio 1
	v_mfma_f32_16x16x32_bf16 v[118:121], v[164:167], v[180:183], v[118:121]
	v_mfma_f32_16x16x32_bf16 v[114:117], v[172:175], v[180:183], v[114:117]
	v_mfma_f32_16x16x32_bf16 v[102:105], v[164:167], v[198:201], v[102:105]
	v_mfma_f32_16x16x32_bf16 v[98:101], v[172:175], v[198:201], v[98:101]
	v_mfma_f32_16x16x32_bf16 v[84:87], v[164:167], v[206:209], v[84:87]
	v_mfma_f32_16x16x32_bf16 v[80:83], v[172:175], v[206:209], v[80:83]
	v_mfma_f32_16x16x32_bf16 v[68:71], v[164:167], v[214:217], v[68:71]
	v_mfma_f32_16x16x32_bf16 v[64:67], v[172:175], v[214:217], v[64:67]
	v_mfma_f32_16x16x32_bf16 v[118:121], v[168:171], v[194:197], v[118:121]
	v_mfma_f32_16x16x32_bf16 v[114:117], v[176:179], v[194:197], v[114:117]
	v_mfma_f32_16x16x32_bf16 v[102:105], v[168:171], v[202:205], v[102:105]
	v_mfma_f32_16x16x32_bf16 v[98:101], v[176:179], v[202:205], v[98:101]
	v_mfma_f32_16x16x32_bf16 v[84:87], v[168:171], v[210:213], v[84:87]
	v_mfma_f32_16x16x32_bf16 v[80:83], v[176:179], v[210:213], v[80:83]
	v_mfma_f32_16x16x32_bf16 v[68:71], v[168:171], v[218:221], v[68:71]
	v_mfma_f32_16x16x32_bf16 v[64:67], v[176:179], v[218:221], v[64:67]
	s_setprio 0
	s_barrier
	s_add_i32 s12, s12, s40
	s_mov_b32 m0, s12
	ds_read_b128 v[180:183], v150 offset:16384
	ds_read_b128 v[194:197], v150 offset:17408
	ds_read_b128 v[198:201], v150 offset:18432
	ds_read_b128 v[202:205], v150 offset:19456
	ds_read_b128 v[206:209], v150 offset:20480
	ds_read_b128 v[210:213], v150 offset:21504
	ds_read_b128 v[214:217], v150 offset:22528
	ds_read_b128 v[218:221], v150 offset:23552
	global_load_lds_dwordx4 v96, s[78:79]
	s_add_i32 m0, s12, 0x2000
	s_add_i32 s12, s13, s40
	global_load_lds_dwordx4 v130, s[78:79]
	s_mov_b32 m0, s12
	s_nop 0
	global_load_lds_dwordx4 v188, s[78:79]
	s_add_i32 m0, s12, 0x2000
	s_nop 0
	global_load_lds_dwordx4 v189, s[78:79]
	s_mov_b32 m0, s41
	s_nop 0
	global_load_lds_dwordx4 v134, s[48:49]
	s_mov_b32 m0, s50
	s_nop 0
	global_load_lds_dwordx4 v132, s[48:49]
	s_waitcnt vmcnt(8)
	s_waitcnt lgkmcnt(0)
	s_barrier
	s_setprio 1
	s_waitcnt lgkmcnt(0)
	v_mfma_f32_16x16x32_bf16 v[60:63], v[140:143], v[180:183], v[60:63]
	v_mfma_f32_16x16x32_bf16 v[56:59], v[156:159], v[180:183], v[56:59]
	v_mfma_f32_16x16x32_bf16 v[44:47], v[140:143], v[198:201], v[44:47]
	v_mfma_f32_16x16x32_bf16 v[40:43], v[156:159], v[198:201], v[40:43]
	v_mfma_f32_16x16x32_bf16 v[28:31], v[140:143], v[206:209], v[28:31]
	v_mfma_f32_16x16x32_bf16 v[24:27], v[156:159], v[206:209], v[24:27]
	v_mfma_f32_16x16x32_bf16 v[12:15], v[140:143], v[214:217], v[12:15]
	v_mfma_f32_16x16x32_bf16 v[8:11], v[156:159], v[214:217], v[8:11]
	v_mfma_f32_16x16x32_bf16 v[60:63], v[152:155], v[194:197], v[60:63]
	v_mfma_f32_16x16x32_bf16 v[56:59], v[160:163], v[194:197], v[56:59]
	v_mfma_f32_16x16x32_bf16 v[44:47], v[152:155], v[202:205], v[44:47]
	v_mfma_f32_16x16x32_bf16 v[40:43], v[160:163], v[202:205], v[40:43]
	v_mfma_f32_16x16x32_bf16 v[28:31], v[152:155], v[210:213], v[28:31]
	v_mfma_f32_16x16x32_bf16 v[24:27], v[160:163], v[210:213], v[24:27]
	v_mfma_f32_16x16x32_bf16 v[12:15], v[152:155], v[218:221], v[12:15]
	v_mfma_f32_16x16x32_bf16 v[8:11], v[160:163], v[218:221], v[8:11]
	s_setprio 0
	s_setprio 1
	v_mfma_f32_16x16x32_bf16 v[52:55], v[164:167], v[180:183], v[52:55]
	v_mfma_f32_16x16x32_bf16 v[48:51], v[172:175], v[180:183], v[48:51]
	v_mfma_f32_16x16x32_bf16 v[36:39], v[164:167], v[198:201], v[36:39]
	v_mfma_f32_16x16x32_bf16 v[32:35], v[172:175], v[198:201], v[32:35]
	v_mfma_f32_16x16x32_bf16 v[20:23], v[164:167], v[206:209], v[20:23]
	v_mfma_f32_16x16x32_bf16 v[16:19], v[172:175], v[206:209], v[16:19]
	v_mfma_f32_16x16x32_bf16 v[4:7], v[164:167], v[214:217], v[4:7]
	v_mfma_f32_16x16x32_bf16 v[0:3], v[172:175], v[214:217], v[0:3]
	v_mfma_f32_16x16x32_bf16 v[52:55], v[168:171], v[194:197], v[52:55]
	v_mfma_f32_16x16x32_bf16 v[48:51], v[176:179], v[194:197], v[48:51]
	v_mfma_f32_16x16x32_bf16 v[36:39], v[168:171], v[202:205], v[36:39]
	v_mfma_f32_16x16x32_bf16 v[32:35], v[176:179], v[202:205], v[32:35]
	v_mfma_f32_16x16x32_bf16 v[20:23], v[168:171], v[210:213], v[20:23]
	v_mfma_f32_16x16x32_bf16 v[16:19], v[176:179], v[210:213], v[16:19]
	v_mfma_f32_16x16x32_bf16 v[4:7], v[168:171], v[218:221], v[4:7]
	v_mfma_f32_16x16x32_bf16 v[0:3], v[176:179], v[218:221], v[0:3]
	s_setprio 0
	s_barrier
; #define PG8_STAGE(bufoff, gbase, voff) do { _Pragma("unroll") for (int _i = 0; _i < 2; ++_i) \
;         __builtin_amdgcn_global_load_lds((const unsigned*)((const char*)(gbase) + (voff)[_i]), (PG8_LAS unsigned*)(lds + (bufoff) + ldsw + _i * 8192), 16, 0, 0); } while (0)
; #define PG8_LDA(dst, b, h) do { _Pragma("unroll") for (int m = 0; m < 4; ++m) _Pragma("unroll") for (int k = 0; k < 2; ++k) dst[m][k] = *(const PG8_LAS bf16x8*)(lds + PG8_SA(b, h) + aoff + m * 2048 + k * 1024); } while (0)
; #define PG8_LDB(dst, b, h) do { _Pragma("unroll") for (int n = 0; n < 2; ++n) _Pragma("unroll") for (int k = 0; k < 2; ++k) dst[n][k] = *(const PG8_LAS bf16x8*)(lds + PG8_SB(b, h) + boff + n * 2048 + k * 1024); } while (0)
; #define PG8_MMA(ai, bj, At, Bt) do { __builtin_amdgcn_s_setprio(1); _Pragma("unroll") for (int m = 0; m < 4; ++m) _Pragma("unroll") for (int n = 0; n < 2; ++n) _Pragma("unroll") for (int k = 0; k < 2; ++k) \
;         acc[ai][bj][m][n] = __builtin_amdgcn_mfma_f32_16x16x32_bf16(Bt[n][k], At[m][k], acc[ai][bj][m][n], 0, 0, 0); __builtin_amdgcn_s_setprio(0); } while (0)
; #define PG8_WAIT_V(n) asm volatile("s_waitcnt vmcnt(" #n ")" ::: "memory")
; #define PG8_WAIT_L(n) asm volatile("s_waitcnt lgkmcnt(" #n ")" ::: "memory")
; #define PG8_BAR __builtin_amdgcn_s_barrier()
; #define PG8_SCHED __builtin_amdgcn_sched_barrier(0)
; template <class Epi, class Sched, bool ALIGN_EPI = false, bool SP2 = false>
; __device__ __forceinline__ void gemm_phase(PG8_LAS unsigned char* lds, const Gemm g, const Sched& S, const Epi& E, int wid_s_) {
;     ...
;             PG8_LDB(B0, 1, 0); PG8_LDB(B1, 1, 1); PG8_SCHED; PG8_LDA(At, 1, 0); PG8_STAGE(PG8_SA(0, 1), a2 + hstep, voffA);
;             PG8_WAIT_V(8); PG8_WAIT_L(0); PG8_BAR; PG8_MMA(0, 0, At, B0); PG8_MMA(0, 1, At, B1); PG8_BAR; PG8_SCHED;
;             PG8_LDA(At, 1, 1); PG8_STAGE(PG8_SB(1, 0), b3, voffB); PG8_STAGE(PG8_SB(1, 1), b3 + hstep, voffB); PG8_STAGE(PG8_SA(1, 0), a3, voffA);
;             PG8_WAIT_V(8); PG8_WAIT_L(0); PG8_BAR; PG8_MMA(1, 0, At, B0); PG8_MMA(1, 1, At, B1); PG8_BAR; PG8_SCHED;
	s_add_i32 s12, 16, 0x18000
	v_add_u32_e32 v151, s12, v144
	s_add_i32 s13, 16, 0x1c000
	ds_read_b128 v[140:143], v151
	ds_read_b128 v[152:155], v151 offset:1024
	ds_read_b128 v[156:159], v151 offset:2048
	ds_read_b128 v[160:163], v151 offset:3072
	v_add_u32_e32 v151, s13, v144
	ds_read_b128 v[164:167], v151
	ds_read_b128 v[168:171], v151 offset:1024
	ds_read_b128 v[172:175], v151 offset:2048
	ds_read_b128 v[176:179], v151 offset:3072
	s_mov_b32 m0, s51
	ds_read_b128 v[180:183], v150 offset:32768
	ds_read_b128 v[194:197], v150 offset:33792
	ds_read_b128 v[198:201], v150 offset:34816
	ds_read_b128 v[202:205], v150 offset:35840
	ds_read_b128 v[206:209], v150 offset:36864
	ds_read_b128 v[210:213], v150 offset:37888
	ds_read_b128 v[214:217], v150 offset:38912
	ds_read_b128 v[218:221], v150 offset:39936
	global_load_lds_dwordx4 v192, s[48:49]
	s_mov_b32 m0, s82
	s_nop 0
	global_load_lds_dwordx4 v193, s[48:49]
	s_waitcnt vmcnt(8)
	s_waitcnt lgkmcnt(0)
	s_barrier
	s_setprio 1
	s_waitcnt lgkmcnt(0)
	v_mfma_f32_16x16x32_bf16 v[126:129], v[140:143], v[180:183], v[126:129]
	v_mfma_f32_16x16x32_bf16 v[122:125], v[156:159], v[180:183], v[122:125]
	v_mfma_f32_16x16x32_bf16 v[110:113], v[140:143], v[198:201], v[110:113]
	v_mfma_f32_16x16x32_bf16 v[106:109], v[156:159], v[198:201], v[106:109]
	v_mfma_f32_16x16x32_bf16 v[92:95], v[140:143], v[206:209], v[92:95]
	v_mfma_f32_16x16x32_bf16 v[88:91], v[156:159], v[206:209], v[88:91]
	v_mfma_f32_16x16x32_bf16 v[76:79], v[140:143], v[214:217], v[76:79]
	v_mfma_f32_16x16x32_bf16 v[72:75], v[156:159], v[214:217], v[72:75]
	v_mfma_f32_16x16x32_bf16 v[126:129], v[152:155], v[194:197], v[126:129]
	v_mfma_f32_16x16x32_bf16 v[122:125], v[160:163], v[194:197], v[122:125]
	v_mfma_f32_16x16x32_bf16 v[110:113], v[152:155], v[202:205], v[110:113]
	v_mfma_f32_16x16x32_bf16 v[106:109], v[160:163], v[202:205], v[106:109]
	v_mfma_f32_16x16x32_bf16 v[92:95], v[152:155], v[210:213], v[92:95]
	v_mfma_f32_16x16x32_bf16 v[88:91], v[160:163], v[210:213], v[88:91]
	v_mfma_f32_16x16x32_bf16 v[76:79], v[152:155], v[218:221], v[76:79]
	v_mfma_f32_16x16x32_bf16 v[72:75], v[160:163], v[218:221], v[72:75]
	s_setprio 0
	s_setprio 1
	v_mfma_f32_16x16x32_bf16 v[118:121], v[164:167], v[180:183], v[118:121]
	v_mfma_f32_16x16x32_bf16 v[114:117], v[172:175], v[180:183], v[114:117]
	v_mfma_f32_16x16x32_bf16 v[102:105], v[164:167], v[198:201], v[102:105]
	v_mfma_f32_16x16x32_bf16 v[98:101], v[172:175], v[198:201], v[98:101]
	v_mfma_f32_16x16x32_bf16 v[84:87], v[164:167], v[206:209], v[84:87]
	v_mfma_f32_16x16x32_bf16 v[80:83], v[172:175], v[206:209], v[80:83]
	v_mfma_f32_16x16x32_bf16 v[68:71], v[164:167], v[214:217], v[68:71]
	v_mfma_f32_16x16x32_bf16 v[64:67], v[172:175], v[214:217], v[64:67]
	v_mfma_f32_16x16x32_bf16 v[118:121], v[168:171], v[194:197], v[118:121]
	v_mfma_f32_16x16x32_bf16 v[114:117], v[176:179], v[194:197], v[114:117]
	v_mfma_f32_16x16x32_bf16 v[102:105], v[168:171], v[202:205], v[102:105]
	v_mfma_f32_16x16x32_bf16 v[98:101], v[176:179], v[202:205], v[98:101]
	v_mfma_f32_16x16x32_bf16 v[84:87], v[168:171], v[210:213], v[84:87]
	v_mfma_f32_16x16x32_bf16 v[80:83], v[176:179], v[210:213], v[80:83]
	v_mfma_f32_16x16x32_bf16 v[68:71], v[168:171], v[218:221], v[68:71]
	v_mfma_f32_16x16x32_bf16 v[64:67], v[176:179], v[218:221], v[64:67]
	s_setprio 0
	s_barrier
	s_add_i32 s12, s12, s40
	s_mov_b32 m0, s12
	ds_read_b128 v[180:183], v150 offset:49152
	ds_read_b128 v[194:197], v150 offset:50176
	ds_read_b128 v[198:201], v150 offset:51200
	ds_read_b128 v[202:205], v150 offset:52224
	ds_read_b128 v[206:209], v150 offset:53248
	ds_read_b128 v[210:213], v150 offset:54272
	ds_read_b128 v[214:217], v150 offset:55296
	ds_read_b128 v[218:221], v150 offset:56320
	global_load_lds_dwordx4 v222, s[78:79]
	s_add_i32 m0, s12, 0x2000
	s_add_i32 s12, s13, s40
	global_load_lds_dwordx4 v223, s[78:79]
	s_mov_b32 m0, s12
	s_nop 0
	global_load_lds_dwordx4 v224, s[78:79]
	s_add_i32 m0, s12, 0x2000
	s_nop 0
	global_load_lds_dwordx4 v225, s[78:79]
	s_mov_b32 m0, s83
	s_nop 0
	global_load_lds_dwordx4 v226, s[48:49]
	s_mov_b32 m0, s84
	s_nop 0
	global_load_lds_dwordx4 v227, s[48:49]
	s_waitcnt vmcnt(8)
	s_waitcnt lgkmcnt(0)
	s_barrier
	s_setprio 1
	s_waitcnt lgkmcnt(0)
	v_mfma_f32_16x16x32_bf16 v[60:63], v[140:143], v[180:183], v[60:63]
	v_mfma_f32_16x16x32_bf16 v[56:59], v[156:159], v[180:183], v[56:59]
	v_mfma_f32_16x16x32_bf16 v[44:47], v[140:143], v[198:201], v[44:47]
	v_mfma_f32_16x16x32_bf16 v[40:43], v[156:159], v[198:201], v[40:43]
	v_mfma_f32_16x16x32_bf16 v[28:31], v[140:143], v[206:209], v[28:31]
	v_mfma_f32_16x16x32_bf16 v[24:27], v[156:159], v[206:209], v[24:27]
	v_mfma_f32_16x16x32_bf16 v[12:15], v[140:143], v[214:217], v[12:15]
	v_mfma_f32_16x16x32_bf16 v[8:11], v[156:159], v[214:217], v[8:11]
	v_mfma_f32_16x16x32_bf16 v[60:63], v[152:155], v[194:197], v[60:63]
	v_mfma_f32_16x16x32_bf16 v[56:59], v[160:163], v[194:197], v[56:59]
	v_mfma_f32_16x16x32_bf16 v[44:47], v[152:155], v[202:205], v[44:47]
	v_mfma_f32_16x16x32_bf16 v[40:43], v[160:163], v[202:205], v[40:43]
	v_mfma_f32_16x16x32_bf16 v[28:31], v[152:155], v[210:213], v[28:31]
	v_mfma_f32_16x16x32_bf16 v[24:27], v[160:163], v[210:213], v[24:27]
	v_mfma_f32_16x16x32_bf16 v[12:15], v[152:155], v[218:221], v[12:15]
	v_mfma_f32_16x16x32_bf16 v[8:11], v[160:163], v[218:221], v[8:11]
	s_setprio 0
	s_setprio 1
	v_mfma_f32_16x16x32_bf16 v[52:55], v[164:167], v[180:183], v[52:55]
	v_mfma_f32_16x16x32_bf16 v[48:51], v[172:175], v[180:183], v[48:51]
	v_mfma_f32_16x16x32_bf16 v[36:39], v[164:167], v[198:201], v[36:39]
	v_mfma_f32_16x16x32_bf16 v[32:35], v[172:175], v[198:201], v[32:35]
	v_mfma_f32_16x16x32_bf16 v[20:23], v[164:167], v[206:209], v[20:23]
	v_mfma_f32_16x16x32_bf16 v[16:19], v[172:175], v[206:209], v[16:19]
	v_mfma_f32_16x16x32_bf16 v[4:7], v[164:167], v[214:217], v[4:7]
	v_mfma_f32_16x16x32_bf16 v[0:3], v[172:175], v[214:217], v[0:3]
	v_mfma_f32_16x16x32_bf16 v[52:55], v[168:171], v[194:197], v[52:55]
	v_mfma_f32_16x16x32_bf16 v[48:51], v[176:179], v[194:197], v[48:51]
	v_mfma_f32_16x16x32_bf16 v[36:39], v[168:171], v[202:205], v[36:39]
	v_mfma_f32_16x16x32_bf16 v[32:35], v[176:179], v[202:205], v[32:35]
	v_mfma_f32_16x16x32_bf16 v[20:23], v[168:171], v[210:213], v[20:23]
	v_mfma_f32_16x16x32_bf16 v[16:19], v[176:179], v[210:213], v[16:19]
	v_mfma_f32_16x16x32_bf16 v[4:7], v[168:171], v[218:221], v[4:7]
	v_mfma_f32_16x16x32_bf16 v[0:3], v[176:179], v[218:221], v[0:3]
	s_setprio 0
	s_barrier
	s_add_u32 s91, s91, 0x100
	s_addc_u32 vcc_lo, vcc_lo, 0
	s_add_u32 s2, s2, 0x100
	s_addc_u32 s3, s3, 0
	s_cmp_ge_i32 vcc_hi, s85
	s_mov_b32 s48, vcc_hi
	s_cbranch_scc0 .LBB0_540
	v_add_u32_e32 v192, 64, v191

; template <class Epi, class Sched, bool ALIGN_EPI = false, bool SP2 = false>
; __device__ __forceinline__ void gemm_phase(PG8_LAS unsigned char* lds, const Gemm g, const Sched& S, const Epi& E, int wid_s_) {
;     ...
;     for (int i = 0; i < 2; ++i) { int R, C; stage_rc(tid * 16 + i * 8192, R, C); const int Rb = Epi::PERM ? ((R & ~31) + perm32(R & 31)) : R;
;         voffA[i] = (unsigned)(R * K + C) * 2u; voffB[i] = (unsigned)(Rb * K + C) * 2u; }
;     const size_t kstep = (size_t)(BK * 2);
;     const size_t hstep = (size_t)HALF * K * 2;
;     const size_t tstep = 2 * hstep;
;     ...
;     f32x4 acc[2][2][4][2];
; #pragma unroll
;     for (int a = 0; a < 2; ++a)
; #pragma unroll
;         for (int b = 0; b < 2; ++b)
; #pragma unroll
;             for (int m = 0; m < 4; ++m)
; #pragma unroll
;                 for (int n = 0; n < 2; ++n) acc[a][b][m][n] = (f32x4){0.f, 0.f, 0.f, 0.f};
.LBB0_626:
	v_readlane_b32 s2, v255, 54
	v_mov_b32_e32 v137, 0
	v_readlane_b32 s3, v255, 55
	s_andn2_b64 vcc, exec, s[2:3]
	v_mov_b32_e32 v136, v137
	v_mov_b32_e32 v135, v137
	v_mov_b32_e32 v134, v137
	v_mov_b32_e32 v133, v137
	v_mov_b32_e32 v132, v137
	v_mov_b32_e32 v131, v137
	v_mov_b32_e32 v130, v137
	v_mov_b32_e32 v121, v137
	v_mov_b32_e32 v120, v137
	v_mov_b32_e32 v119, v137
	v_mov_b32_e32 v118, v137
	v_mov_b32_e32 v117, v137
	v_mov_b32_e32 v116, v137
	v_mov_b32_e32 v115, v137
	v_mov_b32_e32 v114, v137
	v_mov_b32_e32 v113, v137
	v_mov_b32_e32 v112, v137
	v_mov_b32_e32 v111, v137
	v_mov_b32_e32 v110, v137
	v_mov_b32_e32 v109, v137
	v_mov_b32_e32 v108, v137
	v_mov_b32_e32 v107, v137
	v_mov_b32_e32 v106, v137
	v_mov_b32_e32 v105, v137
	v_mov_b32_e32 v104, v137
	v_mov_b32_e32 v103, v137
	v_mov_b32_e32 v102, v137
	v_mov_b32_e32 v101, v137
	v_mov_b32_e32 v100, v137
	v_mov_b32_e32 v99, v137
	v_mov_b32_e32 v98, v137
	v_mov_b32_e32 v63, v137
	v_mov_b32_e32 v62, v137
	v_mov_b32_e32 v61, v137
	v_mov_b32_e32 v60, v137
	v_mov_b32_e32 v59, v137
	v_mov_b32_e32 v58, v137
	v_mov_b32_e32 v57, v137
	v_mov_b32_e32 v56, v137
	v_mov_b32_e32 v55, v137
	v_mov_b32_e32 v54, v137
	v_mov_b32_e32 v53, v137
	v_mov_b32_e32 v52, v137
	v_mov_b32_e32 v51, v137
	v_mov_b32_e32 v50, v137
	v_mov_b32_e32 v49, v137
	v_mov_b32_e32 v48, v137
	v_mov_b32_e32 v47, v137
	v_mov_b32_e32 v46, v137
	v_mov_b32_e32 v45, v137
	v_mov_b32_e32 v44, v137
	v_mov_b32_e32 v43, v137
	v_mov_b32_e32 v42, v137
	v_mov_b32_e32 v41, v137
	v_mov_b32_e32 v40, v137
	v_mov_b32_e32 v39, v137
	v_mov_b32_e32 v38, v137
	v_mov_b32_e32 v37, v137
	v_mov_b32_e32 v36, v137
	v_mov_b32_e32 v35, v137
	v_mov_b32_e32 v34, v137
	v_mov_b32_e32 v33, v137
	v_mov_b32_e32 v32, v137
	v_mov_b32_e32 v95, v137
	v_mov_b32_e32 v94, v137
	v_mov_b32_e32 v93, v137
	v_mov_b32_e32 v92, v137
	v_mov_b32_e32 v91, v137
	v_mov_b32_e32 v90, v137
	v_mov_b32_e32 v89, v137
	v_mov_b32_e32 v88, v137
	v_mov_b32_e32 v87, v137
	v_mov_b32_e32 v86, v137
	v_mov_b32_e32 v85, v137
	v_mov_b32_e32 v84, v137
	v_mov_b32_e32 v83, v137
	v_mov_b32_e32 v82, v137
	v_mov_b32_e32 v81, v137
	v_mov_b32_e32 v80, v137
	v_mov_b32_e32 v79, v137
	v_mov_b32_e32 v78, v137
	v_mov_b32_e32 v77, v137
	v_mov_b32_e32 v76, v137
	v_mov_b32_e32 v75, v137
	v_mov_b32_e32 v74, v137
	v_mov_b32_e32 v73, v137
	v_mov_b32_e32 v72, v137
	v_mov_b32_e32 v71, v137
	v_mov_b32_e32 v70, v137
	v_mov_b32_e32 v69, v137
	v_mov_b32_e32 v68, v137
	v_mov_b32_e32 v67, v137
	v_mov_b32_e32 v66, v137
	v_mov_b32_e32 v65, v137
	v_mov_b32_e32 v64, v137
	v_mov_b32_e32 v31, v137
	v_mov_b32_e32 v30, v137
	v_mov_b32_e32 v29, v137
	v_mov_b32_e32 v28, v137
	v_mov_b32_e32 v27, v137
	v_mov_b32_e32 v26, v137
	v_mov_b32_e32 v25, v137
	v_mov_b32_e32 v24, v137
	v_mov_b32_e32 v23, v137
	v_mov_b32_e32 v22, v137
	v_mov_b32_e32 v21, v137
	v_mov_b32_e32 v20, v137
	v_mov_b32_e32 v19, v137
	v_mov_b32_e32 v18, v137
	v_mov_b32_e32 v17, v137
	v_mov_b32_e32 v16, v137
	v_mov_b32_e32 v15, v137
	v_mov_b32_e32 v14, v137
	v_mov_b32_e32 v13, v137
	v_mov_b32_e32 v12, v137
	v_mov_b32_e32 v11, v137
	v_mov_b32_e32 v10, v137
	v_mov_b32_e32 v9, v137
	v_mov_b32_e32 v8, v137
	v_mov_b32_e32 v7, v137
	v_mov_b32_e32 v6, v137
	v_mov_b32_e32 v5, v137
	v_mov_b32_e32 v4, v137
	v_mov_b32_e32 v3, v137
	v_mov_b32_e32 v2, v137
	v_mov_b32_e32 v1, v137
	v_mov_b32_e32 v0, v137
	s_cbranch_vccnz .LBB0_630
	s_add_u32 vcc_lo, s48, 0x100
	s_addc_u32 vcc_hi, s49, 0
	s_add_u32 s2, s84, 0x80
	v_mov_b32_e32 v0, 0
	s_addc_u32 s3, s85, 0
	s_mov_b32 s48, 0
	v_mov_b32_e32 v1, v0
	v_mov_b32_e32 v2, v0
	v_mov_b32_e32 v3, v0
	v_mov_b32_e32 v4, v0
	v_mov_b32_e32 v5, v0
	v_mov_b32_e32 v6, v0
	v_mov_b32_e32 v7, v0
	v_mov_b32_e32 v8, v0
	v_mov_b32_e32 v9, v0
	v_mov_b32_e32 v10, v0
	v_mov_b32_e32 v11, v0
	v_mov_b32_e32 v12, v0
	v_mov_b32_e32 v13, v0
	v_mov_b32_e32 v14, v0
	v_mov_b32_e32 v15, v0
	v_mov_b32_e32 v16, v0
	v_mov_b32_e32 v17, v0
	v_mov_b32_e32 v18, v0
	v_mov_b32_e32 v19, v0
	v_mov_b32_e32 v20, v0
	v_mov_b32_e32 v21, v0
	v_mov_b32_e32 v22, v0
	v_mov_b32_e32 v23, v0
	v_mov_b32_e32 v24, v0
	v_mov_b32_e32 v25, v0
	v_mov_b32_e32 v26, v0
	v_mov_b32_e32 v27, v0
	v_mov_b32_e32 v28, v0
	v_mov_b32_e32 v29, v0
	v_mov_b32_e32 v30, v0
	v_mov_b32_e32 v31, v0
	v_mov_b32_e32 v64, v0
	v_mov_b32_e32 v65, v0
	v_mov_b32_e32 v66, v0
	v_mov_b32_e32 v67, v0
	v_mov_b32_e32 v68, v0
	v_mov_b32_e32 v69, v0
	v_mov_b32_e32 v70, v0
	v_mov_b32_e32 v71, v0
	v_mov_b32_e32 v72, v0
	v_mov_b32_e32 v73, v0
	v_mov_b32_e32 v74, v0
	v_mov_b32_e32 v75, v0
	v_mov_b32_e32 v76, v0
	v_mov_b32_e32 v77, v0
	v_mov_b32_e32 v78, v0
	v_mov_b32_e32 v79, v0
	v_mov_b32_e32 v80, v0
	v_mov_b32_e32 v81, v0
	v_mov_b32_e32 v82, v0
	v_mov_b32_e32 v83, v0
	v_mov_b32_e32 v84, v0
	v_mov_b32_e32 v85, v0
	v_mov_b32_e32 v86, v0
	v_mov_b32_e32 v87, v0
	v_mov_b32_e32 v88, v0
	v_mov_b32_e32 v89, v0
	v_mov_b32_e32 v90, v0
	v_mov_b32_e32 v91, v0
	v_mov_b32_e32 v92, v0
	v_mov_b32_e32 v93, v0
	v_mov_b32_e32 v94, v0
	v_mov_b32_e32 v95, v0
	v_mov_b32_e32 v32, v0
	v_mov_b32_e32 v33, v0
	v_mov_b32_e32 v34, v0
	v_mov_b32_e32 v35, v0
	v_mov_b32_e32 v36, v0
	v_mov_b32_e32 v37, v0
	v_mov_b32_e32 v38, v0
	v_mov_b32_e32 v39, v0
	v_mov_b32_e32 v40, v0
	v_mov_b32_e32 v41, v0
	v_mov_b32_e32 v42, v0
	v_mov_b32_e32 v43, v0
	v_mov_b32_e32 v44, v0
	v_mov_b32_e32 v45, v0
	v_mov_b32_e32 v46, v0
	v_mov_b32_e32 v47, v0
	v_mov_b32_e32 v48, v0
	v_mov_b32_e32 v49, v0
	v_mov_b32_e32 v50, v0
	v_mov_b32_e32 v51, v0
	v_mov_b32_e32 v52, v0
	v_mov_b32_e32 v53, v0
	v_mov_b32_e32 v54, v0
	v_mov_b32_e32 v55, v0
	v_mov_b32_e32 v56, v0
	v_mov_b32_e32 v57, v0
	v_mov_b32_e32 v58, v0
	v_mov_b32_e32 v59, v0
	v_mov_b32_e32 v60, v0
	v_mov_b32_e32 v61, v0
	v_mov_b32_e32 v62, v0
	v_mov_b32_e32 v63, v0
	v_mov_b32_e32 v98, v0
	v_mov_b32_e32 v99, v0
	v_mov_b32_e32 v100, v0
	v_mov_b32_e32 v101, v0
	v_mov_b32_e32 v102, v0
	v_mov_b32_e32 v103, v0
	v_mov_b32_e32 v104, v0
	v_mov_b32_e32 v105, v0
	v_mov_b32_e32 v106, v0
	v_mov_b32_e32 v107, v0
	v_mov_b32_e32 v108, v0
	v_mov_b32_e32 v109, v0
	v_mov_b32_e32 v110, v0
	v_mov_b32_e32 v111, v0
	v_mov_b32_e32 v112, v0
	v_mov_b32_e32 v113, v0
	v_mov_b32_e32 v114, v0
	v_mov_b32_e32 v115, v0
	v_mov_b32_e32 v116, v0
	v_mov_b32_e32 v117, v0
	v_mov_b32_e32 v118, v0
	v_mov_b32_e32 v119, v0
	v_mov_b32_e32 v120, v0
	v_mov_b32_e32 v121, v0
	v_mov_b32_e32 v130, v0
	v_mov_b32_e32 v131, v0
	v_mov_b32_e32 v132, v0
	v_mov_b32_e32 v133, v0
	v_mov_b32_e32 v134, v0
	v_mov_b32_e32 v135, v0
	v_mov_b32_e32 v136, v0
	v_mov_b32_e32 v137, v0
	v_add_u32_e32 v151, s10, v96
	v_add_u32_e32 v178, s10, v142
	v_add_u32_e32 v179, s10, v138
	v_add_u32_e32 v188, s10, v140
	v_add_u32_e32 v189, s42, v96
	v_add_u32_e32 v192, s42, v142
	v_add_u32_e32 v195, s42, v138
	v_add_u32_e32 v224, s42, v140
	v_add_u32_e32 v193, s42, v151
	v_add_u32_e32 v194, s42, v178
; #define PG8_STAGE(bufoff, gbase, voff) do { _Pragma("unroll") for (int _i = 0; _i < 2; ++_i) \
;         __builtin_amdgcn_global_load_lds((const unsigned*)((const char*)(gbase) + (voff)[_i]), (PG8_LAS unsigned*)(lds + (bufoff) + ldsw + _i * 8192), 16, 0, 0); } while (0)
; #define PG8_LDA(dst, b, h) do { _Pragma("unroll") for (int m = 0; m < 4; ++m) _Pragma("unroll") for (int k = 0; k < 2; ++k) dst[m][k] = *(const PG8_LAS bf16x8*)(lds + PG8_SA(b, h) + aoff + m * 2048 + k * 1024); } while (0)
; #define PG8_LDB(dst, b, h) do { _Pragma("unroll") for (int n = 0; n < 2; ++n) _Pragma("unroll") for (int k = 0; k < 2; ++k) dst[n][k] = *(const PG8_LAS bf16x8*)(lds + PG8_SB(b, h) + boff + n * 2048 + k * 1024); } while (0)
; #define PG8_MMA(ai, bj, At, Bt) do { __builtin_amdgcn_s_setprio(1); _Pragma("unroll") for (int m = 0; m < 4; ++m) _Pragma("unroll") for (int n = 0; n < 2; ++n) _Pragma("unroll") for (int k = 0; k < 2; ++k) \
;         acc[ai][bj][m][n] = __builtin_amdgcn_mfma_f32_16x16x32_bf16(Bt[n][k], At[m][k], acc[ai][bj][m][n], 0, 0, 0); __builtin_amdgcn_s_setprio(0); } while (0)
; #define PG8_WAIT_V(n) asm volatile("s_waitcnt vmcnt(" #n ")" ::: "memory")
; #define PG8_BAR __builtin_amdgcn_s_barrier()
; template <class Epi, class Sched, bool ALIGN_EPI = false, bool SP2 = false>
; __device__ __forceinline__ void gemm_phase(PG8_LAS unsigned char* lds, const Gemm g, const Sched& S, const Epi& E, int wid_s_) {
;     ...
;         for (int t = 0; t < nt; t += 2) {
;             const bool last = (t == nt - 2);
;             const char* a1 = cA + (size_t)(t + 1) * kstep;
;             const char* a2 = last ? nA : cA + (size_t)(t + 2) * kstep; const char* b2 = last ? nB : cB + (size_t)(t + 2) * kstep;
;             const char* a3 = a2 + kstep; const char* b3 = b2 + kstep;
;             if (last && has_next) S.a_ready(nxt);
;             if constexpr (SP2) {
;             PG8_LDB(B0, 0, 0); PG8_LDB(B1, 0, 1); PG8_SCHED; PG8_LDA(At, 0, 0); PG8_STAGE(PG8_SA(1, 1), a1 + hstep, voffA);
;             PG8_WAIT_V(8); PG8_WAIT_L(0); PG8_BAR; PG8_MMA(0, 0, At, B0); PG8_MMA(0, 1, At, B1); PG8_BAR; PG8_SCHED;
;             PG8_LDA(At, 0, 1); PG8_STAGE(PG8_SB(0, 0), b2, voffB); PG8_STAGE(PG8_SB(0, 1), b2 + hstep, voffB); PG8_STAGE(PG8_SA(0, 0), a2, voffA);
;             PG8_WAIT_V(8); PG8_WAIT_L(0); PG8_BAR; PG8_MMA(1, 0, At, B0); PG8_MMA(1, 1, At, B1); PG8_BAR; PG8_SCHED;
.LBB0_628:
	s_add_i32 s84, s48, 2
	s_add_u32 s78, s2, 0x80
	s_addc_u32 s49, s3, 0
	s_add_i32 s85, 16, 0x10000
	s_cmp_eq_u32 s5, s48
	s_cselect_b32 s49, s81, s49
	s_cselect_b32 s48, s80, s78
	v_add_u32_e32 v150, s85, v147
	s_cselect_b32 s79, s83, vcc_hi
	s_cselect_b32 s78, s82, vcc_lo
	s_add_i32 s20, 16, 0x14000
	ds_read_b128 v[122:125], v150
	ds_read_b128 v[126:129], v150 offset:1024
	ds_read_b128 v[154:157], v150 offset:2048
	ds_read_b128 v[158:161], v150 offset:3072
	v_add_u32_e32 v150, s20, v147
	ds_read_b128 v[162:165], v150
	ds_read_b128 v[166:169], v150 offset:1024
	ds_read_b128 v[170:173], v150 offset:2048
	ds_read_b128 v[174:177], v150 offset:3072
	s_add_i32 m0, s51, 0xc000
	ds_read_b128 v[180:183], v149
	ds_read_b128 v[196:199], v149 offset:1024
	ds_read_b128 v[200:203], v149 offset:2048
	ds_read_b128 v[204:207], v149 offset:3072
	ds_read_b128 v[208:211], v149 offset:4096
	ds_read_b128 v[212:215], v149 offset:5120
	ds_read_b128 v[216:219], v149 offset:6144
	ds_read_b128 v[220:223], v149 offset:7168
	global_load_lds_dwordx4 v152, s[2:3]
	s_add_i32 m0, s51, 0xe000
	s_nop 0
	global_load_lds_dwordx4 v144, s[2:3]
	s_waitcnt vmcnt(8)
	s_waitcnt lgkmcnt(0)
	s_barrier
	s_setprio 1
	s_waitcnt lgkmcnt(0)
	v_mfma_f32_16x16x32_bf16 v[134:137], v[122:125], v[180:183], v[134:137]
	v_mfma_f32_16x16x32_bf16 v[130:133], v[154:157], v[180:183], v[130:133]
	v_mfma_f32_16x16x32_bf16 v[118:121], v[122:125], v[200:203], v[118:121]
	v_mfma_f32_16x16x32_bf16 v[114:117], v[154:157], v[200:203], v[114:117]
	v_mfma_f32_16x16x32_bf16 v[110:113], v[122:125], v[208:211], v[110:113]
	v_mfma_f32_16x16x32_bf16 v[106:109], v[154:157], v[208:211], v[106:109]
	v_mfma_f32_16x16x32_bf16 v[102:105], v[122:125], v[216:219], v[102:105]
	v_mfma_f32_16x16x32_bf16 v[98:101], v[154:157], v[216:219], v[98:101]
	v_mfma_f32_16x16x32_bf16 v[134:137], v[126:129], v[196:199], v[134:137]
	v_mfma_f32_16x16x32_bf16 v[130:133], v[158:161], v[196:199], v[130:133]
	v_mfma_f32_16x16x32_bf16 v[118:121], v[126:129], v[204:207], v[118:121]
	v_mfma_f32_16x16x32_bf16 v[114:117], v[158:161], v[204:207], v[114:117]
	v_mfma_f32_16x16x32_bf16 v[110:113], v[126:129], v[212:215], v[110:113]
	v_mfma_f32_16x16x32_bf16 v[106:109], v[158:161], v[212:215], v[106:109]
	v_mfma_f32_16x16x32_bf16 v[102:105], v[126:129], v[220:223], v[102:105]
	v_mfma_f32_16x16x32_bf16 v[98:101], v[158:161], v[220:223], v[98:101]
	s_setprio 0
	s_setprio 1
	v_mfma_f32_16x16x32_bf16 v[60:63], v[162:165], v[180:183], v[60:63]
	v_mfma_f32_16x16x32_bf16 v[56:59], v[170:173], v[180:183], v[56:59]
	v_mfma_f32_16x16x32_bf16 v[52:55], v[162:165], v[200:203], v[52:55]
	v_mfma_f32_16x16x32_bf16 v[48:51], v[170:173], v[200:203], v[48:51]
	v_mfma_f32_16x16x32_bf16 v[44:47], v[162:165], v[208:211], v[44:47]
	v_mfma_f32_16x16x32_bf16 v[40:43], v[170:173], v[208:211], v[40:43]
	v_mfma_f32_16x16x32_bf16 v[36:39], v[162:165], v[216:219], v[36:39]
	v_mfma_f32_16x16x32_bf16 v[32:35], v[170:173], v[216:219], v[32:35]
	v_mfma_f32_16x16x32_bf16 v[60:63], v[166:169], v[196:199], v[60:63]
	v_mfma_f32_16x16x32_bf16 v[56:59], v[174:177], v[196:199], v[56:59]
	v_mfma_f32_16x16x32_bf16 v[52:55], v[166:169], v[204:207], v[52:55]
	v_mfma_f32_16x16x32_bf16 v[48:51], v[174:177], v[204:207], v[48:51]
	v_mfma_f32_16x16x32_bf16 v[44:47], v[166:169], v[212:215], v[44:47]
	v_mfma_f32_16x16x32_bf16 v[40:43], v[174:177], v[212:215], v[40:43]
	v_mfma_f32_16x16x32_bf16 v[36:39], v[166:169], v[220:223], v[36:39]
	v_mfma_f32_16x16x32_bf16 v[32:35], v[174:177], v[220:223], v[32:35]
	s_setprio 0
	s_barrier
	s_add_i32 s21, s85, s50
	s_mov_b32 m0, s21
	ds_read_b128 v[180:183], v149 offset:16384
	ds_read_b128 v[196:199], v149 offset:17408
	ds_read_b128 v[200:203], v149 offset:18432
	ds_read_b128 v[204:207], v149 offset:19456
	ds_read_b128 v[208:211], v149 offset:20480
	ds_read_b128 v[212:215], v149 offset:21504
	ds_read_b128 v[216:219], v149 offset:22528
	ds_read_b128 v[220:223], v149 offset:23552
	global_load_lds_dwordx4 v96, s[78:79]
	s_add_i32 m0, s21, 0x2000
	s_add_i32 s20, s20, s50
	global_load_lds_dwordx4 v142, s[78:79]
	s_mov_b32 m0, s20
	s_nop 0
	global_load_lds_dwordx4 v151, s[78:79]
	s_add_i32 m0, s20, 0x2000
	s_nop 0
	global_load_lds_dwordx4 v178, s[78:79]
	s_mov_b32 m0, s51
	s_nop 0
	global_load_lds_dwordx4 v138, s[48:49]
	s_mov_b32 m0, s86
	s_nop 0
	global_load_lds_dwordx4 v140, s[48:49]
	s_waitcnt vmcnt(8)
	s_waitcnt lgkmcnt(0)
	s_barrier
	s_setprio 1
	s_waitcnt lgkmcnt(0)
	v_mfma_f32_16x16x32_bf16 v[92:95], v[122:125], v[180:183], v[92:95]
	v_mfma_f32_16x16x32_bf16 v[88:91], v[154:157], v[180:183], v[88:91]
	v_mfma_f32_16x16x32_bf16 v[84:87], v[122:125], v[200:203], v[84:87]
	v_mfma_f32_16x16x32_bf16 v[80:83], v[154:157], v[200:203], v[80:83]
	v_mfma_f32_16x16x32_bf16 v[76:79], v[122:125], v[208:211], v[76:79]
	v_mfma_f32_16x16x32_bf16 v[72:75], v[154:157], v[208:211], v[72:75]
	v_mfma_f32_16x16x32_bf16 v[68:71], v[122:125], v[216:219], v[68:71]
	v_mfma_f32_16x16x32_bf16 v[64:67], v[154:157], v[216:219], v[64:67]
	v_mfma_f32_16x16x32_bf16 v[92:95], v[126:129], v[196:199], v[92:95]
	v_mfma_f32_16x16x32_bf16 v[88:91], v[158:161], v[196:199], v[88:91]
	v_mfma_f32_16x16x32_bf16 v[84:87], v[126:129], v[204:207], v[84:87]
	v_mfma_f32_16x16x32_bf16 v[80:83], v[158:161], v[204:207], v[80:83]
	v_mfma_f32_16x16x32_bf16 v[76:79], v[126:129], v[212:215], v[76:79]
	v_mfma_f32_16x16x32_bf16 v[72:75], v[158:161], v[212:215], v[72:75]
	v_mfma_f32_16x16x32_bf16 v[68:71], v[126:129], v[220:223], v[68:71]
	v_mfma_f32_16x16x32_bf16 v[64:67], v[158:161], v[220:223], v[64:67]
	s_setprio 0
	s_setprio 1
	v_mfma_f32_16x16x32_bf16 v[28:31], v[162:165], v[180:183], v[28:31]
	v_mfma_f32_16x16x32_bf16 v[24:27], v[170:173], v[180:183], v[24:27]
	v_mfma_f32_16x16x32_bf16 v[20:23], v[162:165], v[200:203], v[20:23]
	v_mfma_f32_16x16x32_bf16 v[16:19], v[170:173], v[200:203], v[16:19]
	v_mfma_f32_16x16x32_bf16 v[12:15], v[162:165], v[208:211], v[12:15]
	v_mfma_f32_16x16x32_bf16 v[8:11], v[170:173], v[208:211], v[8:11]
	v_mfma_f32_16x16x32_bf16 v[4:7], v[162:165], v[216:219], v[4:7]
	v_mfma_f32_16x16x32_bf16 v[0:3], v[170:173], v[216:219], v[0:3]
	v_mfma_f32_16x16x32_bf16 v[28:31], v[166:169], v[196:199], v[28:31]
	v_mfma_f32_16x16x32_bf16 v[24:27], v[174:177], v[196:199], v[24:27]
	v_mfma_f32_16x16x32_bf16 v[20:23], v[166:169], v[204:207], v[20:23]
	v_mfma_f32_16x16x32_bf16 v[16:19], v[174:177], v[204:207], v[16:19]
	v_mfma_f32_16x16x32_bf16 v[12:15], v[166:169], v[212:215], v[12:15]
	v_mfma_f32_16x16x32_bf16 v[8:11], v[174:177], v[212:215], v[8:11]
	v_mfma_f32_16x16x32_bf16 v[4:7], v[166:169], v[220:223], v[4:7]
	v_mfma_f32_16x16x32_bf16 v[0:3], v[174:177], v[220:223], v[0:3]
	s_setprio 0
	s_barrier
; #define PG8_STAGE(bufoff, gbase, voff) do { _Pragma("unroll") for (int _i = 0; _i < 2; ++_i) \
;         __builtin_amdgcn_global_load_lds((const unsigned*)((const char*)(gbase) + (voff)[_i]), (PG8_LAS unsigned*)(lds + (bufoff) + ldsw + _i * 8192), 16, 0, 0); } while (0)
; #define PG8_LDA(dst, b, h) do { _Pragma("unroll") for (int m = 0; m < 4; ++m) _Pragma("unroll") for (int k = 0; k < 2; ++k) dst[m][k] = *(const PG8_LAS bf16x8*)(lds + PG8_SA(b, h) + aoff + m * 2048 + k * 1024); } while (0)
; #define PG8_LDB(dst, b, h) do { _Pragma("unroll") for (int n = 0; n < 2; ++n) _Pragma("unroll") for (int k = 0; k < 2; ++k) dst[n][k] = *(const PG8_LAS bf16x8*)(lds + PG8_SB(b, h) + boff + n * 2048 + k * 1024); } while (0)
; #define PG8_MMA(ai, bj, At, Bt) do { __builtin_amdgcn_s_setprio(1); _Pragma("unroll") for (int m = 0; m < 4; ++m) _Pragma("unroll") for (int n = 0; n < 2; ++n) _Pragma("unroll") for (int k = 0; k < 2; ++k) \
;         acc[ai][bj][m][n] = __builtin_amdgcn_mfma_f32_16x16x32_bf16(Bt[n][k], At[m][k], acc[ai][bj][m][n], 0, 0, 0); __builtin_amdgcn_s_setprio(0); } while (0)
; #define PG8_WAIT_V(n) asm volatile("s_waitcnt vmcnt(" #n ")" ::: "memory")
; #define PG8_WAIT_L(n) asm volatile("s_waitcnt lgkmcnt(" #n ")" ::: "memory")
; #define PG8_BAR __builtin_amdgcn_s_barrier()
; #define PG8_SCHED __builtin_amdgcn_sched_barrier(0)
; template <class Epi, class Sched, bool ALIGN_EPI = false, bool SP2 = false>
; __device__ __forceinline__ void gemm_phase(PG8_LAS unsigned char* lds, const Gemm g, const Sched& S, const Epi& E, int wid_s_) {
;     ...
;             PG8_LDB(B0, 1, 0); PG8_LDB(B1, 1, 1); PG8_SCHED; PG8_LDA(At, 1, 0); PG8_STAGE(PG8_SA(0, 1), a2 + hstep, voffA);
;             PG8_WAIT_V(8); PG8_WAIT_L(0); PG8_BAR; PG8_MMA(0, 0, At, B0); PG8_MMA(0, 1, At, B1); PG8_BAR; PG8_SCHED;
;             PG8_LDA(At, 1, 1); PG8_STAGE(PG8_SB(1, 0), b3, voffB); PG8_STAGE(PG8_SB(1, 1), b3 + hstep, voffB); PG8_STAGE(PG8_SA(1, 0), a3, voffA);
;             PG8_WAIT_V(8); PG8_WAIT_L(0); PG8_BAR; PG8_MMA(1, 0, At, B0); PG8_MMA(1, 1, At, B1); PG8_BAR; PG8_SCHED;
	s_add_i32 s20, 16, 0x18000
	s_add_i32 s21, 16, 0x1c000
	v_add_u32_e32 v158, s20, v147
	v_add_u32_e32 v174, s21, v147
	ds_read_b128 v[122:125], v158
	ds_read_b128 v[126:129], v158 offset:1024
	ds_read_b128 v[154:157], v158 offset:2048
	ds_read_b128 v[158:161], v158 offset:3072
	ds_read_b128 v[162:165], v174
	ds_read_b128 v[166:169], v174 offset:1024
	ds_read_b128 v[170:173], v174 offset:2048
	ds_read_b128 v[174:177], v174 offset:3072
	s_mov_b32 m0, s87
	ds_read_b128 v[180:183], v149 offset:32768
	ds_read_b128 v[196:199], v149 offset:33792
	ds_read_b128 v[200:203], v149 offset:34816
	ds_read_b128 v[204:207], v149 offset:35840
	ds_read_b128 v[208:211], v149 offset:36864
	ds_read_b128 v[212:215], v149 offset:37888
	ds_read_b128 v[216:219], v149 offset:38912
	ds_read_b128 v[220:223], v149 offset:39936
	global_load_lds_dwordx4 v179, s[48:49]
	s_mov_b32 m0, s88
	s_nop 0
	global_load_lds_dwordx4 v188, s[48:49]
	s_waitcnt vmcnt(8)
	s_waitcnt lgkmcnt(0)
	s_barrier
	s_setprio 1
	s_waitcnt lgkmcnt(0)
	v_mfma_f32_16x16x32_bf16 v[134:137], v[122:125], v[180:183], v[134:137]
	v_mfma_f32_16x16x32_bf16 v[130:133], v[154:157], v[180:183], v[130:133]
	v_mfma_f32_16x16x32_bf16 v[118:121], v[122:125], v[200:203], v[118:121]
	v_mfma_f32_16x16x32_bf16 v[114:117], v[154:157], v[200:203], v[114:117]
	v_mfma_f32_16x16x32_bf16 v[110:113], v[122:125], v[208:211], v[110:113]
	v_mfma_f32_16x16x32_bf16 v[106:109], v[154:157], v[208:211], v[106:109]
	v_mfma_f32_16x16x32_bf16 v[102:105], v[122:125], v[216:219], v[102:105]
	v_mfma_f32_16x16x32_bf16 v[98:101], v[154:157], v[216:219], v[98:101]
	v_mfma_f32_16x16x32_bf16 v[134:137], v[126:129], v[196:199], v[134:137]
	v_mfma_f32_16x16x32_bf16 v[130:133], v[158:161], v[196:199], v[130:133]
	v_mfma_f32_16x16x32_bf16 v[118:121], v[126:129], v[204:207], v[118:121]
	v_mfma_f32_16x16x32_bf16 v[114:117], v[158:161], v[204:207], v[114:117]
	v_mfma_f32_16x16x32_bf16 v[110:113], v[126:129], v[212:215], v[110:113]
	v_mfma_f32_16x16x32_bf16 v[106:109], v[158:161], v[212:215], v[106:109]
	v_mfma_f32_16x16x32_bf16 v[102:105], v[126:129], v[220:223], v[102:105]
	v_mfma_f32_16x16x32_bf16 v[98:101], v[158:161], v[220:223], v[98:101]
	s_setprio 0
	s_setprio 1
	v_mfma_f32_16x16x32_bf16 v[60:63], v[162:165], v[180:183], v[60:63]
	v_mfma_f32_16x16x32_bf16 v[56:59], v[170:173], v[180:183], v[56:59]
	v_mfma_f32_16x16x32_bf16 v[52:55], v[162:165], v[200:203], v[52:55]
	v_mfma_f32_16x16x32_bf16 v[48:51], v[170:173], v[200:203], v[48:51]
	v_mfma_f32_16x16x32_bf16 v[44:47], v[162:165], v[208:211], v[44:47]
	v_mfma_f32_16x16x32_bf16 v[40:43], v[170:173], v[208:211], v[40:43]
	v_mfma_f32_16x16x32_bf16 v[36:39], v[162:165], v[216:219], v[36:39]
	v_mfma_f32_16x16x32_bf16 v[32:35], v[170:173], v[216:219], v[32:35]
	v_mfma_f32_16x16x32_bf16 v[60:63], v[166:169], v[196:199], v[60:63]
	v_mfma_f32_16x16x32_bf16 v[56:59], v[174:177], v[196:199], v[56:59]
	v_mfma_f32_16x16x32_bf16 v[52:55], v[166:169], v[204:207], v[52:55]
	v_mfma_f32_16x16x32_bf16 v[48:51], v[174:177], v[204:207], v[48:51]
	v_mfma_f32_16x16x32_bf16 v[44:47], v[166:169], v[212:215], v[44:47]
	v_mfma_f32_16x16x32_bf16 v[40:43], v[174:177], v[212:215], v[40:43]
	v_mfma_f32_16x16x32_bf16 v[36:39], v[166:169], v[220:223], v[36:39]
	v_mfma_f32_16x16x32_bf16 v[32:35], v[174:177], v[220:223], v[32:35]
	s_setprio 0
	s_barrier
	s_add_i32 s20, s20, s50
	s_mov_b32 m0, s20
	ds_read_b128 v[180:183], v149 offset:49152
	ds_read_b128 v[196:199], v149 offset:50176
	ds_read_b128 v[200:203], v149 offset:51200
	ds_read_b128 v[204:207], v149 offset:52224
	ds_read_b128 v[208:211], v149 offset:53248
	ds_read_b128 v[212:215], v149 offset:54272
	ds_read_b128 v[216:219], v149 offset:55296
	ds_read_b128 v[220:223], v149 offset:56320
	global_load_lds_dwordx4 v189, s[78:79]
	s_add_i32 m0, s20, 0x2000
	s_add_i32 s20, s21, s50
	global_load_lds_dwordx4 v192, s[78:79]
	s_mov_b32 m0, s20
	s_nop 0
	global_load_lds_dwordx4 v193, s[78:79]
	s_add_i32 m0, s20, 0x2000
	s_nop 0
	global_load_lds_dwordx4 v194, s[78:79]
	s_mov_b32 m0, s89
	s_nop 0
	global_load_lds_dwordx4 v195, s[48:49]
	s_mov_b32 m0, s90
	s_nop 0
	global_load_lds_dwordx4 v224, s[48:49]
	s_waitcnt vmcnt(8)
	s_waitcnt lgkmcnt(0)
	s_barrier
	s_setprio 1
	s_waitcnt lgkmcnt(0)
	v_mfma_f32_16x16x32_bf16 v[92:95], v[122:125], v[180:183], v[92:95]
	v_mfma_f32_16x16x32_bf16 v[88:91], v[154:157], v[180:183], v[88:91]
	v_mfma_f32_16x16x32_bf16 v[84:87], v[122:125], v[200:203], v[84:87]
	v_mfma_f32_16x16x32_bf16 v[80:83], v[154:157], v[200:203], v[80:83]
	v_mfma_f32_16x16x32_bf16 v[76:79], v[122:125], v[208:211], v[76:79]
	v_mfma_f32_16x16x32_bf16 v[72:75], v[154:157], v[208:211], v[72:75]
	v_mfma_f32_16x16x32_bf16 v[68:71], v[122:125], v[216:219], v[68:71]
	v_mfma_f32_16x16x32_bf16 v[64:67], v[154:157], v[216:219], v[64:67]
	v_mfma_f32_16x16x32_bf16 v[92:95], v[126:129], v[196:199], v[92:95]
	v_mfma_f32_16x16x32_bf16 v[88:91], v[158:161], v[196:199], v[88:91]
	v_mfma_f32_16x16x32_bf16 v[84:87], v[126:129], v[204:207], v[84:87]
	v_mfma_f32_16x16x32_bf16 v[80:83], v[158:161], v[204:207], v[80:83]
	v_mfma_f32_16x16x32_bf16 v[76:79], v[126:129], v[212:215], v[76:79]
	v_mfma_f32_16x16x32_bf16 v[72:75], v[158:161], v[212:215], v[72:75]
	v_mfma_f32_16x16x32_bf16 v[68:71], v[126:129], v[220:223], v[68:71]
	v_mfma_f32_16x16x32_bf16 v[64:67], v[158:161], v[220:223], v[64:67]
	s_setprio 0
	s_setprio 1
	v_mfma_f32_16x16x32_bf16 v[28:31], v[162:165], v[180:183], v[28:31]
	v_mfma_f32_16x16x32_bf16 v[24:27], v[170:173], v[180:183], v[24:27]
	v_mfma_f32_16x16x32_bf16 v[20:23], v[162:165], v[200:203], v[20:23]
	v_mfma_f32_16x16x32_bf16 v[16:19], v[170:173], v[200:203], v[16:19]
	v_mfma_f32_16x16x32_bf16 v[12:15], v[162:165], v[208:211], v[12:15]
	v_mfma_f32_16x16x32_bf16 v[8:11], v[170:173], v[208:211], v[8:11]
	v_mfma_f32_16x16x32_bf16 v[4:7], v[162:165], v[216:219], v[4:7]
	v_mfma_f32_16x16x32_bf16 v[0:3], v[170:173], v[216:219], v[0:3]
	v_mfma_f32_16x16x32_bf16 v[28:31], v[166:169], v[196:199], v[28:31]
	v_mfma_f32_16x16x32_bf16 v[24:27], v[174:177], v[196:199], v[24:27]
	v_mfma_f32_16x16x32_bf16 v[20:23], v[166:169], v[204:207], v[20:23]
	v_mfma_f32_16x16x32_bf16 v[16:19], v[174:177], v[204:207], v[16:19]
	v_mfma_f32_16x16x32_bf16 v[12:15], v[166:169], v[212:215], v[12:15]
	v_mfma_f32_16x16x32_bf16 v[8:11], v[174:177], v[212:215], v[8:11]
	v_mfma_f32_16x16x32_bf16 v[4:7], v[166:169], v[220:223], v[4:7]
	v_mfma_f32_16x16x32_bf16 v[0:3], v[174:177], v[220:223], v[0:3]
	s_setprio 0
	s_barrier
	s_add_u32 vcc_lo, vcc_lo, 0x100
	s_addc_u32 vcc_hi, vcc_hi, 0
	s_add_u32 s2, s2, 0x100
	s_addc_u32 s3, s3, 0
	s_cmp_ge_i32 s84, s4
	s_mov_b32 s48, s84
	s_cbranch_scc0 .LBB0_628
	s_movk_i32 s21, 0x3fff
	v_add_u32_e32 v192, 64, v191

; #define PG8_STAGE(bufoff, gbase, voff) do { _Pragma("unroll") for (int _i = 0; _i < 2; ++_i) \
;         __builtin_amdgcn_global_load_lds((const unsigned*)((const char*)(gbase) + (voff)[_i]), (PG8_LAS unsigned*)(lds + (bufoff) + ldsw + _i * 8192), 16, 0, 0); } while (0)
; #define PG8_LDA(dst, b, h) do { _Pragma("unroll") for (int m = 0; m < 4; ++m) _Pragma("unroll") for (int k = 0; k < 2; ++k) dst[m][k] = *(const PG8_LAS bf16x8*)(lds + PG8_SA(b, h) + aoff + m * 2048 + k * 1024); } while (0)
; #define PG8_LDB(dst, b, h) do { _Pragma("unroll") for (int n = 0; n < 2; ++n) _Pragma("unroll") for (int k = 0; k < 2; ++k) dst[n][k] = *(const PG8_LAS bf16x8*)(lds + PG8_SB(b, h) + boff + n * 2048 + k * 1024); } while (0)
; #define PG8_MMA(ai, bj, At, Bt) do { __builtin_amdgcn_s_setprio(1); _Pragma("unroll") for (int m = 0; m < 4; ++m) _Pragma("unroll") for (int n = 0; n < 2; ++n) _Pragma("unroll") for (int k = 0; k < 2; ++k) \
;         acc[ai][bj][m][n] = __builtin_amdgcn_mfma_f32_16x16x32_bf16(Bt[n][k], At[m][k], acc[ai][bj][m][n], 0, 0, 0); __builtin_amdgcn_s_setprio(0); } while (0)
; #define PG8_BAR __builtin_amdgcn_s_barrier()
; template <class Epi, class Sched, bool ALIGN_EPI = false, bool SP2 = false>
; __device__ __forceinline__ void gemm_phase(PG8_LAS unsigned char* lds, const Gemm g, const Sched& S, const Epi& E, int wid_s_) {
;     ...
;         for (int t = 0; t < nt; t += 2) {
;             const bool last = (t == nt - 2);
;             const char* a1 = cA + (size_t)(t + 1) * kstep;
;             const char* a2 = last ? nA : cA + (size_t)(t + 2) * kstep; const char* b2 = last ? nB : cB + (size_t)(t + 2) * kstep;
;             const char* a3 = a2 + kstep; const char* b3 = b2 + kstep;
;             if (last && has_next) S.a_ready(nxt);
;             if constexpr (SP2) {
;             PG8_LDB(B0, 0, 0); PG8_LDB(B1, 0, 1); PG8_SCHED; PG8_LDA(At, 0, 0); PG8_STAGE(PG8_SA(1, 1), a1 + hstep, voffA);
;             PG8_WAIT_V(8); PG8_WAIT_L(0); PG8_BAR; PG8_MMA(0, 0, At, B0); PG8_MMA(0, 1, At, B1); PG8_BAR; PG8_SCHED;
;     ...
; #pragma unroll
;         for (int a = 0; a < 2; ++a)
; #pragma unroll
;             for (int b = 0; b < 2; ++b)
; #pragma unroll
;                 for (int m = 0; m < 4; ++m)
; #pragma unroll
;                     for (int n = 0; n < 2; ++n) acc[a][b][m][n] = (f32x4){0.f, 0.f, 0.f, 0.f};
;         cur = nxt; cA = nA; cB = nB; ++ui;
.LBB0_885:
	s_add_u32 vcc_lo, s2, 0x100
	s_addc_u32 vcc_hi, s3, 0
	s_add_u32 s2, s18, 0x80
	v_mov_b32_e32 v0, 0
	s_addc_u32 s3, s19, 0
	s_mov_b32 s18, 0
	v_mov_b32_e32 v1, v0
	v_mov_b32_e32 v2, v0
	v_mov_b32_e32 v3, v0
	v_mov_b32_e32 v4, v0
	v_mov_b32_e32 v5, v0
	v_mov_b32_e32 v6, v0
	v_mov_b32_e32 v7, v0
	v_mov_b32_e32 v8, v0
	v_mov_b32_e32 v9, v0
	v_mov_b32_e32 v10, v0
	v_mov_b32_e32 v11, v0
	v_mov_b32_e32 v12, v0
	v_mov_b32_e32 v13, v0
	v_mov_b32_e32 v14, v0
	v_mov_b32_e32 v15, v0
	v_mov_b32_e32 v24, v0
	v_mov_b32_e32 v25, v0
	v_mov_b32_e32 v26, v0
	v_mov_b32_e32 v27, v0
	v_mov_b32_e32 v28, v0
	v_mov_b32_e32 v29, v0
	v_mov_b32_e32 v30, v0
	v_mov_b32_e32 v31, v0
	v_mov_b32_e32 v40, v0
	v_mov_b32_e32 v41, v0
	v_mov_b32_e32 v42, v0
	v_mov_b32_e32 v43, v0
	v_mov_b32_e32 v44, v0
	v_mov_b32_e32 v45, v0
	v_mov_b32_e32 v46, v0
	v_mov_b32_e32 v47, v0
	v_mov_b32_e32 v16, v0
	v_mov_b32_e32 v17, v0
	v_mov_b32_e32 v18, v0
	v_mov_b32_e32 v19, v0
	v_mov_b32_e32 v20, v0
	v_mov_b32_e32 v21, v0
	v_mov_b32_e32 v22, v0
	v_mov_b32_e32 v23, v0
	v_mov_b32_e32 v32, v0
	v_mov_b32_e32 v33, v0
	v_mov_b32_e32 v34, v0
	v_mov_b32_e32 v35, v0
	v_mov_b32_e32 v36, v0
	v_mov_b32_e32 v37, v0
	v_mov_b32_e32 v38, v0
	v_mov_b32_e32 v39, v0
	v_mov_b32_e32 v48, v0
	v_mov_b32_e32 v49, v0
	v_mov_b32_e32 v50, v0
	v_mov_b32_e32 v51, v0
	v_mov_b32_e32 v52, v0
	v_mov_b32_e32 v53, v0
	v_mov_b32_e32 v54, v0
	v_mov_b32_e32 v55, v0
	v_mov_b32_e32 v56, v0
	v_mov_b32_e32 v57, v0
	v_mov_b32_e32 v58, v0
	v_mov_b32_e32 v59, v0
	v_mov_b32_e32 v60, v0
	v_mov_b32_e32 v61, v0
	v_mov_b32_e32 v62, v0
	v_mov_b32_e32 v63, v0
	v_mov_b32_e32 v64, v0
	v_mov_b32_e32 v65, v0
	v_mov_b32_e32 v66, v0
	v_mov_b32_e32 v67, v0
	v_mov_b32_e32 v68, v0
	v_mov_b32_e32 v69, v0
	v_mov_b32_e32 v70, v0
	v_mov_b32_e32 v71, v0
	v_mov_b32_e32 v72, v0
	v_mov_b32_e32 v73, v0
	v_mov_b32_e32 v74, v0
	v_mov_b32_e32 v75, v0
	v_mov_b32_e32 v80, v0
	v_mov_b32_e32 v81, v0
	v_mov_b32_e32 v82, v0
	v_mov_b32_e32 v83, v0
	v_mov_b32_e32 v88, v0
	v_mov_b32_e32 v89, v0
	v_mov_b32_e32 v90, v0
	v_mov_b32_e32 v91, v0
	v_mov_b32_e32 v100, v0
	v_mov_b32_e32 v101, v0
	v_mov_b32_e32 v102, v0
	v_mov_b32_e32 v103, v0
	v_mov_b32_e32 v108, v0
	v_mov_b32_e32 v109, v0
	v_mov_b32_e32 v110, v0
	v_mov_b32_e32 v111, v0
	v_mov_b32_e32 v116, v0
	v_mov_b32_e32 v117, v0
	v_mov_b32_e32 v118, v0
	v_mov_b32_e32 v119, v0
	v_mov_b32_e32 v76, v0
	v_mov_b32_e32 v77, v0
	v_mov_b32_e32 v78, v0
	v_mov_b32_e32 v79, v0
	v_mov_b32_e32 v84, v0
	v_mov_b32_e32 v85, v0
	v_mov_b32_e32 v86, v0
	v_mov_b32_e32 v87, v0
	v_mov_b32_e32 v92, v0
	v_mov_b32_e32 v93, v0
	v_mov_b32_e32 v94, v0
	v_mov_b32_e32 v95, v0
	v_mov_b32_e32 v104, v0
	v_mov_b32_e32 v105, v0
	v_mov_b32_e32 v106, v0
	v_mov_b32_e32 v107, v0
	v_mov_b32_e32 v112, v0
	v_mov_b32_e32 v113, v0
	v_mov_b32_e32 v114, v0
	v_mov_b32_e32 v115, v0
	v_mov_b32_e32 v120, v0
	v_mov_b32_e32 v121, v0
	v_mov_b32_e32 v122, v0
	v_mov_b32_e32 v123, v0
	v_mov_b32_e32 v124, v0
	v_mov_b32_e32 v125, v0
	v_mov_b32_e32 v126, v0
	v_mov_b32_e32 v127, v0
	v_mov_b32_e32 v128, v0
	v_mov_b32_e32 v129, v0
	v_mov_b32_e32 v130, v0
	v_mov_b32_e32 v131, v0
	v_add_u32_e32 v226, s4, v142
	v_add_u32_e32 v227, s4, v152
	v_add_u32_e32 v228, s4, v140
	v_add_u32_e32 v229, s4, v144
	v_add_u32_e32 v230, s42, v142
	v_add_u32_e32 v231, s42, v152
	v_add_u32_e32 v188, s42, v140
	v_add_u32_e32 v189, s42, v144
	v_add_u32_e32 v232, s42, v226
	v_add_u32_e32 v233, s42, v227
.LBB0_886:
	s_add_i32 s91, s18, 2
	s_add_u32 s8, s2, 0x80
	s_addc_u32 s19, s3, 0
	s_add_i32 s25, 16, 0x10000
	s_cmp_eq_u32 s88, s18
	s_cselect_b32 s19, s15, s19
	s_cselect_b32 s18, s14, s8
	v_add_u32_e32 v96, s25, v147
	s_cselect_b32 s79, s17, vcc_hi
	s_cselect_b32 s78, s16, vcc_lo
	s_add_i32 s8, 16, 0x14000
	ds_read_b128 v[132:135], v96
	ds_read_b128 v[136:139], v96 offset:1024
	ds_read_b128 v[160:163], v96 offset:2048
	ds_read_b128 v[164:167], v96 offset:3072
	v_add_u32_e32 v96, s8, v147
	ds_read_b128 v[168:171], v96
	ds_read_b128 v[172:175], v96 offset:1024
	ds_read_b128 v[176:179], v96 offset:2048
	ds_read_b128 v[180:183], v96 offset:3072
	s_add_i32 m0, s41, 0xc000
	ds_read_b128 v[194:197], v150
	ds_read_b128 v[198:201], v150 offset:1024
	ds_read_b128 v[202:205], v150 offset:2048
	ds_read_b128 v[206:209], v150 offset:3072
	ds_read_b128 v[210:213], v150 offset:4096
	ds_read_b128 v[214:217], v150 offset:5120
	ds_read_b128 v[218:221], v150 offset:6144
	ds_read_b128 v[222:225], v150 offset:7168
	global_load_lds_dwordx4 v156, s[2:3]
	s_add_i32 m0, s41, 0xe000
	s_nop 0
	global_load_lds_dwordx4 v154, s[2:3]
	s_waitcnt vmcnt(8)
	s_waitcnt lgkmcnt(0)
	s_barrier
; #define PG8_STAGE(bufoff, gbase, voff) do { _Pragma("unroll") for (int _i = 0; _i < 2; ++_i) \
;         __builtin_amdgcn_global_load_lds((const unsigned*)((const char*)(gbase) + (voff)[_i]), (PG8_LAS unsigned*)(lds + (bufoff) + ldsw + _i * 8192), 16, 0, 0); } while (0)
; #define PG8_LDA(dst, b, h) do { _Pragma("unroll") for (int m = 0; m < 4; ++m) _Pragma("unroll") for (int k = 0; k < 2; ++k) dst[m][k] = *(const PG8_LAS bf16x8*)(lds + PG8_SA(b, h) + aoff + m * 2048 + k * 1024); } while (0)
; #define PG8_MMA(ai, bj, At, Bt) do { __builtin_amdgcn_s_setprio(1); _Pragma("unroll") for (int m = 0; m < 4; ++m) _Pragma("unroll") for (int n = 0; n < 2; ++n) _Pragma("unroll") for (int k = 0; k < 2; ++k) \
;         acc[ai][bj][m][n] = __builtin_amdgcn_mfma_f32_16x16x32_bf16(Bt[n][k], At[m][k], acc[ai][bj][m][n], 0, 0, 0); __builtin_amdgcn_s_setprio(0); } while (0)
; #define PG8_WAIT_V(n) asm volatile("s_waitcnt vmcnt(" #n ")" ::: "memory")
; #define PG8_WAIT_L(n) asm volatile("s_waitcnt lgkmcnt(" #n ")" ::: "memory")
; #define PG8_BAR __builtin_amdgcn_s_barrier()
; #define PG8_SCHED __builtin_amdgcn_sched_barrier(0)
; template <class Epi, class Sched, bool ALIGN_EPI = false, bool SP2 = false>
; __device__ __forceinline__ void gemm_phase(PG8_LAS unsigned char* lds, const Gemm g, const Sched& S, const Epi& E, int wid_s_) {
;     ...
;             PG8_WAIT_V(8); PG8_WAIT_L(0); PG8_BAR; PG8_MMA(0, 0, At, B0); PG8_MMA(0, 1, At, B1); PG8_BAR; PG8_SCHED;
;             PG8_LDA(At, 0, 1); PG8_STAGE(PG8_SB(0, 0), b2, voffB); PG8_STAGE(PG8_SB(0, 1), b2 + hstep, voffB); PG8_STAGE(PG8_SA(0, 0), a2, voffA);
;             PG8_WAIT_V(8); PG8_WAIT_L(0); PG8_BAR; PG8_MMA(1, 0, At, B0); PG8_MMA(1, 1, At, B1); PG8_BAR; PG8_SCHED;
	s_setprio 1
	s_waitcnt lgkmcnt(0)
	v_mfma_f32_16x16x32_bf16 v[128:131], v[132:135], v[194:197], v[128:131]
	v_mfma_f32_16x16x32_bf16 v[124:127], v[160:163], v[194:197], v[124:127]
	v_mfma_f32_16x16x32_bf16 v[120:123], v[132:135], v[202:205], v[120:123]
	v_mfma_f32_16x16x32_bf16 v[112:115], v[160:163], v[202:205], v[112:115]
	v_mfma_f32_16x16x32_bf16 v[104:107], v[132:135], v[210:213], v[104:107]
	v_mfma_f32_16x16x32_bf16 v[92:95], v[160:163], v[210:213], v[92:95]
	v_mfma_f32_16x16x32_bf16 v[84:87], v[132:135], v[218:221], v[84:87]
	v_mfma_f32_16x16x32_bf16 v[76:79], v[160:163], v[218:221], v[76:79]
	v_mfma_f32_16x16x32_bf16 v[128:131], v[136:139], v[198:201], v[128:131]
	v_mfma_f32_16x16x32_bf16 v[124:127], v[164:167], v[198:201], v[124:127]
	v_mfma_f32_16x16x32_bf16 v[120:123], v[136:139], v[206:209], v[120:123]
	v_mfma_f32_16x16x32_bf16 v[112:115], v[164:167], v[206:209], v[112:115]
	v_mfma_f32_16x16x32_bf16 v[104:107], v[136:139], v[214:217], v[104:107]
	v_mfma_f32_16x16x32_bf16 v[92:95], v[164:167], v[214:217], v[92:95]
	v_mfma_f32_16x16x32_bf16 v[84:87], v[136:139], v[222:225], v[84:87]
	v_mfma_f32_16x16x32_bf16 v[76:79], v[164:167], v[222:225], v[76:79]
	s_setprio 0
	s_setprio 1
	v_mfma_f32_16x16x32_bf16 v[116:119], v[168:171], v[194:197], v[116:119]
	v_mfma_f32_16x16x32_bf16 v[108:111], v[176:179], v[194:197], v[108:111]
	v_mfma_f32_16x16x32_bf16 v[98:101], v[168:171], v[202:205], v[100:103]
	v_mfma_f32_16x16x32_bf16 v[88:91], v[176:179], v[202:205], v[88:91]
	v_mfma_f32_16x16x32_bf16 v[80:83], v[168:171], v[210:213], v[80:83]
	v_mfma_f32_16x16x32_bf16 v[72:75], v[176:179], v[210:213], v[72:75]
	v_mfma_f32_16x16x32_bf16 v[68:71], v[168:171], v[218:221], v[68:71]
	v_mfma_f32_16x16x32_bf16 v[64:67], v[176:179], v[218:221], v[64:67]
	v_mfma_f32_16x16x32_bf16 v[116:119], v[172:175], v[198:201], v[116:119]
	v_mfma_f32_16x16x32_bf16 v[108:111], v[180:183], v[198:201], v[108:111]
	v_mfma_f32_16x16x32_bf16 v[98:101], v[172:175], v[206:209], v[98:101]
	v_mfma_f32_16x16x32_bf16 v[88:91], v[180:183], v[206:209], v[88:91]
	v_mfma_f32_16x16x32_bf16 v[80:83], v[172:175], v[214:217], v[80:83]
	v_mfma_f32_16x16x32_bf16 v[72:75], v[180:183], v[214:217], v[72:75]
	v_mfma_f32_16x16x32_bf16 v[68:71], v[172:175], v[222:225], v[68:71]
	v_mfma_f32_16x16x32_bf16 v[64:67], v[180:183], v[222:225], v[64:67]
	s_setprio 0
	s_barrier
	s_add_i32 s25, s25, s40
	s_mov_b32 m0, s25
	ds_read_b128 v[194:197], v150 offset:16384
	ds_read_b128 v[198:201], v150 offset:17408
	ds_read_b128 v[202:205], v150 offset:18432
	ds_read_b128 v[206:209], v150 offset:19456
	ds_read_b128 v[210:213], v150 offset:20480
	ds_read_b128 v[214:217], v150 offset:21504
	ds_read_b128 v[218:221], v150 offset:22528
	ds_read_b128 v[222:225], v150 offset:23552
	global_load_lds_dwordx4 v142, s[78:79]
	s_add_i32 m0, s25, 0x2000
	s_add_i32 s8, s8, s40
	global_load_lds_dwordx4 v152, s[78:79]
	s_mov_b32 m0, s8
	s_nop 0
	global_load_lds_dwordx4 v226, s[78:79]
	s_add_i32 m0, s8, 0x2000
	s_nop 0
	global_load_lds_dwordx4 v227, s[78:79]
	s_mov_b32 m0, s41
	s_nop 0
	global_load_lds_dwordx4 v140, s[18:19]
	s_mov_b32 m0, s48
	s_nop 0
	global_load_lds_dwordx4 v144, s[18:19]
	s_waitcnt vmcnt(8)
	s_waitcnt lgkmcnt(0)
	s_barrier
	s_setprio 1
	s_waitcnt lgkmcnt(0)
	v_mfma_f32_16x16x32_bf16 v[60:63], v[132:135], v[194:197], v[60:63]
	v_mfma_f32_16x16x32_bf16 v[56:59], v[160:163], v[194:197], v[56:59]
	v_mfma_f32_16x16x32_bf16 v[52:55], v[132:135], v[202:205], v[52:55]
	v_mfma_f32_16x16x32_bf16 v[48:51], v[160:163], v[202:205], v[48:51]
	v_mfma_f32_16x16x32_bf16 v[36:39], v[132:135], v[210:213], v[36:39]
	v_mfma_f32_16x16x32_bf16 v[32:35], v[160:163], v[210:213], v[32:35]
	v_mfma_f32_16x16x32_bf16 v[20:23], v[132:135], v[218:221], v[20:23]
	v_mfma_f32_16x16x32_bf16 v[16:19], v[160:163], v[218:221], v[16:19]
	v_mfma_f32_16x16x32_bf16 v[60:63], v[136:139], v[198:201], v[60:63]
	v_mfma_f32_16x16x32_bf16 v[56:59], v[164:167], v[198:201], v[56:59]
	v_mfma_f32_16x16x32_bf16 v[52:55], v[136:139], v[206:209], v[52:55]
	v_mfma_f32_16x16x32_bf16 v[48:51], v[164:167], v[206:209], v[48:51]
	v_mfma_f32_16x16x32_bf16 v[36:39], v[136:139], v[214:217], v[36:39]
	v_mfma_f32_16x16x32_bf16 v[32:35], v[164:167], v[214:217], v[32:35]
	v_mfma_f32_16x16x32_bf16 v[20:23], v[136:139], v[222:225], v[20:23]
	v_mfma_f32_16x16x32_bf16 v[16:19], v[164:167], v[222:225], v[16:19]
	s_setprio 0
	s_setprio 1
	v_mfma_f32_16x16x32_bf16 v[44:47], v[168:171], v[194:197], v[44:47]
	v_mfma_f32_16x16x32_bf16 v[40:43], v[176:179], v[194:197], v[40:43]
	v_mfma_f32_16x16x32_bf16 v[28:31], v[168:171], v[202:205], v[28:31]
	v_mfma_f32_16x16x32_bf16 v[24:27], v[176:179], v[202:205], v[24:27]
	v_mfma_f32_16x16x32_bf16 v[12:15], v[168:171], v[210:213], v[12:15]
	v_mfma_f32_16x16x32_bf16 v[8:11], v[176:179], v[210:213], v[8:11]
	v_mfma_f32_16x16x32_bf16 v[4:7], v[168:171], v[218:221], v[4:7]
	v_mfma_f32_16x16x32_bf16 v[0:3], v[176:179], v[218:221], v[0:3]
	v_mfma_f32_16x16x32_bf16 v[44:47], v[172:175], v[198:201], v[44:47]
	v_mfma_f32_16x16x32_bf16 v[40:43], v[180:183], v[198:201], v[40:43]
	v_mfma_f32_16x16x32_bf16 v[28:31], v[172:175], v[206:209], v[28:31]
	v_mfma_f32_16x16x32_bf16 v[24:27], v[180:183], v[206:209], v[24:27]
	v_mfma_f32_16x16x32_bf16 v[12:15], v[172:175], v[214:217], v[12:15]
	v_mfma_f32_16x16x32_bf16 v[8:11], v[180:183], v[214:217], v[8:11]
	v_mfma_f32_16x16x32_bf16 v[4:7], v[172:175], v[222:225], v[4:7]
	v_mfma_f32_16x16x32_bf16 v[0:3], v[180:183], v[222:225], v[0:3]
	s_setprio 0
	s_barrier
; #define PG8_STAGE(bufoff, gbase, voff) do { _Pragma("unroll") for (int _i = 0; _i < 2; ++_i) \
;         __builtin_amdgcn_global_load_lds((const unsigned*)((const char*)(gbase) + (voff)[_i]), (PG8_LAS unsigned*)(lds + (bufoff) + ldsw + _i * 8192), 16, 0, 0); } while (0)
; #define PG8_LDA(dst, b, h) do { _Pragma("unroll") for (int m = 0; m < 4; ++m) _Pragma("unroll") for (int k = 0; k < 2; ++k) dst[m][k] = *(const PG8_LAS bf16x8*)(lds + PG8_SA(b, h) + aoff + m * 2048 + k * 1024); } while (0)
; #define PG8_LDB(dst, b, h) do { _Pragma("unroll") for (int n = 0; n < 2; ++n) _Pragma("unroll") for (int k = 0; k < 2; ++k) dst[n][k] = *(const PG8_LAS bf16x8*)(lds + PG8_SB(b, h) + boff + n * 2048 + k * 1024); } while (0)
; #define PG8_MMA(ai, bj, At, Bt) do { __builtin_amdgcn_s_setprio(1); _Pragma("unroll") for (int m = 0; m < 4; ++m) _Pragma("unroll") for (int n = 0; n < 2; ++n) _Pragma("unroll") for (int k = 0; k < 2; ++k) \
;         acc[ai][bj][m][n] = __builtin_amdgcn_mfma_f32_16x16x32_bf16(Bt[n][k], At[m][k], acc[ai][bj][m][n], 0, 0, 0); __builtin_amdgcn_s_setprio(0); } while (0)
; #define PG8_WAIT_V(n) asm volatile("s_waitcnt vmcnt(" #n ")" ::: "memory")
; #define PG8_WAIT_L(n) asm volatile("s_waitcnt lgkmcnt(" #n ")" ::: "memory")
; #define PG8_BAR __builtin_amdgcn_s_barrier()
; #define PG8_SCHED __builtin_amdgcn_sched_barrier(0)
; template <class Epi, class Sched, bool ALIGN_EPI = false, bool SP2 = false>
; __device__ __forceinline__ void gemm_phase(PG8_LAS unsigned char* lds, const Gemm g, const Sched& S, const Epi& E, int wid_s_) {
;     ...
;             PG8_LDB(B0, 1, 0); PG8_LDB(B1, 1, 1); PG8_SCHED; PG8_LDA(At, 1, 0); PG8_STAGE(PG8_SA(0, 1), a2 + hstep, voffA);
;             PG8_WAIT_V(8); PG8_WAIT_L(0); PG8_BAR; PG8_MMA(0, 0, At, B0); PG8_MMA(0, 1, At, B1); PG8_BAR; PG8_SCHED;
;             PG8_LDA(At, 1, 1); PG8_STAGE(PG8_SB(1, 0), b3, voffB); PG8_STAGE(PG8_SB(1, 1), b3 + hstep, voffB); PG8_STAGE(PG8_SA(1, 0), a3, voffA);
;             PG8_WAIT_V(8); PG8_WAIT_L(0); PG8_BAR; PG8_MMA(1, 0, At, B0); PG8_MMA(1, 1, At, B1); PG8_BAR; PG8_SCHED;
	s_add_i32 s8, 16, 0x18000
	v_add_u32_e32 v96, s8, v147
	s_add_i32 s25, 16, 0x1c000
	ds_read_b128 v[132:135], v96
	ds_read_b128 v[136:139], v96 offset:1024
	ds_read_b128 v[160:163], v96 offset:2048
	ds_read_b128 v[164:167], v96 offset:3072
	v_add_u32_e32 v96, s25, v147
	ds_read_b128 v[168:171], v96
	ds_read_b128 v[172:175], v96 offset:1024
	ds_read_b128 v[176:179], v96 offset:2048
	ds_read_b128 v[180:183], v96 offset:3072
	s_mov_b32 m0, s49
	ds_read_b128 v[194:197], v150 offset:32768
	ds_read_b128 v[198:201], v150 offset:33792
	ds_read_b128 v[202:205], v150 offset:34816
	ds_read_b128 v[206:209], v150 offset:35840
	ds_read_b128 v[210:213], v150 offset:36864
	ds_read_b128 v[214:217], v150 offset:37888
	ds_read_b128 v[218:221], v150 offset:38912
	ds_read_b128 v[222:225], v150 offset:39936
	global_load_lds_dwordx4 v228, s[18:19]
	s_mov_b32 m0, s50
	s_nop 0
	global_load_lds_dwordx4 v229, s[18:19]
	s_waitcnt vmcnt(8)
	s_waitcnt lgkmcnt(0)
	s_barrier
	s_setprio 1
	s_waitcnt lgkmcnt(0)
	v_mfma_f32_16x16x32_bf16 v[128:131], v[132:135], v[194:197], v[128:131]
	v_mfma_f32_16x16x32_bf16 v[124:127], v[160:163], v[194:197], v[124:127]
	v_mfma_f32_16x16x32_bf16 v[120:123], v[132:135], v[202:205], v[120:123]
	v_mfma_f32_16x16x32_bf16 v[112:115], v[160:163], v[202:205], v[112:115]
	v_mfma_f32_16x16x32_bf16 v[102:105], v[132:135], v[210:213], v[104:107]
	v_mfma_f32_16x16x32_bf16 v[92:95], v[160:163], v[210:213], v[92:95]
	v_mfma_f32_16x16x32_bf16 v[84:87], v[132:135], v[218:221], v[84:87]
	v_mfma_f32_16x16x32_bf16 v[76:79], v[160:163], v[218:221], v[76:79]
	v_mfma_f32_16x16x32_bf16 v[128:131], v[136:139], v[198:201], v[128:131]
	v_mfma_f32_16x16x32_bf16 v[124:127], v[164:167], v[198:201], v[124:127]
	v_mfma_f32_16x16x32_bf16 v[120:123], v[136:139], v[206:209], v[120:123]
	v_mfma_f32_16x16x32_bf16 v[112:115], v[164:167], v[206:209], v[112:115]
	v_mfma_f32_16x16x32_bf16 v[104:107], v[136:139], v[214:217], v[102:105]
	v_mfma_f32_16x16x32_bf16 v[92:95], v[164:167], v[214:217], v[92:95]
	v_mfma_f32_16x16x32_bf16 v[84:87], v[136:139], v[222:225], v[84:87]
	v_mfma_f32_16x16x32_bf16 v[76:79], v[164:167], v[222:225], v[76:79]
	s_setprio 0
	s_setprio 1
	v_mfma_f32_16x16x32_bf16 v[116:119], v[168:171], v[194:197], v[116:119]
	v_mfma_f32_16x16x32_bf16 v[108:111], v[176:179], v[194:197], v[108:111]
	v_mfma_f32_16x16x32_bf16 v[98:101], v[168:171], v[202:205], v[98:101]
	v_mfma_f32_16x16x32_bf16 v[88:91], v[176:179], v[202:205], v[88:91]
	v_mfma_f32_16x16x32_bf16 v[80:83], v[168:171], v[210:213], v[80:83]
	v_mfma_f32_16x16x32_bf16 v[72:75], v[176:179], v[210:213], v[72:75]
	v_mfma_f32_16x16x32_bf16 v[68:71], v[168:171], v[218:221], v[68:71]
	v_mfma_f32_16x16x32_bf16 v[64:67], v[176:179], v[218:221], v[64:67]
	v_mfma_f32_16x16x32_bf16 v[116:119], v[172:175], v[198:201], v[116:119]
	v_mfma_f32_16x16x32_bf16 v[108:111], v[180:183], v[198:201], v[108:111]
	v_mfma_f32_16x16x32_bf16 v[100:103], v[172:175], v[206:209], v[98:101]
	v_mfma_f32_16x16x32_bf16 v[88:91], v[180:183], v[206:209], v[88:91]
	v_mfma_f32_16x16x32_bf16 v[80:83], v[172:175], v[214:217], v[80:83]
	v_mfma_f32_16x16x32_bf16 v[72:75], v[180:183], v[214:217], v[72:75]
	v_mfma_f32_16x16x32_bf16 v[68:71], v[172:175], v[222:225], v[68:71]
	v_mfma_f32_16x16x32_bf16 v[64:67], v[180:183], v[222:225], v[64:67]
	s_setprio 0
	s_barrier
	s_add_i32 s8, s8, s40
	s_mov_b32 m0, s8
	ds_read_b128 v[194:197], v150 offset:49152
	ds_read_b128 v[198:201], v150 offset:50176
	ds_read_b128 v[202:205], v150 offset:51200
	ds_read_b128 v[206:209], v150 offset:52224
	ds_read_b128 v[210:213], v150 offset:53248
	ds_read_b128 v[214:217], v150 offset:54272
	ds_read_b128 v[218:221], v150 offset:55296
	ds_read_b128 v[222:225], v150 offset:56320
	global_load_lds_dwordx4 v230, s[78:79]
	s_add_i32 m0, s8, 0x2000
	s_add_i32 s8, s25, s40
	global_load_lds_dwordx4 v231, s[78:79]
	s_mov_b32 m0, s8
	s_nop 0
	global_load_lds_dwordx4 v232, s[78:79]
	s_add_i32 m0, s8, 0x2000
	s_nop 0
	global_load_lds_dwordx4 v233, s[78:79]
	s_mov_b32 m0, s85
	s_nop 0
	global_load_lds_dwordx4 v188, s[18:19]
	s_mov_b32 m0, s86
	s_nop 0
	global_load_lds_dwordx4 v189, s[18:19]
	s_waitcnt vmcnt(8)
	s_waitcnt lgkmcnt(0)
	s_barrier
	s_setprio 1
	s_waitcnt lgkmcnt(0)
	v_mfma_f32_16x16x32_bf16 v[60:63], v[132:135], v[194:197], v[60:63]
	v_mfma_f32_16x16x32_bf16 v[56:59], v[160:163], v[194:197], v[56:59]
	v_mfma_f32_16x16x32_bf16 v[52:55], v[132:135], v[202:205], v[52:55]
	v_mfma_f32_16x16x32_bf16 v[48:51], v[160:163], v[202:205], v[48:51]
	v_mfma_f32_16x16x32_bf16 v[36:39], v[132:135], v[210:213], v[36:39]
	v_mfma_f32_16x16x32_bf16 v[32:35], v[160:163], v[210:213], v[32:35]
	v_mfma_f32_16x16x32_bf16 v[20:23], v[132:135], v[218:221], v[20:23]
	v_mfma_f32_16x16x32_bf16 v[16:19], v[160:163], v[218:221], v[16:19]
	v_mfma_f32_16x16x32_bf16 v[60:63], v[136:139], v[198:201], v[60:63]
	v_mfma_f32_16x16x32_bf16 v[56:59], v[164:167], v[198:201], v[56:59]
	v_mfma_f32_16x16x32_bf16 v[52:55], v[136:139], v[206:209], v[52:55]
	v_mfma_f32_16x16x32_bf16 v[48:51], v[164:167], v[206:209], v[48:51]
	v_mfma_f32_16x16x32_bf16 v[36:39], v[136:139], v[214:217], v[36:39]
	v_mfma_f32_16x16x32_bf16 v[32:35], v[164:167], v[214:217], v[32:35]
	v_mfma_f32_16x16x32_bf16 v[20:23], v[136:139], v[222:225], v[20:23]
	v_mfma_f32_16x16x32_bf16 v[16:19], v[164:167], v[222:225], v[16:19]
	s_setprio 0
	s_setprio 1
	v_mfma_f32_16x16x32_bf16 v[44:47], v[168:171], v[194:197], v[44:47]
	v_mfma_f32_16x16x32_bf16 v[40:43], v[176:179], v[194:197], v[40:43]
	v_mfma_f32_16x16x32_bf16 v[28:31], v[168:171], v[202:205], v[28:31]
	v_mfma_f32_16x16x32_bf16 v[24:27], v[176:179], v[202:205], v[24:27]
	v_mfma_f32_16x16x32_bf16 v[12:15], v[168:171], v[210:213], v[12:15]
	v_mfma_f32_16x16x32_bf16 v[8:11], v[176:179], v[210:213], v[8:11]
	v_mfma_f32_16x16x32_bf16 v[4:7], v[168:171], v[218:221], v[4:7]
	v_mfma_f32_16x16x32_bf16 v[0:3], v[176:179], v[218:221], v[0:3]
	v_mfma_f32_16x16x32_bf16 v[44:47], v[172:175], v[198:201], v[44:47]
	v_mfma_f32_16x16x32_bf16 v[40:43], v[180:183], v[198:201], v[40:43]
	v_mfma_f32_16x16x32_bf16 v[28:31], v[172:175], v[206:209], v[28:31]
	v_mfma_f32_16x16x32_bf16 v[24:27], v[180:183], v[206:209], v[24:27]
	v_mfma_f32_16x16x32_bf16 v[12:15], v[172:175], v[214:217], v[12:15]
	v_mfma_f32_16x16x32_bf16 v[8:11], v[180:183], v[214:217], v[8:11]
	v_mfma_f32_16x16x32_bf16 v[4:7], v[172:175], v[222:225], v[4:7]
	v_mfma_f32_16x16x32_bf16 v[0:3], v[180:183], v[222:225], v[0:3]
	s_setprio 0
	s_barrier
	s_add_u32 vcc_lo, vcc_lo, 0x100
	s_addc_u32 vcc_hi, vcc_hi, 0
	s_add_u32 s2, s2, 0x100
	s_addc_u32 s3, s3, 0
	s_cmp_ge_i32 s91, s87
	s_mov_b32 s18, s91
	s_cbranch_scc0 .LBB0_886
	v_readlane_b32 s78, v255, 54
	v_readlane_b32 s79, v255, 55
	s_and_b64 vcc, exec, s[12:13]
	s_cbranch_vccnz .LBB0_891
	s_branch .LBB0_892

; template <class Epi, class Sched, bool ALIGN_EPI = false, bool SP2 = false>
; __device__ __forceinline__ void gemm_phase(PG8_LAS unsigned char* lds, const Gemm g, const Sched& S, const Epi& E, int wid_s_) {
;     ...
;     for (int i = 0; i < 2; ++i) { int R, C; stage_rc(tid * 16 + i * 8192, R, C); const int Rb = Epi::PERM ? ((R & ~31) + perm32(R & 31)) : R;
;         voffA[i] = (unsigned)(R * K + C) * 2u; voffB[i] = (unsigned)(Rb * K + C) * 2u; }
;     const size_t kstep = (size_t)(BK * 2);
;     const size_t hstep = (size_t)HALF * K * 2;
;     const size_t tstep = 2 * hstep;
;     ...
;     f32x4 acc[2][2][4][2];
; #pragma unroll
;     for (int a = 0; a < 2; ++a)
; #pragma unroll
;         for (int b = 0; b < 2; ++b)
; #pragma unroll
;             for (int m = 0; m < 4; ++m)
; #pragma unroll
;                 for (int n = 0; n < 2; ++n) acc[a][b][m][n] = (f32x4){0.f, 0.f, 0.f, 0.f};
.LBB0_1274:
	v_mov_b32_e32 v125, 0
	s_andn2_b64 vcc, exec, s[12:13]
	v_mov_b32_e32 v124, v125
	v_mov_b32_e32 v123, v125
	v_mov_b32_e32 v122, v125
	v_mov_b32_e32 v129, v125
	v_mov_b32_e32 v128, v125
	v_mov_b32_e32 v127, v125
	v_mov_b32_e32 v126, v125
	v_mov_b32_e32 v121, v125
	v_mov_b32_e32 v120, v125
	v_mov_b32_e32 v119, v125
	v_mov_b32_e32 v118, v125
	v_mov_b32_e32 v117, v125
	v_mov_b32_e32 v116, v125
	v_mov_b32_e32 v115, v125
	v_mov_b32_e32 v114, v125
	v_mov_b32_e32 v113, v125
	v_mov_b32_e32 v112, v125
	v_mov_b32_e32 v111, v125
	v_mov_b32_e32 v110, v125
	v_mov_b32_e32 v109, v125
	v_mov_b32_e32 v108, v125
	v_mov_b32_e32 v107, v125
	v_mov_b32_e32 v106, v125
	v_mov_b32_e32 v105, v125
	v_mov_b32_e32 v104, v125
	v_mov_b32_e32 v103, v125
	v_mov_b32_e32 v102, v125
	v_mov_b32_e32 v101, v125
	v_mov_b32_e32 v100, v125
	v_mov_b32_e32 v99, v125
	v_mov_b32_e32 v98, v125
	v_mov_b32_e32 v63, v125
	v_mov_b32_e32 v62, v125
	v_mov_b32_e32 v61, v125
	v_mov_b32_e32 v60, v125
	v_mov_b32_e32 v59, v125
	v_mov_b32_e32 v58, v125
	v_mov_b32_e32 v57, v125
	v_mov_b32_e32 v56, v125
	v_mov_b32_e32 v55, v125
	v_mov_b32_e32 v54, v125
	v_mov_b32_e32 v53, v125
	v_mov_b32_e32 v52, v125
	v_mov_b32_e32 v51, v125
	v_mov_b32_e32 v50, v125
	v_mov_b32_e32 v49, v125
	v_mov_b32_e32 v48, v125
	v_mov_b32_e32 v47, v125
	v_mov_b32_e32 v46, v125
	v_mov_b32_e32 v45, v125
	v_mov_b32_e32 v44, v125
	v_mov_b32_e32 v43, v125
	v_mov_b32_e32 v42, v125
	v_mov_b32_e32 v41, v125
	v_mov_b32_e32 v40, v125
	v_mov_b32_e32 v39, v125
	v_mov_b32_e32 v38, v125
	v_mov_b32_e32 v37, v125
	v_mov_b32_e32 v36, v125
	v_mov_b32_e32 v35, v125
	v_mov_b32_e32 v34, v125
	v_mov_b32_e32 v33, v125
	v_mov_b32_e32 v32, v125
	v_mov_b32_e32 v95, v125
	v_mov_b32_e32 v94, v125
	v_mov_b32_e32 v93, v125
	v_mov_b32_e32 v92, v125
	v_mov_b32_e32 v91, v125
	v_mov_b32_e32 v90, v125
	v_mov_b32_e32 v89, v125
	v_mov_b32_e32 v88, v125
	v_mov_b32_e32 v87, v125
	v_mov_b32_e32 v86, v125
	v_mov_b32_e32 v85, v125
	v_mov_b32_e32 v84, v125
	v_mov_b32_e32 v83, v125
	v_mov_b32_e32 v82, v125
	v_mov_b32_e32 v81, v125
	v_mov_b32_e32 v80, v125
	v_mov_b32_e32 v79, v125
	v_mov_b32_e32 v78, v125
	v_mov_b32_e32 v77, v125
	v_mov_b32_e32 v76, v125
	v_mov_b32_e32 v75, v125
	v_mov_b32_e32 v74, v125
	v_mov_b32_e32 v73, v125
	v_mov_b32_e32 v72, v125
	v_mov_b32_e32 v71, v125
	v_mov_b32_e32 v70, v125
	v_mov_b32_e32 v69, v125
	v_mov_b32_e32 v68, v125
	v_mov_b32_e32 v67, v125
	v_mov_b32_e32 v66, v125
	v_mov_b32_e32 v65, v125
	v_mov_b32_e32 v64, v125
	v_mov_b32_e32 v31, v125
	v_mov_b32_e32 v30, v125
	v_mov_b32_e32 v29, v125
	v_mov_b32_e32 v28, v125
	v_mov_b32_e32 v27, v125
	v_mov_b32_e32 v26, v125
	v_mov_b32_e32 v25, v125
	v_mov_b32_e32 v24, v125
	v_mov_b32_e32 v23, v125
	v_mov_b32_e32 v22, v125
	v_mov_b32_e32 v21, v125
	v_mov_b32_e32 v20, v125
	v_mov_b32_e32 v19, v125
	v_mov_b32_e32 v18, v125
	v_mov_b32_e32 v17, v125
	v_mov_b32_e32 v16, v125
	v_mov_b32_e32 v15, v125
	v_mov_b32_e32 v14, v125
	v_mov_b32_e32 v13, v125
	v_mov_b32_e32 v12, v125
	v_mov_b32_e32 v11, v125
	v_mov_b32_e32 v10, v125
	v_mov_b32_e32 v9, v125
	v_mov_b32_e32 v8, v125
	v_mov_b32_e32 v7, v125
	v_mov_b32_e32 v6, v125
	v_mov_b32_e32 v5, v125
	v_mov_b32_e32 v4, v125
	v_mov_b32_e32 v3, v125
	v_mov_b32_e32 v2, v125
	v_mov_b32_e32 v1, v125
	v_mov_b32_e32 v0, v125
	s_cbranch_vccnz .LBB0_1278
	s_add_u32 vcc_lo, s20, 0x100
	s_addc_u32 vcc_hi, s21, 0
	s_add_u32 s20, s22, 0x80
	v_mov_b32_e32 v0, 0
	s_addc_u32 s21, s23, 0
	s_mov_b32 s22, 0
	v_mov_b32_e32 v1, v0
	v_mov_b32_e32 v2, v0
	v_mov_b32_e32 v3, v0
	v_mov_b32_e32 v4, v0
	v_mov_b32_e32 v5, v0
	v_mov_b32_e32 v6, v0
	v_mov_b32_e32 v7, v0
	v_mov_b32_e32 v8, v0
	v_mov_b32_e32 v9, v0
	v_mov_b32_e32 v10, v0
	v_mov_b32_e32 v11, v0
	v_mov_b32_e32 v12, v0
	v_mov_b32_e32 v13, v0
	v_mov_b32_e32 v14, v0
	v_mov_b32_e32 v15, v0
	v_mov_b32_e32 v16, v0
	v_mov_b32_e32 v17, v0
	v_mov_b32_e32 v18, v0
	v_mov_b32_e32 v19, v0
	v_mov_b32_e32 v20, v0
	v_mov_b32_e32 v21, v0
	v_mov_b32_e32 v22, v0
	v_mov_b32_e32 v23, v0
	v_mov_b32_e32 v24, v0
	v_mov_b32_e32 v25, v0
	v_mov_b32_e32 v26, v0
	v_mov_b32_e32 v27, v0
	v_mov_b32_e32 v28, v0
	v_mov_b32_e32 v29, v0
	v_mov_b32_e32 v30, v0
	v_mov_b32_e32 v31, v0
	v_mov_b32_e32 v64, v0
	v_mov_b32_e32 v65, v0
	v_mov_b32_e32 v66, v0
	v_mov_b32_e32 v67, v0
	v_mov_b32_e32 v68, v0
	v_mov_b32_e32 v69, v0
	v_mov_b32_e32 v70, v0
	v_mov_b32_e32 v71, v0
	v_mov_b32_e32 v72, v0
	v_mov_b32_e32 v73, v0
	v_mov_b32_e32 v74, v0
	v_mov_b32_e32 v75, v0
	v_mov_b32_e32 v76, v0
	v_mov_b32_e32 v77, v0
	v_mov_b32_e32 v78, v0
	v_mov_b32_e32 v79, v0
	v_mov_b32_e32 v80, v0
	v_mov_b32_e32 v81, v0
	v_mov_b32_e32 v82, v0
	v_mov_b32_e32 v83, v0
	v_mov_b32_e32 v84, v0
	v_mov_b32_e32 v85, v0
	v_mov_b32_e32 v86, v0
	v_mov_b32_e32 v87, v0
	v_mov_b32_e32 v88, v0
	v_mov_b32_e32 v89, v0
	v_mov_b32_e32 v90, v0
	v_mov_b32_e32 v91, v0
	v_mov_b32_e32 v92, v0
	v_mov_b32_e32 v93, v0
	v_mov_b32_e32 v94, v0
	v_mov_b32_e32 v95, v0
	v_mov_b32_e32 v32, v0
	v_mov_b32_e32 v33, v0
	v_mov_b32_e32 v34, v0
	v_mov_b32_e32 v35, v0
	v_mov_b32_e32 v36, v0
	v_mov_b32_e32 v37, v0
	v_mov_b32_e32 v38, v0
	v_mov_b32_e32 v39, v0
	v_mov_b32_e32 v40, v0
	v_mov_b32_e32 v41, v0
	v_mov_b32_e32 v42, v0
	v_mov_b32_e32 v43, v0
	v_mov_b32_e32 v44, v0
	v_mov_b32_e32 v45, v0
	v_mov_b32_e32 v46, v0
	v_mov_b32_e32 v47, v0
	v_mov_b32_e32 v48, v0
	v_mov_b32_e32 v49, v0
	v_mov_b32_e32 v50, v0
	v_mov_b32_e32 v51, v0
	v_mov_b32_e32 v52, v0
	v_mov_b32_e32 v53, v0
	v_mov_b32_e32 v54, v0
	v_mov_b32_e32 v55, v0
	v_mov_b32_e32 v56, v0
	v_mov_b32_e32 v57, v0
	v_mov_b32_e32 v58, v0
	v_mov_b32_e32 v59, v0
	v_mov_b32_e32 v60, v0
	v_mov_b32_e32 v61, v0
	v_mov_b32_e32 v62, v0
	v_mov_b32_e32 v63, v0
	v_mov_b32_e32 v98, v0
	v_mov_b32_e32 v99, v0
	v_mov_b32_e32 v100, v0
	v_mov_b32_e32 v101, v0
	v_mov_b32_e32 v102, v0
	v_mov_b32_e32 v103, v0
	v_mov_b32_e32 v104, v0
	v_mov_b32_e32 v105, v0
	v_mov_b32_e32 v106, v0
	v_mov_b32_e32 v107, v0
	v_mov_b32_e32 v108, v0
	v_mov_b32_e32 v109, v0
	v_mov_b32_e32 v110, v0
	v_mov_b32_e32 v111, v0
	v_mov_b32_e32 v112, v0
	v_mov_b32_e32 v113, v0
	v_mov_b32_e32 v114, v0
	v_mov_b32_e32 v115, v0
	v_mov_b32_e32 v116, v0
	v_mov_b32_e32 v117, v0
	v_mov_b32_e32 v118, v0
	v_mov_b32_e32 v119, v0
	v_mov_b32_e32 v120, v0
	v_mov_b32_e32 v121, v0
	v_mov_b32_e32 v126, v0
	v_mov_b32_e32 v127, v0
	v_mov_b32_e32 v128, v0
	v_mov_b32_e32 v129, v0
	v_mov_b32_e32 v122, v0
	v_mov_b32_e32 v123, v0
	v_mov_b32_e32 v124, v0
	v_mov_b32_e32 v125, v0
	v_add_u32_e32 v151, s2, v96
	v_add_u32_e32 v178, s2, v138
	v_add_u32_e32 v179, s2, v142
	v_add_u32_e32 v188, s2, v140
	v_add_u32_e32 v189, s42, v96
	v_add_u32_e32 v194, s42, v138
	v_add_u32_e32 v225, s42, v142
	v_add_u32_e32 v226, s42, v140
	v_add_u32_e32 v195, s42, v151
	v_add_u32_e32 v224, s42, v178
; #define PG8_STAGE(bufoff, gbase, voff) do { _Pragma("unroll") for (int _i = 0; _i < 2; ++_i) \
;         __builtin_amdgcn_global_load_lds((const unsigned*)((const char*)(gbase) + (voff)[_i]), (PG8_LAS unsigned*)(lds + (bufoff) + ldsw + _i * 8192), 16, 0, 0); } while (0)
; #define PG8_LDA(dst, b, h) do { _Pragma("unroll") for (int m = 0; m < 4; ++m) _Pragma("unroll") for (int k = 0; k < 2; ++k) dst[m][k] = *(const PG8_LAS bf16x8*)(lds + PG8_SA(b, h) + aoff + m * 2048 + k * 1024); } while (0)
; #define PG8_LDB(dst, b, h) do { _Pragma("unroll") for (int n = 0; n < 2; ++n) _Pragma("unroll") for (int k = 0; k < 2; ++k) dst[n][k] = *(const PG8_LAS bf16x8*)(lds + PG8_SB(b, h) + boff + n * 2048 + k * 1024); } while (0)
; #define PG8_MMA(ai, bj, At, Bt) do { __builtin_amdgcn_s_setprio(1); _Pragma("unroll") for (int m = 0; m < 4; ++m) _Pragma("unroll") for (int n = 0; n < 2; ++n) _Pragma("unroll") for (int k = 0; k < 2; ++k) \
;         acc[ai][bj][m][n] = __builtin_amdgcn_mfma_f32_16x16x32_bf16(Bt[n][k], At[m][k], acc[ai][bj][m][n], 0, 0, 0); __builtin_amdgcn_s_setprio(0); } while (0)
; #define PG8_WAIT_V(n) asm volatile("s_waitcnt vmcnt(" #n ")" ::: "memory")
; #define PG8_BAR __builtin_amdgcn_s_barrier()
; template <class Epi, class Sched, bool ALIGN_EPI = false, bool SP2 = false>
; __device__ __forceinline__ void gemm_phase(PG8_LAS unsigned char* lds, const Gemm g, const Sched& S, const Epi& E, int wid_s_) {
;     ...
;         for (int t = 0; t < nt; t += 2) {
;             const bool last = (t == nt - 2);
;             const char* a1 = cA + (size_t)(t + 1) * kstep;
;             const char* a2 = last ? nA : cA + (size_t)(t + 2) * kstep; const char* b2 = last ? nB : cB + (size_t)(t + 2) * kstep;
;             const char* a3 = a2 + kstep; const char* b3 = b2 + kstep;
;             if (last && has_next) S.a_ready(nxt);
;             if constexpr (SP2) {
;             PG8_LDB(B0, 0, 0); PG8_LDB(B1, 0, 1); PG8_SCHED; PG8_LDA(At, 0, 0); PG8_STAGE(PG8_SA(1, 1), a1 + hstep, voffA);
;             PG8_WAIT_V(8); PG8_WAIT_L(0); PG8_BAR; PG8_MMA(0, 0, At, B0); PG8_MMA(0, 1, At, B1); PG8_BAR; PG8_SCHED;
;             PG8_LDA(At, 0, 1); PG8_STAGE(PG8_SB(0, 0), b2, voffB); PG8_STAGE(PG8_SB(0, 1), b2 + hstep, voffB); PG8_STAGE(PG8_SA(0, 0), a2, voffA);
;             PG8_WAIT_V(8); PG8_WAIT_L(0); PG8_BAR; PG8_MMA(1, 0, At, B0); PG8_MMA(1, 1, At, B1); PG8_BAR; PG8_SCHED;
.LBB0_1276:
	s_add_i32 s84, s22, 2
	s_add_u32 s78, s20, 0x80
	s_addc_u32 s23, s21, 0
	s_add_i32 s85, 16, 0x10000
	s_cmp_eq_u32 s86, s22
	s_cselect_b32 s23, s17, s23
	s_cselect_b32 s22, s16, s78
	v_add_u32_e32 v150, s85, v147
	s_cselect_b32 s79, s19, vcc_hi
	s_cselect_b32 s78, s18, vcc_lo
	s_add_i32 s8, 16, 0x14000
	ds_read_b128 v[130:133], v150
	ds_read_b128 v[134:137], v150 offset:1024
	ds_read_b128 v[154:157], v150 offset:2048
	ds_read_b128 v[158:161], v150 offset:3072
	v_add_u32_e32 v150, s8, v147
	ds_read_b128 v[162:165], v150
	ds_read_b128 v[166:169], v150 offset:1024
	ds_read_b128 v[170:173], v150 offset:2048
	ds_read_b128 v[174:177], v150 offset:3072
	s_add_i32 m0, s40, 0xc000
	ds_read_b128 v[180:183], v149
	ds_read_b128 v[196:199], v149 offset:1024
	ds_read_b128 v[200:203], v149 offset:2048
	ds_read_b128 v[204:207], v149 offset:3072
	ds_read_b128 v[208:211], v149 offset:4096
	ds_read_b128 v[212:215], v149 offset:5120
	ds_read_b128 v[216:219], v149 offset:6144
	ds_read_b128 v[220:223], v149 offset:7168
	global_load_lds_dwordx4 v152, s[20:21]
	s_add_i32 m0, s40, 0xe000
	s_nop 0
	global_load_lds_dwordx4 v144, s[20:21]
	s_waitcnt vmcnt(8)
	s_waitcnt lgkmcnt(0)
	s_barrier
	s_setprio 1
	s_waitcnt lgkmcnt(0)
	v_mfma_f32_16x16x32_bf16 v[122:125], v[130:133], v[180:183], v[122:125]
	v_mfma_f32_16x16x32_bf16 v[126:129], v[154:157], v[180:183], v[126:129]
	v_mfma_f32_16x16x32_bf16 v[118:121], v[130:133], v[200:203], v[118:121]
	v_mfma_f32_16x16x32_bf16 v[114:117], v[154:157], v[200:203], v[114:117]
	v_mfma_f32_16x16x32_bf16 v[110:113], v[130:133], v[208:211], v[110:113]
	v_mfma_f32_16x16x32_bf16 v[106:109], v[154:157], v[208:211], v[106:109]
	v_mfma_f32_16x16x32_bf16 v[102:105], v[130:133], v[216:219], v[102:105]
	v_mfma_f32_16x16x32_bf16 v[98:101], v[154:157], v[216:219], v[98:101]
	v_mfma_f32_16x16x32_bf16 v[122:125], v[134:137], v[196:199], v[122:125]
	v_mfma_f32_16x16x32_bf16 v[126:129], v[158:161], v[196:199], v[126:129]
	v_mfma_f32_16x16x32_bf16 v[118:121], v[134:137], v[204:207], v[118:121]
	v_mfma_f32_16x16x32_bf16 v[114:117], v[158:161], v[204:207], v[114:117]
	v_mfma_f32_16x16x32_bf16 v[110:113], v[134:137], v[212:215], v[110:113]
	v_mfma_f32_16x16x32_bf16 v[106:109], v[158:161], v[212:215], v[106:109]
	v_mfma_f32_16x16x32_bf16 v[102:105], v[134:137], v[220:223], v[102:105]
	v_mfma_f32_16x16x32_bf16 v[98:101], v[158:161], v[220:223], v[98:101]
	s_setprio 0
	s_setprio 1
	v_mfma_f32_16x16x32_bf16 v[60:63], v[162:165], v[180:183], v[60:63]
	v_mfma_f32_16x16x32_bf16 v[56:59], v[170:173], v[180:183], v[56:59]
	v_mfma_f32_16x16x32_bf16 v[52:55], v[162:165], v[200:203], v[52:55]
	v_mfma_f32_16x16x32_bf16 v[48:51], v[170:173], v[200:203], v[48:51]
	v_mfma_f32_16x16x32_bf16 v[44:47], v[162:165], v[208:211], v[44:47]
	v_mfma_f32_16x16x32_bf16 v[40:43], v[170:173], v[208:211], v[40:43]
	v_mfma_f32_16x16x32_bf16 v[36:39], v[162:165], v[216:219], v[36:39]
	v_mfma_f32_16x16x32_bf16 v[32:35], v[170:173], v[216:219], v[32:35]
	v_mfma_f32_16x16x32_bf16 v[60:63], v[166:169], v[196:199], v[60:63]
	v_mfma_f32_16x16x32_bf16 v[56:59], v[174:177], v[196:199], v[56:59]
	v_mfma_f32_16x16x32_bf16 v[52:55], v[166:169], v[204:207], v[52:55]
	v_mfma_f32_16x16x32_bf16 v[48:51], v[174:177], v[204:207], v[48:51]
	v_mfma_f32_16x16x32_bf16 v[44:47], v[166:169], v[212:215], v[44:47]
	v_mfma_f32_16x16x32_bf16 v[40:43], v[174:177], v[212:215], v[40:43]
	v_mfma_f32_16x16x32_bf16 v[36:39], v[166:169], v[220:223], v[36:39]
	v_mfma_f32_16x16x32_bf16 v[32:35], v[174:177], v[220:223], v[32:35]
	s_setprio 0
	s_barrier
	s_add_i32 s9, s85, s37
	s_mov_b32 m0, s9
	ds_read_b128 v[180:183], v149 offset:16384
	ds_read_b128 v[196:199], v149 offset:17408
	ds_read_b128 v[200:203], v149 offset:18432
	ds_read_b128 v[204:207], v149 offset:19456
	ds_read_b128 v[208:211], v149 offset:20480
	ds_read_b128 v[212:215], v149 offset:21504
	ds_read_b128 v[216:219], v149 offset:22528
	ds_read_b128 v[220:223], v149 offset:23552
	global_load_lds_dwordx4 v96, s[78:79]
	s_add_i32 m0, s9, 0x2000
	s_add_i32 s8, s8, s37
	global_load_lds_dwordx4 v138, s[78:79]
	s_mov_b32 m0, s8
	s_nop 0
	global_load_lds_dwordx4 v151, s[78:79]
	s_add_i32 m0, s8, 0x2000
	s_nop 0
	global_load_lds_dwordx4 v178, s[78:79]
	s_mov_b32 m0, s40
	s_nop 0
	global_load_lds_dwordx4 v142, s[22:23]
	s_mov_b32 m0, s41
	s_nop 0
	global_load_lds_dwordx4 v140, s[22:23]
	s_waitcnt vmcnt(8)
	s_waitcnt lgkmcnt(0)
	s_barrier
	s_setprio 1
	s_waitcnt lgkmcnt(0)
	v_mfma_f32_16x16x32_bf16 v[92:95], v[130:133], v[180:183], v[92:95]
	v_mfma_f32_16x16x32_bf16 v[88:91], v[154:157], v[180:183], v[88:91]
	v_mfma_f32_16x16x32_bf16 v[84:87], v[130:133], v[200:203], v[84:87]
	v_mfma_f32_16x16x32_bf16 v[80:83], v[154:157], v[200:203], v[80:83]
	v_mfma_f32_16x16x32_bf16 v[76:79], v[130:133], v[208:211], v[76:79]
	v_mfma_f32_16x16x32_bf16 v[72:75], v[154:157], v[208:211], v[72:75]
	v_mfma_f32_16x16x32_bf16 v[68:71], v[130:133], v[216:219], v[68:71]
	v_mfma_f32_16x16x32_bf16 v[64:67], v[154:157], v[216:219], v[64:67]
	v_mfma_f32_16x16x32_bf16 v[92:95], v[134:137], v[196:199], v[92:95]
	v_mfma_f32_16x16x32_bf16 v[88:91], v[158:161], v[196:199], v[88:91]
	v_mfma_f32_16x16x32_bf16 v[84:87], v[134:137], v[204:207], v[84:87]
	v_mfma_f32_16x16x32_bf16 v[80:83], v[158:161], v[204:207], v[80:83]
	v_mfma_f32_16x16x32_bf16 v[76:79], v[134:137], v[212:215], v[76:79]
	v_mfma_f32_16x16x32_bf16 v[72:75], v[158:161], v[212:215], v[72:75]
	v_mfma_f32_16x16x32_bf16 v[68:71], v[134:137], v[220:223], v[68:71]
	v_mfma_f32_16x16x32_bf16 v[64:67], v[158:161], v[220:223], v[64:67]
	s_setprio 0
	s_setprio 1
	v_mfma_f32_16x16x32_bf16 v[28:31], v[162:165], v[180:183], v[28:31]
	v_mfma_f32_16x16x32_bf16 v[24:27], v[170:173], v[180:183], v[24:27]
	v_mfma_f32_16x16x32_bf16 v[20:23], v[162:165], v[200:203], v[20:23]
	v_mfma_f32_16x16x32_bf16 v[16:19], v[170:173], v[200:203], v[16:19]
	v_mfma_f32_16x16x32_bf16 v[12:15], v[162:165], v[208:211], v[12:15]
	v_mfma_f32_16x16x32_bf16 v[8:11], v[170:173], v[208:211], v[8:11]
	v_mfma_f32_16x16x32_bf16 v[4:7], v[162:165], v[216:219], v[4:7]
	v_mfma_f32_16x16x32_bf16 v[0:3], v[170:173], v[216:219], v[0:3]
	v_mfma_f32_16x16x32_bf16 v[28:31], v[166:169], v[196:199], v[28:31]
	v_mfma_f32_16x16x32_bf16 v[24:27], v[174:177], v[196:199], v[24:27]
	v_mfma_f32_16x16x32_bf16 v[20:23], v[166:169], v[204:207], v[20:23]
	v_mfma_f32_16x16x32_bf16 v[16:19], v[174:177], v[204:207], v[16:19]
	v_mfma_f32_16x16x32_bf16 v[12:15], v[166:169], v[212:215], v[12:15]
	v_mfma_f32_16x16x32_bf16 v[8:11], v[174:177], v[212:215], v[8:11]
	v_mfma_f32_16x16x32_bf16 v[4:7], v[166:169], v[220:223], v[4:7]
	v_mfma_f32_16x16x32_bf16 v[0:3], v[174:177], v[220:223], v[0:3]
	s_setprio 0
	s_barrier
; #define PG8_STAGE(bufoff, gbase, voff) do { _Pragma("unroll") for (int _i = 0; _i < 2; ++_i) \
;         __builtin_amdgcn_global_load_lds((const unsigned*)((const char*)(gbase) + (voff)[_i]), (PG8_LAS unsigned*)(lds + (bufoff) + ldsw + _i * 8192), 16, 0, 0); } while (0)
; #define PG8_LDA(dst, b, h) do { _Pragma("unroll") for (int m = 0; m < 4; ++m) _Pragma("unroll") for (int k = 0; k < 2; ++k) dst[m][k] = *(const PG8_LAS bf16x8*)(lds + PG8_SA(b, h) + aoff + m * 2048 + k * 1024); } while (0)
; #define PG8_LDB(dst, b, h) do { _Pragma("unroll") for (int n = 0; n < 2; ++n) _Pragma("unroll") for (int k = 0; k < 2; ++k) dst[n][k] = *(const PG8_LAS bf16x8*)(lds + PG8_SB(b, h) + boff + n * 2048 + k * 1024); } while (0)
; #define PG8_MMA(ai, bj, At, Bt) do { __builtin_amdgcn_s_setprio(1); _Pragma("unroll") for (int m = 0; m < 4; ++m) _Pragma("unroll") for (int n = 0; n < 2; ++n) _Pragma("unroll") for (int k = 0; k < 2; ++k) \
;         acc[ai][bj][m][n] = __builtin_amdgcn_mfma_f32_16x16x32_bf16(Bt[n][k], At[m][k], acc[ai][bj][m][n], 0, 0, 0); __builtin_amdgcn_s_setprio(0); } while (0)
; #define PG8_WAIT_V(n) asm volatile("s_waitcnt vmcnt(" #n ")" ::: "memory")
; #define PG8_WAIT_L(n) asm volatile("s_waitcnt lgkmcnt(" #n ")" ::: "memory")
; #define PG8_BAR __builtin_amdgcn_s_barrier()
; #define PG8_SCHED __builtin_amdgcn_sched_barrier(0)
; template <class Epi, class Sched, bool ALIGN_EPI = false, bool SP2 = false>
; __device__ __forceinline__ void gemm_phase(PG8_LAS unsigned char* lds, const Gemm g, const Sched& S, const Epi& E, int wid_s_) {
;     ...
;             PG8_LDB(B0, 1, 0); PG8_LDB(B1, 1, 1); PG8_SCHED; PG8_LDA(At, 1, 0); PG8_STAGE(PG8_SA(0, 1), a2 + hstep, voffA);
;             PG8_WAIT_V(8); PG8_WAIT_L(0); PG8_BAR; PG8_MMA(0, 0, At, B0); PG8_MMA(0, 1, At, B1); PG8_BAR; PG8_SCHED;
;             PG8_LDA(At, 1, 1); PG8_STAGE(PG8_SB(1, 0), b3, voffB); PG8_STAGE(PG8_SB(1, 1), b3 + hstep, voffB); PG8_STAGE(PG8_SA(1, 0), a3, voffA);
;             PG8_WAIT_V(8); PG8_WAIT_L(0); PG8_BAR; PG8_MMA(1, 0, At, B0); PG8_MMA(1, 1, At, B1); PG8_BAR; PG8_SCHED;
	s_add_i32 s8, 16, 0x18000
	s_add_i32 s9, 16, 0x1c000
	v_add_u32_e32 v158, s8, v147
	v_add_u32_e32 v174, s9, v147
	ds_read_b128 v[130:133], v158
	ds_read_b128 v[134:137], v158 offset:1024
	ds_read_b128 v[154:157], v158 offset:2048
	ds_read_b128 v[158:161], v158 offset:3072
	ds_read_b128 v[162:165], v174
	ds_read_b128 v[166:169], v174 offset:1024
	ds_read_b128 v[170:173], v174 offset:2048
	ds_read_b128 v[174:177], v174 offset:3072
	s_mov_b32 m0, s48
	ds_read_b128 v[180:183], v149 offset:32768
	ds_read_b128 v[196:199], v149 offset:33792
	ds_read_b128 v[200:203], v149 offset:34816
	ds_read_b128 v[204:207], v149 offset:35840
	ds_read_b128 v[208:211], v149 offset:36864
	ds_read_b128 v[212:215], v149 offset:37888
	ds_read_b128 v[216:219], v149 offset:38912
	ds_read_b128 v[220:223], v149 offset:39936
	global_load_lds_dwordx4 v179, s[22:23]
	s_mov_b32 m0, s49
	s_nop 0
	global_load_lds_dwordx4 v188, s[22:23]
	s_waitcnt vmcnt(8)
	s_waitcnt lgkmcnt(0)
	s_barrier
	s_setprio 1
	s_waitcnt lgkmcnt(0)
	v_mfma_f32_16x16x32_bf16 v[122:125], v[130:133], v[180:183], v[122:125]
	v_mfma_f32_16x16x32_bf16 v[126:129], v[154:157], v[180:183], v[126:129]
	v_mfma_f32_16x16x32_bf16 v[118:121], v[130:133], v[200:203], v[118:121]
	v_mfma_f32_16x16x32_bf16 v[114:117], v[154:157], v[200:203], v[114:117]
	v_mfma_f32_16x16x32_bf16 v[110:113], v[130:133], v[208:211], v[110:113]
	v_mfma_f32_16x16x32_bf16 v[106:109], v[154:157], v[208:211], v[106:109]
	v_mfma_f32_16x16x32_bf16 v[102:105], v[130:133], v[216:219], v[102:105]
	v_mfma_f32_16x16x32_bf16 v[98:101], v[154:157], v[216:219], v[98:101]
	v_mfma_f32_16x16x32_bf16 v[122:125], v[134:137], v[196:199], v[122:125]
	v_mfma_f32_16x16x32_bf16 v[126:129], v[158:161], v[196:199], v[126:129]
	v_mfma_f32_16x16x32_bf16 v[118:121], v[134:137], v[204:207], v[118:121]
	v_mfma_f32_16x16x32_bf16 v[114:117], v[158:161], v[204:207], v[114:117]
	v_mfma_f32_16x16x32_bf16 v[110:113], v[134:137], v[212:215], v[110:113]
	v_mfma_f32_16x16x32_bf16 v[106:109], v[158:161], v[212:215], v[106:109]
	v_mfma_f32_16x16x32_bf16 v[102:105], v[134:137], v[220:223], v[102:105]
	v_mfma_f32_16x16x32_bf16 v[98:101], v[158:161], v[220:223], v[98:101]
	s_setprio 0
	s_setprio 1
	v_mfma_f32_16x16x32_bf16 v[60:63], v[162:165], v[180:183], v[60:63]
	v_mfma_f32_16x16x32_bf16 v[56:59], v[170:173], v[180:183], v[56:59]
	v_mfma_f32_16x16x32_bf16 v[52:55], v[162:165], v[200:203], v[52:55]
	v_mfma_f32_16x16x32_bf16 v[48:51], v[170:173], v[200:203], v[48:51]
	v_mfma_f32_16x16x32_bf16 v[44:47], v[162:165], v[208:211], v[44:47]
	v_mfma_f32_16x16x32_bf16 v[40:43], v[170:173], v[208:211], v[40:43]
	v_mfma_f32_16x16x32_bf16 v[36:39], v[162:165], v[216:219], v[36:39]
	v_mfma_f32_16x16x32_bf16 v[32:35], v[170:173], v[216:219], v[32:35]
	v_mfma_f32_16x16x32_bf16 v[60:63], v[166:169], v[196:199], v[60:63]
	v_mfma_f32_16x16x32_bf16 v[56:59], v[174:177], v[196:199], v[56:59]
	v_mfma_f32_16x16x32_bf16 v[52:55], v[166:169], v[204:207], v[52:55]
	v_mfma_f32_16x16x32_bf16 v[48:51], v[174:177], v[204:207], v[48:51]
	v_mfma_f32_16x16x32_bf16 v[44:47], v[166:169], v[212:215], v[44:47]
	v_mfma_f32_16x16x32_bf16 v[40:43], v[174:177], v[212:215], v[40:43]
	v_mfma_f32_16x16x32_bf16 v[36:39], v[166:169], v[220:223], v[36:39]
	v_mfma_f32_16x16x32_bf16 v[32:35], v[174:177], v[220:223], v[32:35]
	s_setprio 0
	s_barrier
	s_add_i32 s8, s8, s37
	s_mov_b32 m0, s8
	ds_read_b128 v[180:183], v149 offset:49152
	ds_read_b128 v[196:199], v149 offset:50176
	ds_read_b128 v[200:203], v149 offset:51200
	ds_read_b128 v[204:207], v149 offset:52224
	ds_read_b128 v[208:211], v149 offset:53248
	ds_read_b128 v[212:215], v149 offset:54272
	ds_read_b128 v[216:219], v149 offset:55296
	ds_read_b128 v[220:223], v149 offset:56320
	global_load_lds_dwordx4 v189, s[78:79]
	s_add_i32 m0, s8, 0x2000
	s_add_i32 s8, s9, s37
	global_load_lds_dwordx4 v194, s[78:79]
	s_mov_b32 m0, s8
	s_nop 0
	global_load_lds_dwordx4 v195, s[78:79]
	s_add_i32 m0, s8, 0x2000
	s_nop 0
	global_load_lds_dwordx4 v224, s[78:79]
	s_mov_b32 m0, s26
	s_nop 0
	global_load_lds_dwordx4 v225, s[22:23]
	s_mov_b32 m0, s50
	s_nop 0
	global_load_lds_dwordx4 v226, s[22:23]
	s_waitcnt vmcnt(8)
	s_waitcnt lgkmcnt(0)
	s_barrier
	s_setprio 1
	s_waitcnt lgkmcnt(0)
	v_mfma_f32_16x16x32_bf16 v[92:95], v[130:133], v[180:183], v[92:95]
	v_mfma_f32_16x16x32_bf16 v[88:91], v[154:157], v[180:183], v[88:91]
	v_mfma_f32_16x16x32_bf16 v[84:87], v[130:133], v[200:203], v[84:87]
	v_mfma_f32_16x16x32_bf16 v[80:83], v[154:157], v[200:203], v[80:83]
	v_mfma_f32_16x16x32_bf16 v[76:79], v[130:133], v[208:211], v[76:79]
	v_mfma_f32_16x16x32_bf16 v[72:75], v[154:157], v[208:211], v[72:75]
	v_mfma_f32_16x16x32_bf16 v[68:71], v[130:133], v[216:219], v[68:71]
	v_mfma_f32_16x16x32_bf16 v[64:67], v[154:157], v[216:219], v[64:67]
	v_mfma_f32_16x16x32_bf16 v[92:95], v[134:137], v[196:199], v[92:95]
	v_mfma_f32_16x16x32_bf16 v[88:91], v[158:161], v[196:199], v[88:91]
	v_mfma_f32_16x16x32_bf16 v[84:87], v[134:137], v[204:207], v[84:87]
	v_mfma_f32_16x16x32_bf16 v[80:83], v[158:161], v[204:207], v[80:83]
	v_mfma_f32_16x16x32_bf16 v[76:79], v[134:137], v[212:215], v[76:79]
	v_mfma_f32_16x16x32_bf16 v[72:75], v[158:161], v[212:215], v[72:75]
	v_mfma_f32_16x16x32_bf16 v[68:71], v[134:137], v[220:223], v[68:71]
	v_mfma_f32_16x16x32_bf16 v[64:67], v[158:161], v[220:223], v[64:67]
	s_setprio 0
	s_setprio 1
	v_mfma_f32_16x16x32_bf16 v[28:31], v[162:165], v[180:183], v[28:31]
	v_mfma_f32_16x16x32_bf16 v[24:27], v[170:173], v[180:183], v[24:27]
	v_mfma_f32_16x16x32_bf16 v[20:23], v[162:165], v[200:203], v[20:23]
	v_mfma_f32_16x16x32_bf16 v[16:19], v[170:173], v[200:203], v[16:19]
	v_mfma_f32_16x16x32_bf16 v[12:15], v[162:165], v[208:211], v[12:15]
	v_mfma_f32_16x16x32_bf16 v[8:11], v[170:173], v[208:211], v[8:11]
	v_mfma_f32_16x16x32_bf16 v[4:7], v[162:165], v[216:219], v[4:7]
	v_mfma_f32_16x16x32_bf16 v[0:3], v[170:173], v[216:219], v[0:3]
	v_mfma_f32_16x16x32_bf16 v[28:31], v[166:169], v[196:199], v[28:31]
	v_mfma_f32_16x16x32_bf16 v[24:27], v[174:177], v[196:199], v[24:27]
	v_mfma_f32_16x16x32_bf16 v[20:23], v[166:169], v[204:207], v[20:23]
	v_mfma_f32_16x16x32_bf16 v[16:19], v[174:177], v[204:207], v[16:19]
	v_mfma_f32_16x16x32_bf16 v[12:15], v[166:169], v[212:215], v[12:15]
	v_mfma_f32_16x16x32_bf16 v[8:11], v[174:177], v[212:215], v[8:11]
	v_mfma_f32_16x16x32_bf16 v[4:7], v[166:169], v[220:223], v[4:7]
	v_mfma_f32_16x16x32_bf16 v[0:3], v[174:177], v[220:223], v[0:3]
	s_setprio 0
	s_barrier
	s_add_u32 vcc_lo, vcc_lo, 0x100
	s_addc_u32 vcc_hi, vcc_hi, 0
	s_add_u32 s20, s20, 0x100
	s_addc_u32 s21, s21, 0
	s_cmp_ge_i32 s84, s51
	s_mov_b32 s22, s84
	s_cbranch_scc0 .LBB0_1276
	v_readlane_b32 s78, v255, 54
	v_readlane_b32 s79, v255, 55

; #define ATT_DMA(t, b) do { \
;         _Pragma("unroll") for (int i_ = 0; i_ < 2; ++i_) glds16(Kg + (size_t)(t) * 64 * ZP + offK[i_], lds + (b) * BUF + (i_ * 8 + wid) * 1024); \
;         _Pragma("unroll") for (int i_ = 0; i_ < 2; ++i_) glds16(Vg + (size_t)(t) * 64 + offV[i_], lds + (b) * BUF + KBYTES + (i_ * 8 + wid) * 1024); } while (0)
; __device__ __forceinline__ void attn_phase(LAS unsigned char* lds, const bf16_t* Z, const bf16_t* VT, bf16_t* Y, const float* subln, float lam, float lam_init, float M0, unsigned* ctr, LAS int* s_unit, int wid_s_) {
;     ...
;         if (tid == 0) *s_unit = (int)atomicAdd(ctr, 1u);
;         __syncthreads();
;         const int U = *s_unit;
;         if (U >= 1024) break;
;         const int h = 7 - (U >> 7), qb = U & 127, q0 = qb * 128, qw = q0 + rg * 32;
;         const float m2 = exp2f(-(float)(h + 1)) * LOG2E;
;         const int W = (int)(150.f / m2) + 1;
;         const int tlo = max(0, q0 - W) >> 6, thi = min(S - 1, q0 + 127 + W) >> 6;
;         const int wlo = max(0, qw - W) >> 6, whi = min(S - 1, qw + 31 + W) >> 6;
;         const bf16_t* Kg = Z + 2048 + h * 128; const bf16_t* Vg = VT + (size_t)h * 128 * S;
;         bf16x8 qf[4];
;         { const bf16_t* qp = Z + (size_t)(qw + rr) * ZP + 1024 + h * 128 + jm * 64 + hh * 8;
; #pragma unroll
;           for (int t4 = 0; t4 < 4; ++t4) qf[t4] = *(const bf16x8*)(qp + t4 * 16); }
;         f32x16 O[4];
; #pragma unroll
;         for (int cb = 0; cb < 4; ++cb)
; #pragma unroll
;             for (int r = 0; r < 16; ++r) O[cb][r] = 0.f;
;         float ls = 0.f;
;     ...
;         const int Tlo = tlo >> 1, Thi = thi >> 1;
;         ATT_DMA(2 * Tlo, 0); ATT_DMA(2 * Tlo + 1, 1);
.LBB0_1294:
	s_or_b64 exec, exec, s[2:3]
	s_waitcnt lgkmcnt(0)
	s_barrier
	ds_read_b32 v0, v97 offset:8
	s_movk_i32 s2, 0x3ff
	s_waitcnt lgkmcnt(0)
	v_cmp_lt_i32_e32 vcc, s2, v0
	v_readfirstlane_b32 s15, v0
	s_mov_b64 s[2:3], -1
	s_cbranch_vccnz .LBB0_1291
	s_ashr_i32 s2, s15, 7
	s_sub_i32 s3, 8, s2
	v_cvt_f32_u32_e32 v0, s3
	s_sub_i32 s26, 7, s2
	s_lshl_b32 s2, s15, 7
	s_and_b32 s16, s2, 0x3f80
	s_mov_b32 s2, 0x42fc0000
	v_cmp_lt_f32_e32 vcc, s2, v0
	v_mov_b32_e32 v1, 0x42800000
	s_add_i32 s40, s16, s25
	v_cndmask_b32_e32 v1, 0, v1, vcc
	v_sub_f32_e32 v0, v1, v0
	v_exp_f32_e32 v0, v0
	s_and_b64 s[2:3], vcc, exec
	s_cselect_b32 s2, 0xffffffc0, 0
	s_mov_b32 s15, 0x42fc0000
	v_ldexp_f32 v0, v0, s2
	v_mul_f32_e32 v171, 0x3fb8aa3b, v0
	v_div_scale_f32 v0, s[2:3], v171, v171, s15
	v_rcp_f32_e32 v1, v0
	s_lshl_b32 s41, s26, 7
	s_mov_b32 m0, s37
	v_mov_b32_e32 v15, 0
	v_fma_f32 v2, -v0, v1, 1.0
	v_fmac_f32_e32 v1, v2, v1
	v_div_scale_f32 v2, vcc, s15, v171, s15
	v_mul_f32_e32 v3, v2, v1
	v_fma_f32 v4, -v0, v3, v2
	v_fmac_f32_e32 v3, v4, v1
	v_fma_f32 v0, -v0, v3, v2
	v_div_fmas_f32 v0, v0, v1, v3
	v_div_fixup_f32 v0, v0, v171, s15
	v_cvt_i32_f32_e32 v0, v0
	v_or_b32_e32 v2, s40, v203
	s_mov_b32 s15, s27
	v_mov_b32_e32 v14, 0
	v_readfirstlane_b32 s17, v0
	s_add_i32 s17, s17, 1
	s_add_i32 s2, s17, s16
	v_mov_b64_e32 v[0:1], s[78:79]
	s_add_i32 s51, s2, 0x7f
	s_lshl_b64 s[2:3], s[26:27], 22
	v_mad_i64_i32 v[0:1], s[48:49], v2, s33, v[0:1]
	s_lshl_b32 s26, s26, 8
	s_sub_i32 s50, s16, s17
	v_lshl_add_u64 v[0:1], v[0:1], 0, s[26:27]
	v_lshl_add_u64 v[0:1], v[0:1], 0, s[14:15]
	s_max_i32 s15, s50, 0
	s_add_u32 s50, s22, s26
	s_addc_u32 s78, s23, 0
	s_lshr_b32 s15, s15, 7
	s_lshl_b32 s26, s15, 1
	s_mul_i32 s86, s15, 0x140000
	s_mul_hi_u32 s49, s26, 0xa0000
	s_add_u32 s48, s50, s86
	v_lshl_add_u64 v[0:1], v[0:1], 0, v[96:97]
	s_addc_u32 s49, s78, s49
	flat_load_dwordx4 v[98:101], v[0:1] offset:2048
	flat_load_dwordx4 v[102:105], v[0:1] offset:2080
	flat_load_dwordx4 v[106:109], v[0:1] offset:2112
	flat_load_dwordx4 v[110:113], v[0:1] offset:2144
	v_lshl_add_u64 v[0:1], s[48:49], 0, v[168:169]
	global_load_lds_dwordx4 v[0:1], off
	v_lshl_add_u64 v[0:1], s[48:49], 0, v[166:167]
	s_add_i32 m0, s37, 0x2000
	v_readlane_b32 s48, v255, 52
	v_readlane_b32 s49, v255, 53
	s_add_u32 s48, s48, s2
	s_addc_u32 s49, s49, s3
	s_lshl_b32 s87, s15, 8
	s_add_u32 s48, s48, s87
	s_addc_u32 s49, s49, 0
	global_load_lds_dwordx4 v[0:1], off
	v_lshl_add_u64 v[0:1], v[156:157], 1, s[48:49]
	s_add_i32 m0, s37, 0x4000
	v_lshl_add_u64 v[2:3], v[158:159], 1, s[48:49]
	s_or_b32 s48, s26, 1
	global_load_lds_dwordx4 v[0:1], off
	s_add_i32 m0, s37, 0x6000
	s_min_i32 s51, s51, 0x3fff
	s_mul_hi_u32 s49, s48, 0xa0000
	s_mul_i32 s48, s48, 0xa0000
	s_add_u32 s48, s50, s48
	s_addc_u32 s49, s78, s49
	global_load_lds_dwordx4 v[2:3], off
	v_lshl_add_u64 v[4:5], s[48:49], 0, v[168:169]
	s_add_i32 m0, s37, 0x8000
	v_lshl_add_u64 v[0:1], v[0:1], 0, s[42:43]
	global_load_lds_dwordx4 v[4:5], off
	v_lshl_add_u64 v[4:5], s[48:49], 0, v[166:167]
	s_add_i32 m0, s37, 0xa000
	s_ashr_i32 s48, s51, 7
	global_load_lds_dwordx4 v[4:5], off
	s_add_i32 m0, s37, 0xc000
	v_mov_b32_e32 v13, 0
	global_load_lds_dwordx4 v[0:1], off
	v_lshl_add_u64 v[0:1], v[2:3], 0, s[42:43]
	s_add_i32 m0, s37, 0xe000
	s_cmp_gt_i32 s15, s48
	global_load_lds_dwordx4 v[0:1], off
	v_mov_b32_e32 v12, 0
	v_mov_b32_e32 v11, 0
	v_mov_b32_e32 v10, 0
	v_mov_b32_e32 v9, 0
	v_mov_b32_e32 v8, 0
	v_mov_b32_e32 v7, 0
	v_mov_b32_e32 v6, 0
	v_mov_b32_e32 v5, 0
	v_mov_b32_e32 v4, 0
	v_mov_b32_e32 v3, 0
	v_mov_b32_e32 v2, 0
	v_mov_b32_e32 v1, 0
	v_mov_b32_e32 v0, 0
	v_mov_b32_e32 v31, 0
	v_mov_b32_e32 v30, 0
	v_mov_b32_e32 v29, 0
	v_mov_b32_e32 v28, 0
	v_mov_b32_e32 v27, 0
	v_mov_b32_e32 v26, 0
	v_mov_b32_e32 v25, 0
	v_mov_b32_e32 v24, 0
	v_mov_b32_e32 v23, 0
	v_mov_b32_e32 v22, 0
	v_mov_b32_e32 v21, 0
	v_mov_b32_e32 v20, 0
	v_mov_b32_e32 v19, 0
	v_mov_b32_e32 v18, 0
	v_mov_b32_e32 v17, 0
	v_mov_b32_e32 v16, 0
	v_mov_b32_e32 v63, 0
	v_mov_b32_e32 v62, 0
	v_mov_b32_e32 v61, 0
	v_mov_b32_e32 v60, 0
	v_mov_b32_e32 v59, 0
	v_mov_b32_e32 v58, 0
	v_mov_b32_e32 v57, 0
	v_mov_b32_e32 v56, 0
	v_mov_b32_e32 v55, 0
	v_mov_b32_e32 v54, 0
	v_mov_b32_e32 v53, 0
	v_mov_b32_e32 v52, 0
	v_mov_b32_e32 v51, 0
	v_mov_b32_e32 v50, 0
	v_mov_b32_e32 v49, 0
	v_mov_b32_e32 v48, 0
	v_mov_b32_e32 v47, 0
	v_mov_b32_e32 v46, 0
	v_mov_b32_e32 v45, 0
	v_mov_b32_e32 v44, 0
	v_mov_b32_e32 v43, 0
	v_mov_b32_e32 v42, 0
	v_mov_b32_e32 v41, 0
	v_mov_b32_e32 v40, 0
	v_mov_b32_e32 v39, 0
	v_mov_b32_e32 v38, 0
	v_mov_b32_e32 v37, 0
	v_mov_b32_e32 v36, 0
	v_mov_b32_e32 v35, 0
	v_mov_b32_e32 v34, 0
	v_mov_b32_e32 v33, 0
	v_mov_b32_e32 v32, 0
	v_mov_b32_e32 v197, 0
	s_cbranch_scc1 .LBB0_1315
; #define ATT_DMA(t, b) do { \
;         _Pragma("unroll") for (int i_ = 0; i_ < 2; ++i_) glds16(Kg + (size_t)(t) * 64 * ZP + offK[i_], lds + (b) * BUF + (i_ * 8 + wid) * 1024); \
;         _Pragma("unroll") for (int i_ = 0; i_ < 2; ++i_) glds16(Vg + (size_t)(t) * 64 + offV[i_], lds + (b) * BUF + KBYTES + (i_ * 8 + wid) * 1024); } while (0)
; __device__ __forceinline__ void attn_phase(LAS unsigned char* lds, const bf16_t* Z, const bf16_t* VT, bf16_t* Y, const float* subln, float lam, float lam_init, float M0, unsigned* ctr, LAS int* s_unit, int wid_s_) {
;     ...
;         const int h = 7 - (U >> 7), qb = U & 127, q0 = qb * 128, qw = q0 + rg * 32;
;         const float m2 = exp2f(-(float)(h + 1)) * LOG2E;
;         const int W = (int)(150.f / m2) + 1;
;         const int tlo = max(0, q0 - W) >> 6, thi = min(S - 1, q0 + 127 + W) >> 6;
;         const int wlo = max(0, qw - W) >> 6, whi = min(S - 1, qw + 31 + W) >> 6;
;         const bf16_t* Kg = Z + 2048 + h * 128; const bf16_t* Vg = VT + (size_t)h * 128 * S;
;         bf16x8 qf[4];
;         { const bf16_t* qp = Z + (size_t)(qw + rr) * ZP + 1024 + h * 128 + jm * 64 + hh * 8;
; #pragma unroll
;           for (int t4 = 0; t4 < 4; ++t4) qf[t4] = *(const bf16x8*)(qp + t4 * 16); }
;         f32x16 O[4];
; #pragma unroll
;         for (int cb = 0; cb < 4; ++cb)
; #pragma unroll
;             for (int r = 0; r < 16; ++r) O[cb][r] = 0.f;
;         float ls = 0.f;
;     ...
;         const int Tlo = tlo >> 1, Thi = thi >> 1;
;         ATT_DMA(2 * Tlo, 0); ATT_DMA(2 * Tlo + 1, 1);
	s_sub_i32 s50, s40, s17
	s_max_i32 s51, s50, 0
	s_or_b32 s50, s40, 31
	s_add_i32 s17, s17, s50
	s_min_i32 s17, s17, 0x3fff
	s_lshr_b32 s51, s51, 6
	s_ashr_i32 s84, s17, 6
	s_lshl_b32 s85, s15, 7
	s_add_u32 s2, s87, s2
	s_addc_u32 s3, 0, s3
	s_add_u32 s70, s2, s28
	s_addc_u32 s71, s3, s29
	s_add_u32 s76, s70, 0x1a400180
	s_addc_u32 s77, s71, 0
	s_add_u32 s70, s70, 0x1a400100
	s_addc_u32 s71, s71, 0
	s_lshl_b32 s2, s41, 1
	v_add_u32_e32 v0, s16, v240
	s_mul_hi_u32 s3, s15, 0x140000
	s_add_u32 s2, s2, s86
	v_mov_b32_e32 v32, v97
	v_mov_b32_e32 v33, v97
	v_mov_b32_e32 v46, v97
	v_mov_b32_e32 v47, v97
	v_xor_b32_e32 v172, 0x80000000, v171
	v_subrev_u32_e32 v193, s85, v0
	s_addc_u32 s3, 0, s3
	v_mov_b32_e32 v34, v97
	v_mov_b32_e32 v35, v97
	v_mov_b32_e32 v36, v97
	v_mov_b32_e32 v37, v97
	v_mov_b32_e32 v38, v97
	v_mov_b32_e32 v39, v97
	v_mov_b32_e32 v40, v97
	v_mov_b32_e32 v41, v97
	v_mov_b32_e32 v42, v97
	v_mov_b32_e32 v43, v97
	v_mov_b32_e32 v44, v97
	v_mov_b32_e32 v45, v97
	v_mov_b64_e32 v[62:63], v[46:47]
	v_mov_b64_e32 v[16:17], v[32:33]
	v_mov_b64_e32 v[0:1], v[32:33]
	s_mov_b32 s49, 0
	v_mov_b32_e32 v174, v172
	v_mov_b32_e32 v175, v172
	s_add_u32 s68, s2, s28
	s_addc_u32 s69, s3, s29
	s_add_u32 s72, s68, 0x105e1000
	s_addc_u32 s73, s69, 0
	s_add_u32 s68, s68, 0x10541000
	s_addc_u32 s69, s69, 0
	v_mov_b32_e32 v197, 0
	v_mov_b64_e32 v[60:61], v[44:45]
	v_mov_b64_e32 v[58:59], v[42:43]
	v_mov_b64_e32 v[56:57], v[40:41]
	v_mov_b64_e32 v[54:55], v[38:39]
	v_mov_b64_e32 v[52:53], v[36:37]
	v_mov_b64_e32 v[50:51], v[34:35]
	v_mov_b64_e32 v[48:49], v[32:33]
	v_mov_b64_e32 v[18:19], v[34:35]
	v_mov_b64_e32 v[20:21], v[36:37]
	v_mov_b64_e32 v[22:23], v[38:39]
	v_mov_b64_e32 v[24:25], v[40:41]
	v_mov_b64_e32 v[26:27], v[42:43]
	v_mov_b64_e32 v[28:29], v[44:45]
	v_mov_b64_e32 v[30:31], v[46:47]
	v_mov_b64_e32 v[2:3], v[34:35]
	v_mov_b64_e32 v[4:5], v[36:37]
	v_mov_b64_e32 v[6:7], v[38:39]
	v_mov_b64_e32 v[8:9], v[40:41]
	v_mov_b64_e32 v[10:11], v[42:43]
	v_mov_b64_e32 v[12:13], v[44:45]
	v_mov_b64_e32 v[14:15], v[46:47]
	v_add3_u32 v176, v210, v211, 16
	v_add3_u32 v177, v210, v212, 16
	v_add3_u32 v178, v210, v213, 16
	v_add3_u32 v179, v210, v214, 16
	v_add3_u32 v180, v205, v206, 16
	v_add3_u32 v181, v205, v207, 16
	v_add3_u32 v182, v205, v208, 16
	v_add3_u32 v183, v205, v209, 16
	s_waitcnt vmcnt(0)
	s_branch .LBB0_1299
; #define LAS __attribute__((address_space(3)))
; __device__ __forceinline__ unsigned cvtpk(float lo, float hi) { f32x2_t v = {lo, hi}; bf16x2_t b = __builtin_convertvector(v, bf16x2_t); return __builtin_bit_cast(unsigned, b); }
; __device__ __forceinline__ void tile_body(bool DIAG, const LAS unsigned char* kb, const LAS unsigned char* vb, int krow, int jm, int hh, int rr, float d00, float m2, float sm2, float M0,
;                                           const bf16x8 (&qf)[4], f32x16 (&O)[4], float& ls) {
;     ...
;     float a = 0.f;
; #pragma unroll
;     for (int sb = 0; sb < 2; ++sb) {
;         bf16x8 vf[4][2];
; #pragma unroll
;         for (int cb = 0; cb < 4; ++cb)
; #pragma unroll
;             for (int k2 = 0; k2 < 2; ++k2) { const int e = 32 * cb + rr, c = 2 * (2 * sb + k2) + hh;
;                 vf[cb][k2] = *(const LAS bf16x8*)(vb + e * 128 + ((c ^ ((e >> 1) & 7)) * 16)); }
;         f32x16& s = sb ? s1 : s0;
; #pragma unroll
;         for (int r = 0; r < 16; ++r) { s[r] = __builtin_amdgcn_exp2f(s[r]); a += s[r]; }
;         bf16x8 pk[2];
; #pragma unroll
;         for (int k2 = 0; k2 < 2; ++k2) { u32x4 w; w.x = cvtpk(s[8 * k2 + 0], s[8 * k2 + 1]); w.y = cvtpk(s[8 * k2 + 2], s[8 * k2 + 3]); w.z = cvtpk(s[8 * k2 + 4], s[8 * k2 + 5]); w.w = cvtpk(s[8 * k2 + 6], s[8 * k2 + 7]);
;             pk[k2] = __builtin_bit_cast(bf16x8, w); }
;         __builtin_amdgcn_s_setprio(1);
; #pragma unroll
;         for (int cb = 0; cb < 4; ++cb)
; #pragma unroll
;             for (int k2 = 0; k2 < 2; ++k2) O[cb] = __builtin_amdgcn_mfma_f32_32x32x16_bf16(pk[k2], vf[cb][k2], O[cb], 0, 0, 0);
;         __builtin_amdgcn_s_setprio(0);
;         if (sb == 0) __builtin_amdgcn_sched_barrier(0);
;     }
;     ls += a;
.LBB0_1297:
	s_waitcnt lgkmcnt(0)
	v_mfma_f32_32x32x16_bf16 v[64:79], v[130:133], v[98:101], v[64:79]
	v_mfma_f32_32x32x16_bf16 v[80:95], v[114:117], v[98:101], v[80:95]
	v_mfma_f32_32x32x16_bf16 v[64:79], v[134:137], v[102:105], v[64:79]
	v_mfma_f32_32x32x16_bf16 v[80:95], v[118:121], v[102:105], v[80:95]
	v_mfma_f32_32x32x16_bf16 v[64:79], v[138:141], v[106:109], v[64:79]
	v_mfma_f32_32x32x16_bf16 v[80:95], v[122:125], v[106:109], v[80:95]
	v_mfma_f32_32x32x16_bf16 v[64:79], v[142:145], v[110:113], v[64:79]
	v_mfma_f32_32x32x16_bf16 v[80:95], v[126:129], v[110:113], v[80:95]
	ds_read_b128 v[114:117], v176 offset:49152
	ds_read_b128 v[118:121], v176 offset:53248
	ds_read_b128 v[122:125], v177 offset:49152
	ds_read_b128 v[126:129], v177 offset:53248
	ds_read_b128 v[130:133], v176 offset:57344
	ds_read_b128 v[134:137], v176 offset:61440
	ds_read_b128 v[138:141], v177 offset:57344
	ds_read_b128 v[142:145], v177 offset:61440
	v_exp_f32_e32 v173, v80
	v_exp_f32_e32 v184, v81
	v_exp_f32_e32 v189, v82
	v_exp_f32_e32 v192, v83
	v_exp_f32_e32 v194, v84
	v_exp_f32_e32 v195, v85
	v_exp_f32_e32 v198, v86
	v_exp_f32_e32 v217, v87
	v_exp_f32_e32 v218, v88
	v_exp_f32_e32 v219, v89
	v_exp_f32_e32 v220, v90
	v_exp_f32_e32 v221, v91
	v_exp_f32_e32 v222, v92
	v_exp_f32_e32 v223, v93
	v_exp_f32_e32 v224, v94
	v_exp_f32_e32 v225, v95
	v_cvt_pk_bf16_f32 v80, v173, v184
	v_cvt_pk_bf16_f32 v81, v189, v192
	v_cvt_pk_bf16_f32 v82, v194, v195
	v_cvt_pk_bf16_f32 v83, v198, v217
	v_cvt_pk_bf16_f32 v84, v218, v219
	v_cvt_pk_bf16_f32 v85, v220, v221
	v_cvt_pk_bf16_f32 v86, v222, v223
	v_cvt_pk_bf16_f32 v87, v224, v225
	s_waitcnt lgkmcnt(0)
	v_mfma_f32_32x32x16_bf16 v[32:47], v[80:83], v[114:117], v[32:47]
	v_mfma_f32_32x32x16_bf16 v[48:63], v[80:83], v[118:121], v[48:63]
	v_mfma_f32_32x32x16_bf16 v[16:31], v[80:83], v[130:133], v[16:31]
	v_mfma_f32_32x32x16_bf16 v[0:15], v[80:83], v[134:137], v[0:15]
	v_mfma_f32_32x32x16_bf16 v[32:47], v[84:87], v[122:125], v[32:47]
	v_mfma_f32_32x32x16_bf16 v[48:63], v[84:87], v[126:129], v[48:63]
	v_mfma_f32_32x32x16_bf16 v[16:31], v[84:87], v[138:141], v[16:31]
	v_mfma_f32_32x32x16_bf16 v[0:15], v[84:87], v[142:145], v[0:15]
	ds_read_b128 v[80:83], v178 offset:49152
	ds_read_b128 v[84:87], v178 offset:53248
	ds_read_b128 v[88:91], v179 offset:49152
	ds_read_b128 v[92:95], v179 offset:53248
	ds_read_b128 v[114:117], v178 offset:57344
	ds_read_b128 v[118:121], v178 offset:61440
	ds_read_b128 v[122:125], v179 offset:57344
	ds_read_b128 v[126:129], v179 offset:61440
	v_exp_f32_e32 v130, v64
	v_exp_f32_e32 v131, v65
	v_exp_f32_e32 v132, v66
	v_exp_f32_e32 v133, v67
	v_exp_f32_e32 v134, v68
	v_exp_f32_e32 v135, v69
	v_exp_f32_e32 v136, v70
	v_exp_f32_e32 v137, v71
	v_exp_f32_e32 v72, v72
	v_exp_f32_e32 v73, v73
	v_exp_f32_e32 v74, v74
	v_exp_f32_e32 v75, v75
	v_exp_f32_e32 v76, v76
	v_exp_f32_e32 v77, v77
	v_exp_f32_e32 v78, v78
	v_exp_f32_e32 v79, v79
	v_cvt_pk_bf16_f32 v64, v130, v131
	v_cvt_pk_bf16_f32 v65, v132, v133
	v_cvt_pk_bf16_f32 v66, v134, v135
	v_cvt_pk_bf16_f32 v67, v136, v137
	v_cvt_pk_bf16_f32 v68, v72, v73
	v_cvt_pk_bf16_f32 v69, v74, v75
	v_cvt_pk_bf16_f32 v70, v76, v77
	v_cvt_pk_bf16_f32 v71, v78, v79
	s_waitcnt lgkmcnt(0)
	v_mfma_f32_32x32x16_bf16 v[32:47], v[64:67], v[80:83], v[32:47]
	v_mfma_f32_32x32x16_bf16 v[48:63], v[64:67], v[84:87], v[48:63]
	v_mfma_f32_32x32x16_bf16 v[16:31], v[64:67], v[114:117], v[16:31]
	v_mfma_f32_32x32x16_bf16 v[0:15], v[64:67], v[118:121], v[0:15]
	v_mfma_f32_32x32x16_bf16 v[32:47], v[68:71], v[88:91], v[32:47]
	v_mfma_f32_32x32x16_bf16 v[48:63], v[68:71], v[92:95], v[48:63]
	v_mfma_f32_32x32x16_bf16 v[16:31], v[68:71], v[122:125], v[16:31]
	v_mfma_f32_32x32x16_bf16 v[0:15], v[68:71], v[126:129], v[0:15]
	v_add_f32_e32 v64, 0, v173
	v_add_f32_e32 v64, v184, v64
	v_add_f32_e32 v64, v189, v64
	v_add_f32_e32 v64, v192, v64
	v_add_f32_e32 v64, v194, v64
	v_add_f32_e32 v64, v195, v64
	v_add_f32_e32 v64, v198, v64
	v_add_f32_e32 v64, v217, v64
	v_add_f32_e32 v64, v218, v64
	v_add_f32_e32 v64, v219, v64
	v_add_f32_e32 v64, v220, v64
	v_add_f32_e32 v64, v221, v64
	v_add_f32_e32 v64, v222, v64
	v_add_f32_e32 v64, v223, v64
	v_add_f32_e32 v64, v224, v64
	v_add_f32_e32 v64, v225, v64
	v_add_f32_e32 v64, v130, v64
	v_add_f32_e32 v64, v131, v64
	v_add_f32_e32 v64, v132, v64
	v_add_f32_e32 v64, v133, v64
	v_add_f32_e32 v64, v134, v64
	v_add_f32_e32 v64, v135, v64
	v_add_f32_e32 v64, v136, v64
	v_add_f32_e32 v64, v137, v64
	v_add_f32_e32 v64, v72, v64
	v_add_f32_e32 v64, v73, v64
	v_add_f32_e32 v64, v74, v64
	v_add_f32_e32 v64, v75, v64
	v_add_f32_e32 v64, v76, v64
	v_add_f32_e32 v64, v77, v64
	v_add_f32_e32 v64, v78, v64
	v_add_f32_e32 v64, v79, v64
	v_add_f32_e32 v197, v197, v64
.LBB0_1298:
	s_add_i32 s49, s49, 1
	s_add_i32 s2, s15, s49
	s_addk_i32 s85, 0x80
	s_add_i32 s26, s26, 2
	s_add_i32 s2, s2, -1
	v_add_u32_e32 v193, 0xffffff80, v193
	v_xor_b32_e32 v176, 0x10000, v176
	v_xor_b32_e32 v177, 0x10000, v177
	v_xor_b32_e32 v178, 0x10000, v178
	v_xor_b32_e32 v179, 0x10000, v179
	v_xor_b32_e32 v180, 0x10000, v180
	v_xor_b32_e32 v181, 0x10000, v181
	v_xor_b32_e32 v182, 0x10000, v182
	v_xor_b32_e32 v183, 0x10000, v183
	s_add_u32 s70, s70, s44
	s_addc_u32 s71, s71, s45
	s_add_u32 s76, s76, s44
	s_addc_u32 s77, s77, s45
	s_add_u32 s68, s68, s46
	s_addc_u32 s69, s69, s47
	s_add_u32 s72, s72, s46
	s_addc_u32 s73, s73, s47
	s_cmp_ge_i32 s2, s48
	s_cbranch_scc1 .LBB0_1314

; #define LAS __attribute__((address_space(3)))
; __device__ __forceinline__ void tile_body(bool DIAG, const LAS unsigned char* kb, const LAS unsigned char* vb, int krow, int jm, int hh, int rr, float d00, float m2, float sm2, float M0,
;                                           const bf16x8 (&qf)[4], f32x16 (&O)[4], float& ls) {
;     bf16x8 kf[2][4];
; #pragma unroll
;     for (int sb = 0; sb < 2; ++sb)
; #pragma unroll
;         for (int t4 = 0; t4 < 4; ++t4) { const int c = jm * 8 + 2 * t4 + hh, kr = 32 * sb + krow;
;             kf[sb][t4] = *(const LAS bf16x8*)(kb + kr * 256 + ((c ^ (kr & 15)) * 16)); }
;     f32x16 s0, s1;
;     if (!DIAG) { const float base0 = -M0 - sm2 * d00, base1 = base0 + sm2 * 32.0f;
; #pragma unroll
;         for (int r = 0; r < 16; ++r) { const float cr = (float)(16 * (r >> 3) + (r & 7)); s0[r] = fmaf(sm2, cr, base0); s1[r] = fmaf(sm2, cr, base1); }
; __device__ __forceinline__ void attn_phase(LAS unsigned char* lds, const bf16_t* Z, const bf16_t* VT, bf16_t* Y, const float* subln, float lam, float lam_init, float M0, unsigned* ctr, LAS int* s_unit, int wid_s_) {
;     ...
;             for (int half = 0; half < 2; ++half) { const int t = 2 * T + half;
;                 if (t >= wlo && t <= whi) {
;                     const LAS unsigned char* kb = lds + (2 * b + half) * BUF; const LAS unsigned char* vb = kb + KBYTES;
;                     const int k0 = t * 64;
;                     const float d00 = (float)(qw + rr - (k0 + 8 * hh));
;                     const bool left = (k0 + 63 <= qw), right = (k0 >= qw + 31);
;                     tile_body(!(left || right), kb, vb, krow, jm, hh, rr, d00, m2, right ? -m2 : m2, M0, qf, O, ls);
.LBB0_1303:
	s_add_i32 s86, s16, 16
	s_cmp_lt_u32 s26, s51
	s_cselect_b64 s[2:3], -1, 0
	s_cmp_gt_i32 s26, s84
	s_cselect_b64 s[16:17], -1, 0
	s_or_b64 s[2:3], s[2:3], s[16:17]
	s_and_b64 vcc, exec, s[2:3]
	s_cbranch_vccnz .LBB0_1309
	ds_read_b128 v[114:117], v180
	ds_read_b128 v[130:133], v180 offset:8192
	ds_read_b128 v[118:121], v181
	ds_read_b128 v[134:137], v181 offset:8192
	ds_read_b128 v[122:125], v182
	ds_read_b128 v[138:141], v182 offset:8192
	ds_read_b128 v[126:129], v183
	ds_read_b128 v[142:145], v183 offset:8192
	s_add_i32 s2, s85, 63
	s_cmp_le_i32 s2, s40
	s_cselect_b64 s[2:3], -1, 0
	s_cmp_lt_i32 s85, s50
	v_cvt_f32_i32_e32 v184, v193
	s_cselect_b64 s[16:17], -1, 0
	s_cmp_ge_i32 s85, s50
	s_cselect_b64 s[78:79], -1, 0
	s_or_b64 s[78:79], s[78:79], s[2:3]
	s_mov_b64 s[2:3], -1
	s_and_b64 vcc, exec, s[78:79]
	s_cbranch_vccz .LBB0_1306
	v_cndmask_b32_e64 v78, -v171, v171, s[16:17]
	v_fma_f32 v94, -v78, v184, -v201
	v_fmamk_f32 v218, v78, 0x42000000, v94
	v_fma_f32 v80, 0, v78, v94
	v_fma_f32 v64, 0, v78, v218
	v_add_f32_e32 v81, v78, v94
	v_add_f32_e32 v65, v78, v218
	v_fma_f32 v82, v78, s80, v94
	v_fma_f32 v83, v78, s81, v94
	v_fma_f32 v66, v78, s80, v218
	v_fma_f32 v67, v78, s81, v218
	v_fma_f32 v84, v78, s66, v94
	v_fma_f32 v85, v78, s67, v94
	v_fma_f32 v68, v78, s66, v218
	v_fma_f32 v69, v78, s67, v218
	v_fma_f32 v86, v78, s74, v94
	v_fma_f32 v87, v78, s75, v94
	v_fma_f32 v70, v78, s74, v218
	v_fma_f32 v71, v78, s75, v218
	v_fma_f32 v88, v78, s34, v94
	v_fma_f32 v89, v78, s35, v94
	v_fma_f32 v72, v78, s34, v218
	v_fma_f32 v73, v78, s35, v218
	v_fma_f32 v90, v78, s96, v94
	v_fma_f32 v91, v78, s97, v94
	v_fma_f32 v74, v78, s96, v218
	v_fma_f32 v75, v78, s97, v218
	v_fma_f32 v92, v78, s52, v94
	v_fma_f32 v93, v78, s53, v94
	v_fma_f32 v76, v78, s52, v218
	v_fma_f32 v77, v78, s53, v218
	v_fma_f32 v95, v78, s55, v94
	v_fma_f32 v94, v78, s54, v94
	v_fma_f32 v79, v78, s55, v218
	v_fma_f32 v78, v78, s54, v218
	s_mov_b64 s[2:3], 0

; #define LAS __attribute__((address_space(3)))
; __device__ __forceinline__ unsigned cvtpk(float lo, float hi) { f32x2_t v = {lo, hi}; bf16x2_t b = __builtin_convertvector(v, bf16x2_t); return __builtin_bit_cast(unsigned, b); }
; __device__ __forceinline__ void tile_body(bool DIAG, const LAS unsigned char* kb, const LAS unsigned char* vb, int krow, int jm, int hh, int rr, float d00, float m2, float sm2, float M0,
;                                           const bf16x8 (&qf)[4], f32x16 (&O)[4], float& ls) {
;     ...
;     __builtin_amdgcn_s_setprio(1);
; #pragma unroll
;     for (int t4 = 0; t4 < 4; ++t4) s0 = __builtin_amdgcn_mfma_f32_32x32x16_bf16(kf[0][t4], qf[t4], s0, 0, 0, 0);
; #pragma unroll
;     for (int t4 = 0; t4 < 4; ++t4) s1 = __builtin_amdgcn_mfma_f32_32x32x16_bf16(kf[1][t4], qf[t4], s1, 0, 0, 0);
;     __builtin_amdgcn_s_setprio(0);
;     __builtin_amdgcn_sched_barrier(0);
;     float a = 0.f;
; #pragma unroll
;     for (int sb = 0; sb < 2; ++sb) {
;         bf16x8 vf[4][2];
; #pragma unroll
;         for (int cb = 0; cb < 4; ++cb)
; #pragma unroll
;             for (int k2 = 0; k2 < 2; ++k2) { const int e = 32 * cb + rr, c = 2 * (2 * sb + k2) + hh;
;                 vf[cb][k2] = *(const LAS bf16x8*)(vb + e * 128 + ((c ^ ((e >> 1) & 7)) * 16)); }
;         f32x16& s = sb ? s1 : s0;
; #pragma unroll
;         for (int r = 0; r < 16; ++r) { s[r] = __builtin_amdgcn_exp2f(s[r]); a += s[r]; }
;         bf16x8 pk[2];
; #pragma unroll
;         for (int k2 = 0; k2 < 2; ++k2) { u32x4 w; w.x = cvtpk(s[8 * k2 + 0], s[8 * k2 + 1]); w.y = cvtpk(s[8 * k2 + 2], s[8 * k2 + 3]); w.z = cvtpk(s[8 * k2 + 4], s[8 * k2 + 5]); w.w = cvtpk(s[8 * k2 + 6], s[8 * k2 + 7]);
;             pk[k2] = __builtin_bit_cast(bf16x8, w); }
;         __builtin_amdgcn_s_setprio(1);
; #pragma unroll
;         for (int cb = 0; cb < 4; ++cb)
; #pragma unroll
;             for (int k2 = 0; k2 < 2; ++k2) O[cb] = __builtin_amdgcn_mfma_f32_32x32x16_bf16(pk[k2], vf[cb][k2], O[cb], 0, 0, 0);
;         __builtin_amdgcn_s_setprio(0);
;         if (sb == 0) __builtin_amdgcn_sched_barrier(0);
;     }
;     ls += a;
.LBB0_1308:
	s_waitcnt lgkmcnt(0)
	v_mfma_f32_32x32x16_bf16 v[64:79], v[130:133], v[98:101], v[64:79]
	v_mfma_f32_32x32x16_bf16 v[80:95], v[114:117], v[98:101], v[80:95]
	v_mfma_f32_32x32x16_bf16 v[64:79], v[134:137], v[102:105], v[64:79]
	v_mfma_f32_32x32x16_bf16 v[80:95], v[118:121], v[102:105], v[80:95]
	v_mfma_f32_32x32x16_bf16 v[64:79], v[138:141], v[106:109], v[64:79]
	v_mfma_f32_32x32x16_bf16 v[80:95], v[122:125], v[106:109], v[80:95]
	v_mfma_f32_32x32x16_bf16 v[64:79], v[142:145], v[110:113], v[64:79]
	v_mfma_f32_32x32x16_bf16 v[80:95], v[126:129], v[110:113], v[80:95]
	ds_read_b128 v[114:117], v176 offset:16384
	ds_read_b128 v[118:121], v176 offset:20480
	ds_read_b128 v[122:125], v177 offset:16384
	ds_read_b128 v[126:129], v177 offset:20480
	ds_read_b128 v[130:133], v176 offset:24576
	ds_read_b128 v[134:137], v176 offset:28672
	ds_read_b128 v[138:141], v177 offset:24576
	ds_read_b128 v[142:145], v177 offset:28672
	v_exp_f32_e32 v173, v80
	v_exp_f32_e32 v184, v81
	v_exp_f32_e32 v192, v82
	v_exp_f32_e32 v218, v83
	v_exp_f32_e32 v219, v84
	v_exp_f32_e32 v220, v85
	v_exp_f32_e32 v221, v86
	v_exp_f32_e32 v222, v87
	v_exp_f32_e32 v223, v88
	v_exp_f32_e32 v224, v89
	v_exp_f32_e32 v225, v90
	v_exp_f32_e32 v217, v91
	v_exp_f32_e32 v226, v92
	v_exp_f32_e32 v227, v93
	v_exp_f32_e32 v228, v94
	v_exp_f32_e32 v229, v95
	v_cvt_pk_bf16_f32 v80, v173, v184
	v_cvt_pk_bf16_f32 v81, v192, v218
	v_cvt_pk_bf16_f32 v82, v219, v220
	v_cvt_pk_bf16_f32 v83, v221, v222
	v_cvt_pk_bf16_f32 v84, v223, v224
	v_cvt_pk_bf16_f32 v85, v225, v217
	v_cvt_pk_bf16_f32 v86, v226, v227
	v_cvt_pk_bf16_f32 v87, v228, v229
	s_waitcnt lgkmcnt(0)
	v_mfma_f32_32x32x16_bf16 v[32:47], v[80:83], v[114:117], v[32:47]
	v_mfma_f32_32x32x16_bf16 v[48:63], v[80:83], v[118:121], v[48:63]
	v_mfma_f32_32x32x16_bf16 v[16:31], v[80:83], v[130:133], v[16:31]
	v_mfma_f32_32x32x16_bf16 v[0:15], v[80:83], v[134:137], v[0:15]
	v_mfma_f32_32x32x16_bf16 v[32:47], v[84:87], v[122:125], v[32:47]
	v_mfma_f32_32x32x16_bf16 v[48:63], v[84:87], v[126:129], v[48:63]
	v_mfma_f32_32x32x16_bf16 v[16:31], v[84:87], v[138:141], v[16:31]
	v_mfma_f32_32x32x16_bf16 v[0:15], v[84:87], v[142:145], v[0:15]
	ds_read_b128 v[80:83], v178 offset:16384
	ds_read_b128 v[84:87], v178 offset:20480
	ds_read_b128 v[88:91], v179 offset:16384
	ds_read_b128 v[92:95], v179 offset:20480
	ds_read_b128 v[114:117], v178 offset:24576
	ds_read_b128 v[118:121], v178 offset:28672
	ds_read_b128 v[122:125], v179 offset:24576
	ds_read_b128 v[126:129], v179 offset:28672
	v_exp_f32_e32 v130, v64
	v_exp_f32_e32 v131, v65
	v_exp_f32_e32 v132, v66
	v_exp_f32_e32 v133, v67
	v_exp_f32_e32 v134, v68
	v_exp_f32_e32 v135, v69
	v_exp_f32_e32 v136, v70
	v_exp_f32_e32 v137, v71
	v_exp_f32_e32 v72, v72
	v_exp_f32_e32 v73, v73
	v_exp_f32_e32 v74, v74
	v_exp_f32_e32 v75, v75
	v_exp_f32_e32 v76, v76
	v_exp_f32_e32 v77, v77
	v_exp_f32_e32 v78, v78
	v_exp_f32_e32 v79, v79
	v_cvt_pk_bf16_f32 v64, v130, v131
	v_cvt_pk_bf16_f32 v65, v132, v133
	v_cvt_pk_bf16_f32 v66, v134, v135
	v_cvt_pk_bf16_f32 v67, v136, v137
	v_cvt_pk_bf16_f32 v68, v72, v73
	v_cvt_pk_bf16_f32 v69, v74, v75
	v_cvt_pk_bf16_f32 v70, v76, v77
	v_cvt_pk_bf16_f32 v71, v78, v79
	s_waitcnt lgkmcnt(0)
	v_mfma_f32_32x32x16_bf16 v[32:47], v[64:67], v[80:83], v[32:47]
	v_mfma_f32_32x32x16_bf16 v[48:63], v[64:67], v[84:87], v[48:63]
	v_mfma_f32_32x32x16_bf16 v[16:31], v[64:67], v[114:117], v[16:31]
	v_mfma_f32_32x32x16_bf16 v[0:15], v[64:67], v[118:121], v[0:15]
	v_mfma_f32_32x32x16_bf16 v[32:47], v[68:71], v[88:91], v[32:47]
	v_mfma_f32_32x32x16_bf16 v[48:63], v[68:71], v[92:95], v[48:63]
	v_mfma_f32_32x32x16_bf16 v[16:31], v[68:71], v[122:125], v[16:31]
	v_mfma_f32_32x32x16_bf16 v[0:15], v[68:71], v[126:129], v[0:15]
	v_add_f32_e32 v64, 0, v173
	v_add_f32_e32 v64, v184, v64
	v_add_f32_e32 v64, v192, v64
	v_add_f32_e32 v64, v218, v64
	v_add_f32_e32 v64, v219, v64
	v_add_f32_e32 v64, v220, v64
	v_add_f32_e32 v64, v221, v64
	v_add_f32_e32 v64, v222, v64
	v_add_f32_e32 v64, v223, v64
	v_add_f32_e32 v64, v224, v64
	v_add_f32_e32 v64, v225, v64
	v_add_f32_e32 v64, v217, v64
	v_add_f32_e32 v64, v226, v64
	v_add_f32_e32 v64, v227, v64
	v_add_f32_e32 v64, v228, v64
	v_add_f32_e32 v64, v229, v64
	v_add_f32_e32 v64, v130, v64
	v_add_f32_e32 v64, v131, v64
	v_add_f32_e32 v64, v132, v64
	v_add_f32_e32 v64, v133, v64
	v_add_f32_e32 v64, v134, v64
	v_add_f32_e32 v64, v135, v64
	v_add_f32_e32 v64, v136, v64
	v_add_f32_e32 v64, v137, v64
	v_add_f32_e32 v64, v72, v64
	v_add_f32_e32 v64, v73, v64
	v_add_f32_e32 v64, v74, v64
	v_add_f32_e32 v64, v75, v64
	v_add_f32_e32 v64, v76, v64
	v_add_f32_e32 v64, v77, v64
	v_add_f32_e32 v64, v78, v64
	v_add_f32_e32 v64, v79, v64
	v_add_f32_e32 v197, v197, v64

; #define LAS __attribute__((address_space(3)))
; __device__ __forceinline__ void tile_body(bool DIAG, const LAS unsigned char* kb, const LAS unsigned char* vb, int krow, int jm, int hh, int rr, float d00, float m2, float sm2, float M0,
;                                           const bf16x8 (&qf)[4], f32x16 (&O)[4], float& ls) {
;     bf16x8 kf[2][4];
; #pragma unroll
;     for (int sb = 0; sb < 2; ++sb)
; #pragma unroll
;         for (int t4 = 0; t4 < 4; ++t4) { const int c = jm * 8 + 2 * t4 + hh, kr = 32 * sb + krow;
;             kf[sb][t4] = *(const LAS bf16x8*)(kb + kr * 256 + ((c ^ (kr & 15)) * 16)); }
;     f32x16 s0, s1;
;     if (!DIAG) { const float base0 = -M0 - sm2 * d00, base1 = base0 + sm2 * 32.0f;
; #pragma unroll
;         for (int r = 0; r < 16; ++r) { const float cr = (float)(16 * (r >> 3) + (r & 7)); s0[r] = fmaf(sm2, cr, base0); s1[r] = fmaf(sm2, cr, base1); }
; __device__ __forceinline__ void attn_phase(LAS unsigned char* lds, const bf16_t* Z, const bf16_t* VT, bf16_t* Y, const float* subln, float lam, float lam_init, float M0, unsigned* ctr, LAS int* s_unit, int wid_s_) {
;     ...
;             for (int half = 0; half < 2; ++half) { const int t = 2 * T + half;
;                 if (t >= wlo && t <= whi) {
;                     const LAS unsigned char* kb = lds + (2 * b + half) * BUF; const LAS unsigned char* vb = kb + KBYTES;
;                     const int k0 = t * 64;
;                     const float d00 = (float)(qw + rr - (k0 + 8 * hh));
;                     const bool left = (k0 + 63 <= qw), right = (k0 >= qw + 31);
;                     tile_body(!(left || right), kb, vb, krow, jm, hh, rr, d00, m2, right ? -m2 : m2, M0, qf, O, ls);
.Ldma_mid_skip:
	s_add_i32 s2, s26, 1
	s_cmp_lt_u32 s2, s51
	s_cselect_b64 s[2:3], -1, 0
	s_cmp_ge_i32 s26, s84
	s_cselect_b64 s[16:17], -1, 0
	s_or_b64 s[2:3], s[16:17], s[2:3]
	s_and_b64 vcc, exec, s[2:3]
	s_cbranch_vccnz .LBB0_1298
	ds_read_b128 v[114:117], v180 offset:32768
	ds_read_b128 v[130:133], v180 offset:40960
	ds_read_b128 v[118:121], v181 offset:32768
	ds_read_b128 v[134:137], v181 offset:40960
	ds_read_b128 v[122:125], v182 offset:32768
	ds_read_b128 v[138:141], v182 offset:40960
	ds_read_b128 v[126:129], v183 offset:32768
	ds_read_b128 v[142:145], v183 offset:40960
	s_add_i32 s16, s85, 64
	s_add_i32 s2, s85, 0x7f
	v_subrev_u32_e32 v64, 64, v193
	s_cmp_gt_i32 s2, s40
	v_cvt_f32_i32_e32 v184, v64
	s_cselect_b64 s[2:3], -1, 0
	s_cmp_lt_i32 s16, s50
	s_cselect_b64 s[16:17], -1, 0
	s_and_b64 s[78:79], s[16:17], s[2:3]
	s_mov_b64 s[2:3], -1
	s_and_b64 vcc, exec, s[78:79]
	s_cbranch_vccnz .LBB0_1312
	v_cndmask_b32_e64 v78, -v171, v171, s[16:17]
	v_fma_f32 v94, -v78, v184, -v201
	v_fmamk_f32 v194, v78, 0x42000000, v94
	v_fma_f32 v80, 0, v78, v94
	v_fma_f32 v64, 0, v78, v194
	v_add_f32_e32 v81, v78, v94
	v_add_f32_e32 v65, v78, v194
	v_fma_f32 v82, v78, s80, v94
	v_fma_f32 v83, v78, s81, v94
	v_fma_f32 v66, v78, s80, v194
	v_fma_f32 v67, v78, s81, v194
	v_fma_f32 v84, v78, s66, v94
	v_fma_f32 v85, v78, s67, v94
	v_fma_f32 v68, v78, s66, v194
	v_fma_f32 v69, v78, s67, v194
	v_fma_f32 v86, v78, s74, v94
	v_fma_f32 v87, v78, s75, v94
	v_fma_f32 v70, v78, s74, v194
	v_fma_f32 v71, v78, s75, v194
	v_fma_f32 v88, v78, s34, v94
	v_fma_f32 v89, v78, s35, v94
	v_fma_f32 v72, v78, s34, v194
	v_fma_f32 v73, v78, s35, v194
	v_fma_f32 v90, v78, s96, v94
	v_fma_f32 v91, v78, s97, v94
	v_fma_f32 v74, v78, s96, v194
	v_fma_f32 v75, v78, s97, v194
	v_fma_f32 v92, v78, s52, v94
	v_fma_f32 v93, v78, s53, v94
	v_fma_f32 v76, v78, s52, v194
	v_fma_f32 v77, v78, s53, v194
	v_fma_f32 v95, v78, s55, v94
	v_fma_f32 v94, v78, s54, v94
	v_fma_f32 v79, v78, s55, v194
	v_fma_f32 v78, v78, s54, v194
	s_mov_b64 s[2:3], 0

; template <class Epi, class Sched, bool ALIGN_EPI = false, bool SP2 = false>
; __device__ __forceinline__ void gemm_phase(PG8_LAS unsigned char* lds, const Gemm g, const Sched& S, const Epi& E, int wid_s_) {
;     ...
; #pragma unroll
;         for (int a = 0; a < 2; ++a)
; #pragma unroll
;             for (int b = 0; b < 2; ++b)
; #pragma unroll
;                 for (int m = 0; m < 4; ++m)
; #pragma unroll
;                     for (int n = 0; n < 2; ++n) acc[a][b][m][n] = (f32x4){0.f, 0.f, 0.f, 0.f};
;         cur = nxt; cA = nA; cB = nB; ++ui;
.LBB0_1391:
	v_mov_b32_e32 v129, 0
	s_andn2_b64 vcc, exec, s[14:15]
	v_mov_b32_e32 v128, v129
	v_mov_b32_e32 v127, v129
	v_mov_b32_e32 v126, v129
	v_mov_b32_e32 v125, v129
	v_mov_b32_e32 v124, v129
	v_mov_b32_e32 v123, v129
	v_mov_b32_e32 v122, v129
	v_mov_b32_e32 v121, v129
	v_mov_b32_e32 v120, v129
	v_mov_b32_e32 v119, v129
	v_mov_b32_e32 v118, v129
	v_mov_b32_e32 v117, v129
	v_mov_b32_e32 v116, v129
	v_mov_b32_e32 v115, v129
	v_mov_b32_e32 v114, v129
	v_mov_b32_e32 v113, v129
	v_mov_b32_e32 v112, v129
	v_mov_b32_e32 v111, v129
	v_mov_b32_e32 v110, v129
	v_mov_b32_e32 v109, v129
	v_mov_b32_e32 v108, v129
	v_mov_b32_e32 v107, v129
	v_mov_b32_e32 v106, v129
	v_mov_b32_e32 v105, v129
	v_mov_b32_e32 v104, v129
	v_mov_b32_e32 v103, v129
	v_mov_b32_e32 v102, v129
	v_mov_b32_e32 v101, v129
	v_mov_b32_e32 v100, v129
	v_mov_b32_e32 v99, v129
	v_mov_b32_e32 v98, v129
	v_mov_b32_e32 v63, v129
	v_mov_b32_e32 v62, v129
	v_mov_b32_e32 v61, v129
	v_mov_b32_e32 v60, v129
	v_mov_b32_e32 v59, v129
	v_mov_b32_e32 v58, v129
	v_mov_b32_e32 v57, v129
	v_mov_b32_e32 v56, v129
	v_mov_b32_e32 v55, v129
	v_mov_b32_e32 v54, v129
	v_mov_b32_e32 v53, v129
	v_mov_b32_e32 v52, v129
	v_mov_b32_e32 v51, v129
	v_mov_b32_e32 v50, v129
	v_mov_b32_e32 v49, v129
	v_mov_b32_e32 v48, v129
	v_mov_b32_e32 v47, v129
	v_mov_b32_e32 v46, v129
	v_mov_b32_e32 v45, v129
	v_mov_b32_e32 v44, v129
	v_mov_b32_e32 v43, v129
	v_mov_b32_e32 v42, v129
	v_mov_b32_e32 v41, v129
	v_mov_b32_e32 v40, v129
	v_mov_b32_e32 v39, v129
	v_mov_b32_e32 v38, v129
	v_mov_b32_e32 v37, v129
	v_mov_b32_e32 v36, v129
	v_mov_b32_e32 v35, v129
	v_mov_b32_e32 v34, v129
	v_mov_b32_e32 v33, v129
	v_mov_b32_e32 v32, v129
	v_mov_b32_e32 v95, v129
	v_mov_b32_e32 v94, v129
	v_mov_b32_e32 v93, v129
	v_mov_b32_e32 v92, v129
	v_mov_b32_e32 v91, v129
	v_mov_b32_e32 v90, v129
	v_mov_b32_e32 v89, v129
	v_mov_b32_e32 v88, v129
	v_mov_b32_e32 v87, v129
	v_mov_b32_e32 v86, v129
	v_mov_b32_e32 v85, v129
	v_mov_b32_e32 v84, v129
	v_mov_b32_e32 v83, v129
	v_mov_b32_e32 v82, v129
	v_mov_b32_e32 v81, v129
	v_mov_b32_e32 v80, v129
	v_mov_b32_e32 v79, v129
	v_mov_b32_e32 v78, v129
	v_mov_b32_e32 v77, v129
	v_mov_b32_e32 v76, v129
	v_mov_b32_e32 v75, v129
	v_mov_b32_e32 v74, v129
	v_mov_b32_e32 v73, v129
	v_mov_b32_e32 v72, v129
	v_mov_b32_e32 v71, v129
	v_mov_b32_e32 v70, v129
	v_mov_b32_e32 v69, v129
	v_mov_b32_e32 v68, v129
	v_mov_b32_e32 v67, v129
	v_mov_b32_e32 v66, v129
	v_mov_b32_e32 v65, v129
	v_mov_b32_e32 v64, v129
	v_mov_b32_e32 v31, v129
	v_mov_b32_e32 v30, v129
	v_mov_b32_e32 v29, v129
	v_mov_b32_e32 v28, v129
	v_mov_b32_e32 v27, v129
	v_mov_b32_e32 v26, v129
	v_mov_b32_e32 v25, v129
	v_mov_b32_e32 v24, v129
	v_mov_b32_e32 v23, v129
	v_mov_b32_e32 v22, v129
	v_mov_b32_e32 v21, v129
	v_mov_b32_e32 v20, v129
	v_mov_b32_e32 v19, v129
	v_mov_b32_e32 v18, v129
	v_mov_b32_e32 v17, v129
	v_mov_b32_e32 v16, v129
	v_mov_b32_e32 v15, v129
	v_mov_b32_e32 v14, v129
	v_mov_b32_e32 v13, v129
	v_mov_b32_e32 v12, v129
	v_mov_b32_e32 v11, v129
	v_mov_b32_e32 v10, v129
	v_mov_b32_e32 v9, v129
	v_mov_b32_e32 v8, v129
	v_mov_b32_e32 v7, v129
	v_mov_b32_e32 v6, v129
	v_mov_b32_e32 v5, v129
	v_mov_b32_e32 v4, v129
	v_mov_b32_e32 v3, v129
	v_mov_b32_e32 v2, v129
	v_mov_b32_e32 v1, v129
	v_mov_b32_e32 v0, v129
	s_cbranch_vccnz .LBB0_1394
	s_add_u32 s90, s20, 0x100
	s_addc_u32 s91, s21, 0
	s_add_u32 s20, s22, 0x80
	v_mov_b32_e32 v0, 0
	s_addc_u32 s21, s23, 0
	s_mov_b32 s22, 0
	v_mov_b32_e32 v1, v0
	v_mov_b32_e32 v2, v0
	v_mov_b32_e32 v3, v0
	v_mov_b32_e32 v4, v0
	v_mov_b32_e32 v5, v0
	v_mov_b32_e32 v6, v0
	v_mov_b32_e32 v7, v0
	v_mov_b32_e32 v8, v0
	v_mov_b32_e32 v9, v0
	v_mov_b32_e32 v10, v0
	v_mov_b32_e32 v11, v0
	v_mov_b32_e32 v12, v0
	v_mov_b32_e32 v13, v0
	v_mov_b32_e32 v14, v0
	v_mov_b32_e32 v15, v0
	v_mov_b32_e32 v16, v0
	v_mov_b32_e32 v17, v0
	v_mov_b32_e32 v18, v0
	v_mov_b32_e32 v19, v0
	v_mov_b32_e32 v20, v0
	v_mov_b32_e32 v21, v0
	v_mov_b32_e32 v22, v0
	v_mov_b32_e32 v23, v0
	v_mov_b32_e32 v24, v0
	v_mov_b32_e32 v25, v0
	v_mov_b32_e32 v26, v0
	v_mov_b32_e32 v27, v0
	v_mov_b32_e32 v28, v0
	v_mov_b32_e32 v29, v0
	v_mov_b32_e32 v30, v0
	v_mov_b32_e32 v31, v0
	v_mov_b32_e32 v64, v0
	v_mov_b32_e32 v65, v0
	v_mov_b32_e32 v66, v0
	v_mov_b32_e32 v67, v0
	v_mov_b32_e32 v68, v0
	v_mov_b32_e32 v69, v0
	v_mov_b32_e32 v70, v0
	v_mov_b32_e32 v71, v0
	v_mov_b32_e32 v72, v0
	v_mov_b32_e32 v73, v0
	v_mov_b32_e32 v74, v0
	v_mov_b32_e32 v75, v0
	v_mov_b32_e32 v76, v0
	v_mov_b32_e32 v77, v0
	v_mov_b32_e32 v78, v0
	v_mov_b32_e32 v79, v0
	v_mov_b32_e32 v80, v0
	v_mov_b32_e32 v81, v0
	v_mov_b32_e32 v82, v0
	v_mov_b32_e32 v83, v0
	v_mov_b32_e32 v84, v0
	v_mov_b32_e32 v85, v0
	v_mov_b32_e32 v86, v0
	v_mov_b32_e32 v87, v0
	v_mov_b32_e32 v88, v0
	v_mov_b32_e32 v89, v0
	v_mov_b32_e32 v90, v0
	v_mov_b32_e32 v91, v0
	v_mov_b32_e32 v92, v0
	v_mov_b32_e32 v93, v0
	v_mov_b32_e32 v94, v0
	v_mov_b32_e32 v95, v0
	v_mov_b32_e32 v32, v0
	v_mov_b32_e32 v33, v0
	v_mov_b32_e32 v34, v0
	v_mov_b32_e32 v35, v0
	v_mov_b32_e32 v36, v0
	v_mov_b32_e32 v37, v0
	v_mov_b32_e32 v38, v0
	v_mov_b32_e32 v39, v0
	v_mov_b32_e32 v40, v0
	v_mov_b32_e32 v41, v0
	v_mov_b32_e32 v42, v0
	v_mov_b32_e32 v43, v0
	v_mov_b32_e32 v44, v0
	v_mov_b32_e32 v45, v0
	v_mov_b32_e32 v46, v0
	v_mov_b32_e32 v47, v0
	v_mov_b32_e32 v48, v0
	v_mov_b32_e32 v49, v0
	v_mov_b32_e32 v50, v0
	v_mov_b32_e32 v51, v0
	v_mov_b32_e32 v52, v0
	v_mov_b32_e32 v53, v0
	v_mov_b32_e32 v54, v0
	v_mov_b32_e32 v55, v0
	v_mov_b32_e32 v56, v0
	v_mov_b32_e32 v57, v0
	v_mov_b32_e32 v58, v0
	v_mov_b32_e32 v59, v0
	v_mov_b32_e32 v60, v0
	v_mov_b32_e32 v61, v0
	v_mov_b32_e32 v62, v0
	v_mov_b32_e32 v63, v0
	v_mov_b32_e32 v98, v0
	v_mov_b32_e32 v99, v0
	v_mov_b32_e32 v100, v0
	v_mov_b32_e32 v101, v0
	v_mov_b32_e32 v102, v0
	v_mov_b32_e32 v103, v0
	v_mov_b32_e32 v104, v0
	v_mov_b32_e32 v105, v0
	v_mov_b32_e32 v106, v0
	v_mov_b32_e32 v107, v0
	v_mov_b32_e32 v108, v0
	v_mov_b32_e32 v109, v0
	v_mov_b32_e32 v110, v0
	v_mov_b32_e32 v111, v0
	v_mov_b32_e32 v112, v0
	v_mov_b32_e32 v113, v0
	v_mov_b32_e32 v114, v0
	v_mov_b32_e32 v115, v0
	v_mov_b32_e32 v116, v0
	v_mov_b32_e32 v117, v0
	v_mov_b32_e32 v118, v0
	v_mov_b32_e32 v119, v0
	v_mov_b32_e32 v120, v0
	v_mov_b32_e32 v121, v0
	v_mov_b32_e32 v122, v0
	v_mov_b32_e32 v123, v0
	v_mov_b32_e32 v124, v0
	v_mov_b32_e32 v125, v0
	v_mov_b32_e32 v126, v0
	v_mov_b32_e32 v127, v0
	v_mov_b32_e32 v128, v0
	v_mov_b32_e32 v129, v0
	v_add_u32_e32 v151, s6, v96
	v_add_u32_e32 v178, s6, v142
	v_add_u32_e32 v179, s6, v138
	v_add_u32_e32 v188, s6, v140
	v_add_u32_e32 v189, s42, v96
	v_add_u32_e32 v194, s42, v142
	v_add_u32_e32 v225, s42, v138
	v_add_u32_e32 v226, s42, v140
	v_add_u32_e32 v195, s42, v151
	v_add_u32_e32 v224, s42, v178
; #define PG8_STAGE(bufoff, gbase, voff) do { _Pragma("unroll") for (int _i = 0; _i < 2; ++_i) \
;         __builtin_amdgcn_global_load_lds((const unsigned*)((const char*)(gbase) + (voff)[_i]), (PG8_LAS unsigned*)(lds + (bufoff) + ldsw + _i * 8192), 16, 0, 0); } while (0)
; #define PG8_LDA(dst, b, h) do { _Pragma("unroll") for (int m = 0; m < 4; ++m) _Pragma("unroll") for (int k = 0; k < 2; ++k) dst[m][k] = *(const PG8_LAS bf16x8*)(lds + PG8_SA(b, h) + aoff + m * 2048 + k * 1024); } while (0)
; #define PG8_LDB(dst, b, h) do { _Pragma("unroll") for (int n = 0; n < 2; ++n) _Pragma("unroll") for (int k = 0; k < 2; ++k) dst[n][k] = *(const PG8_LAS bf16x8*)(lds + PG8_SB(b, h) + boff + n * 2048 + k * 1024); } while (0)
; #define PG8_MMA(ai, bj, At, Bt) do { __builtin_amdgcn_s_setprio(1); _Pragma("unroll") for (int m = 0; m < 4; ++m) _Pragma("unroll") for (int n = 0; n < 2; ++n) _Pragma("unroll") for (int k = 0; k < 2; ++k) \
;         acc[ai][bj][m][n] = __builtin_amdgcn_mfma_f32_16x16x32_bf16(Bt[n][k], At[m][k], acc[ai][bj][m][n], 0, 0, 0); __builtin_amdgcn_s_setprio(0); } while (0)
; #define PG8_WAIT_V(n) asm volatile("s_waitcnt vmcnt(" #n ")" ::: "memory")
; #define PG8_WAIT_L(n) asm volatile("s_waitcnt lgkmcnt(" #n ")" ::: "memory")
; #define PG8_BAR __builtin_amdgcn_s_barrier()
; #define PG8_SCHED __builtin_amdgcn_sched_barrier(0)
; template <class Epi, class Sched, bool ALIGN_EPI = false, bool SP2 = false>
; __device__ __forceinline__ void gemm_phase(PG8_LAS unsigned char* lds, const Gemm g, const Sched& S, const Epi& E, int wid_s_) {
;     ...
;             PG8_LDB(B0, 0, 0); PG8_LDB(B1, 0, 1); PG8_SCHED; PG8_LDA(At, 0, 0); PG8_STAGE(PG8_SA(1, 1), a1 + hstep, voffA);
;             PG8_WAIT_V(8); PG8_WAIT_L(0); PG8_BAR; PG8_MMA(0, 0, At, B0); PG8_MMA(0, 1, At, B1); PG8_BAR; PG8_SCHED;
;             PG8_LDA(At, 0, 1); PG8_STAGE(PG8_SB(0, 0), b2, voffB); PG8_STAGE(PG8_SB(0, 1), b2 + hstep, voffB); PG8_STAGE(PG8_SA(0, 0), a2, voffA);
;             PG8_WAIT_V(8); PG8_WAIT_L(0); PG8_BAR; PG8_MMA(1, 0, At, B0); PG8_MMA(1, 1, At, B1); PG8_BAR; PG8_SCHED;
.LBB0_1393:
	s_add_i32 vcc_lo, s22, 2
	s_add_u32 s78, s20, 0x80
	s_addc_u32 s23, s21, 0
	s_add_i32 vcc_hi, 16, 0x10000
	s_cmp_eq_u32 s83, s22
	s_cselect_b32 s23, s3, s23
	s_cselect_b32 s22, s2, s78
	v_add_u32_e32 v150, vcc_hi, v147
	s_cselect_b32 s79, s19, s91
	s_cselect_b32 s78, s18, s90
	s_add_i32 s10, 16, 0x14000
	ds_read_b128 v[130:133], v150
	ds_read_b128 v[134:137], v150 offset:1024
	ds_read_b128 v[154:157], v150 offset:2048
	ds_read_b128 v[158:161], v150 offset:3072
	v_add_u32_e32 v150, s10, v147
	ds_read_b128 v[162:165], v150
	ds_read_b128 v[166:169], v150 offset:1024
	ds_read_b128 v[170:173], v150 offset:2048
	ds_read_b128 v[174:177], v150 offset:3072
	s_add_i32 m0, s48, 0xc000
	ds_read_b128 v[180:183], v149
	ds_read_b128 v[196:199], v149 offset:1024
	ds_read_b128 v[200:203], v149 offset:2048
	ds_read_b128 v[204:207], v149 offset:3072
	ds_read_b128 v[208:211], v149 offset:4096
	ds_read_b128 v[212:215], v149 offset:5120
	ds_read_b128 v[216:219], v149 offset:6144
	ds_read_b128 v[220:223], v149 offset:7168
	global_load_lds_dwordx4 v152, s[20:21]
	s_add_i32 m0, s48, 0xe000
	s_nop 0
	global_load_lds_dwordx4 v144, s[20:21]
	s_waitcnt vmcnt(8)
	s_waitcnt lgkmcnt(0)
	s_barrier
	s_setprio 1
	s_waitcnt lgkmcnt(0)
	v_mfma_f32_16x16x32_bf16 v[126:129], v[130:133], v[180:183], v[126:129]
	v_mfma_f32_16x16x32_bf16 v[122:125], v[154:157], v[180:183], v[122:125]
	v_mfma_f32_16x16x32_bf16 v[118:121], v[130:133], v[200:203], v[118:121]
	v_mfma_f32_16x16x32_bf16 v[114:117], v[154:157], v[200:203], v[114:117]
	v_mfma_f32_16x16x32_bf16 v[110:113], v[130:133], v[208:211], v[110:113]
	v_mfma_f32_16x16x32_bf16 v[106:109], v[154:157], v[208:211], v[106:109]
	v_mfma_f32_16x16x32_bf16 v[102:105], v[130:133], v[216:219], v[102:105]
	v_mfma_f32_16x16x32_bf16 v[98:101], v[154:157], v[216:219], v[98:101]
	v_mfma_f32_16x16x32_bf16 v[126:129], v[134:137], v[196:199], v[126:129]
	v_mfma_f32_16x16x32_bf16 v[122:125], v[158:161], v[196:199], v[122:125]
	v_mfma_f32_16x16x32_bf16 v[118:121], v[134:137], v[204:207], v[118:121]
	v_mfma_f32_16x16x32_bf16 v[114:117], v[158:161], v[204:207], v[114:117]
	v_mfma_f32_16x16x32_bf16 v[110:113], v[134:137], v[212:215], v[110:113]
	v_mfma_f32_16x16x32_bf16 v[106:109], v[158:161], v[212:215], v[106:109]
	v_mfma_f32_16x16x32_bf16 v[102:105], v[134:137], v[220:223], v[102:105]
	v_mfma_f32_16x16x32_bf16 v[98:101], v[158:161], v[220:223], v[98:101]
	s_setprio 0
	s_setprio 1
	v_mfma_f32_16x16x32_bf16 v[60:63], v[162:165], v[180:183], v[60:63]
	v_mfma_f32_16x16x32_bf16 v[56:59], v[170:173], v[180:183], v[56:59]
	v_mfma_f32_16x16x32_bf16 v[52:55], v[162:165], v[200:203], v[52:55]
	v_mfma_f32_16x16x32_bf16 v[48:51], v[170:173], v[200:203], v[48:51]
	v_mfma_f32_16x16x32_bf16 v[44:47], v[162:165], v[208:211], v[44:47]
	v_mfma_f32_16x16x32_bf16 v[40:43], v[170:173], v[208:211], v[40:43]
	v_mfma_f32_16x16x32_bf16 v[36:39], v[162:165], v[216:219], v[36:39]
	v_mfma_f32_16x16x32_bf16 v[32:35], v[170:173], v[216:219], v[32:35]
	v_mfma_f32_16x16x32_bf16 v[60:63], v[166:169], v[196:199], v[60:63]
	v_mfma_f32_16x16x32_bf16 v[56:59], v[174:177], v[196:199], v[56:59]
	v_mfma_f32_16x16x32_bf16 v[52:55], v[166:169], v[204:207], v[52:55]
	v_mfma_f32_16x16x32_bf16 v[48:51], v[174:177], v[204:207], v[48:51]
	v_mfma_f32_16x16x32_bf16 v[44:47], v[166:169], v[212:215], v[44:47]
	v_mfma_f32_16x16x32_bf16 v[40:43], v[174:177], v[212:215], v[40:43]
	v_mfma_f32_16x16x32_bf16 v[36:39], v[166:169], v[220:223], v[36:39]
	v_mfma_f32_16x16x32_bf16 v[32:35], v[174:177], v[220:223], v[32:35]
	s_setprio 0
	s_barrier
	s_add_i32 s11, vcc_hi, s41
	s_mov_b32 m0, s11
	ds_read_b128 v[180:183], v149 offset:16384
	ds_read_b128 v[196:199], v149 offset:17408
	ds_read_b128 v[200:203], v149 offset:18432
	ds_read_b128 v[204:207], v149 offset:19456
	ds_read_b128 v[208:211], v149 offset:20480
	ds_read_b128 v[212:215], v149 offset:21504
	ds_read_b128 v[216:219], v149 offset:22528
	ds_read_b128 v[220:223], v149 offset:23552
	global_load_lds_dwordx4 v96, s[78:79]
	s_add_i32 m0, s11, 0x2000
	s_add_i32 s10, s10, s41
	global_load_lds_dwordx4 v142, s[78:79]
	s_mov_b32 m0, s10
	s_nop 0
	global_load_lds_dwordx4 v151, s[78:79]
	s_add_i32 m0, s10, 0x2000
	s_nop 0
	global_load_lds_dwordx4 v178, s[78:79]
	s_mov_b32 m0, s48
	s_nop 0
	global_load_lds_dwordx4 v138, s[22:23]
	s_mov_b32 m0, s49
	s_nop 0
	global_load_lds_dwordx4 v140, s[22:23]
	s_waitcnt vmcnt(8)
	s_waitcnt lgkmcnt(0)
	s_barrier
	s_setprio 1
	s_waitcnt lgkmcnt(0)
	v_mfma_f32_16x16x32_bf16 v[92:95], v[130:133], v[180:183], v[92:95]
	v_mfma_f32_16x16x32_bf16 v[88:91], v[154:157], v[180:183], v[88:91]
	v_mfma_f32_16x16x32_bf16 v[84:87], v[130:133], v[200:203], v[84:87]
	v_mfma_f32_16x16x32_bf16 v[80:83], v[154:157], v[200:203], v[80:83]
	v_mfma_f32_16x16x32_bf16 v[76:79], v[130:133], v[208:211], v[76:79]
	v_mfma_f32_16x16x32_bf16 v[72:75], v[154:157], v[208:211], v[72:75]
	v_mfma_f32_16x16x32_bf16 v[68:71], v[130:133], v[216:219], v[68:71]
	v_mfma_f32_16x16x32_bf16 v[64:67], v[154:157], v[216:219], v[64:67]
	v_mfma_f32_16x16x32_bf16 v[92:95], v[134:137], v[196:199], v[92:95]
	v_mfma_f32_16x16x32_bf16 v[88:91], v[158:161], v[196:199], v[88:91]
	v_mfma_f32_16x16x32_bf16 v[84:87], v[134:137], v[204:207], v[84:87]
	v_mfma_f32_16x16x32_bf16 v[80:83], v[158:161], v[204:207], v[80:83]
	v_mfma_f32_16x16x32_bf16 v[76:79], v[134:137], v[212:215], v[76:79]
	v_mfma_f32_16x16x32_bf16 v[72:75], v[158:161], v[212:215], v[72:75]
	v_mfma_f32_16x16x32_bf16 v[68:71], v[134:137], v[220:223], v[68:71]
	v_mfma_f32_16x16x32_bf16 v[64:67], v[158:161], v[220:223], v[64:67]
	s_setprio 0
	s_setprio 1
	v_mfma_f32_16x16x32_bf16 v[28:31], v[162:165], v[180:183], v[28:31]
	v_mfma_f32_16x16x32_bf16 v[24:27], v[170:173], v[180:183], v[24:27]
	v_mfma_f32_16x16x32_bf16 v[20:23], v[162:165], v[200:203], v[20:23]
	v_mfma_f32_16x16x32_bf16 v[16:19], v[170:173], v[200:203], v[16:19]
	v_mfma_f32_16x16x32_bf16 v[12:15], v[162:165], v[208:211], v[12:15]
	v_mfma_f32_16x16x32_bf16 v[8:11], v[170:173], v[208:211], v[8:11]
	v_mfma_f32_16x16x32_bf16 v[4:7], v[162:165], v[216:219], v[4:7]
	v_mfma_f32_16x16x32_bf16 v[0:3], v[170:173], v[216:219], v[0:3]
	v_mfma_f32_16x16x32_bf16 v[28:31], v[166:169], v[196:199], v[28:31]
	v_mfma_f32_16x16x32_bf16 v[24:27], v[174:177], v[196:199], v[24:27]
	v_mfma_f32_16x16x32_bf16 v[20:23], v[166:169], v[204:207], v[20:23]
	v_mfma_f32_16x16x32_bf16 v[16:19], v[174:177], v[204:207], v[16:19]
	v_mfma_f32_16x16x32_bf16 v[12:15], v[166:169], v[212:215], v[12:15]
	v_mfma_f32_16x16x32_bf16 v[8:11], v[174:177], v[212:215], v[8:11]
	v_mfma_f32_16x16x32_bf16 v[4:7], v[166:169], v[220:223], v[4:7]
	v_mfma_f32_16x16x32_bf16 v[0:3], v[174:177], v[220:223], v[0:3]
	s_setprio 0
	s_barrier
; #define PG8_STAGE(bufoff, gbase, voff) do { _Pragma("unroll") for (int _i = 0; _i < 2; ++_i) \
;         __builtin_amdgcn_global_load_lds((const unsigned*)((const char*)(gbase) + (voff)[_i]), (PG8_LAS unsigned*)(lds + (bufoff) + ldsw + _i * 8192), 16, 0, 0); } while (0)
; #define PG8_LDA(dst, b, h) do { _Pragma("unroll") for (int m = 0; m < 4; ++m) _Pragma("unroll") for (int k = 0; k < 2; ++k) dst[m][k] = *(const PG8_LAS bf16x8*)(lds + PG8_SA(b, h) + aoff + m * 2048 + k * 1024); } while (0)
; #define PG8_LDB(dst, b, h) do { _Pragma("unroll") for (int n = 0; n < 2; ++n) _Pragma("unroll") for (int k = 0; k < 2; ++k) dst[n][k] = *(const PG8_LAS bf16x8*)(lds + PG8_SB(b, h) + boff + n * 2048 + k * 1024); } while (0)
; #define PG8_MMA(ai, bj, At, Bt) do { __builtin_amdgcn_s_setprio(1); _Pragma("unroll") for (int m = 0; m < 4; ++m) _Pragma("unroll") for (int n = 0; n < 2; ++n) _Pragma("unroll") for (int k = 0; k < 2; ++k) \
;         acc[ai][bj][m][n] = __builtin_amdgcn_mfma_f32_16x16x32_bf16(Bt[n][k], At[m][k], acc[ai][bj][m][n], 0, 0, 0); __builtin_amdgcn_s_setprio(0); } while (0)
; #define PG8_WAIT_V(n) asm volatile("s_waitcnt vmcnt(" #n ")" ::: "memory")
; #define PG8_WAIT_L(n) asm volatile("s_waitcnt lgkmcnt(" #n ")" ::: "memory")
; #define PG8_BAR __builtin_amdgcn_s_barrier()
; #define PG8_SCHED __builtin_amdgcn_sched_barrier(0)
; template <class Epi, class Sched, bool ALIGN_EPI = false, bool SP2 = false>
; __device__ __forceinline__ void gemm_phase(PG8_LAS unsigned char* lds, const Gemm g, const Sched& S, const Epi& E, int wid_s_) {
;     ...
;             PG8_LDB(B0, 1, 0); PG8_LDB(B1, 1, 1); PG8_SCHED; PG8_LDA(At, 1, 0); PG8_STAGE(PG8_SA(0, 1), a2 + hstep, voffA);
;             PG8_WAIT_V(8); PG8_WAIT_L(0); PG8_BAR; PG8_MMA(0, 0, At, B0); PG8_MMA(0, 1, At, B1); PG8_BAR; PG8_SCHED;
;             PG8_LDA(At, 1, 1); PG8_STAGE(PG8_SB(1, 0), b3, voffB); PG8_STAGE(PG8_SB(1, 1), b3 + hstep, voffB); PG8_STAGE(PG8_SA(1, 0), a3, voffA);
;             PG8_WAIT_V(8); PG8_WAIT_L(0); PG8_BAR; PG8_MMA(1, 0, At, B0); PG8_MMA(1, 1, At, B1); PG8_BAR; PG8_SCHED;
	s_add_i32 s10, 16, 0x18000
	s_add_i32 s11, 16, 0x1c000
	v_add_u32_e32 v158, s10, v147
	v_add_u32_e32 v174, s11, v147
	ds_read_b128 v[130:133], v158
	ds_read_b128 v[134:137], v158 offset:1024
	ds_read_b128 v[154:157], v158 offset:2048
	ds_read_b128 v[158:161], v158 offset:3072
	ds_read_b128 v[162:165], v174
	ds_read_b128 v[166:169], v174 offset:1024
	ds_read_b128 v[170:173], v174 offset:2048
	ds_read_b128 v[174:177], v174 offset:3072
	s_mov_b32 m0, s50
	ds_read_b128 v[180:183], v149 offset:32768
	ds_read_b128 v[196:199], v149 offset:33792
	ds_read_b128 v[200:203], v149 offset:34816
	ds_read_b128 v[204:207], v149 offset:35840
	ds_read_b128 v[208:211], v149 offset:36864
	ds_read_b128 v[212:215], v149 offset:37888
	ds_read_b128 v[216:219], v149 offset:38912
	ds_read_b128 v[220:223], v149 offset:39936
	global_load_lds_dwordx4 v179, s[22:23]
	s_mov_b32 m0, s51
	s_nop 0
	global_load_lds_dwordx4 v188, s[22:23]
	s_waitcnt vmcnt(8)
	s_waitcnt lgkmcnt(0)
	s_barrier
	s_setprio 1
	s_waitcnt lgkmcnt(0)
	v_mfma_f32_16x16x32_bf16 v[126:129], v[130:133], v[180:183], v[126:129]
	v_mfma_f32_16x16x32_bf16 v[122:125], v[154:157], v[180:183], v[122:125]
	v_mfma_f32_16x16x32_bf16 v[118:121], v[130:133], v[200:203], v[118:121]
	v_mfma_f32_16x16x32_bf16 v[114:117], v[154:157], v[200:203], v[114:117]
	v_mfma_f32_16x16x32_bf16 v[110:113], v[130:133], v[208:211], v[110:113]
	v_mfma_f32_16x16x32_bf16 v[106:109], v[154:157], v[208:211], v[106:109]
	v_mfma_f32_16x16x32_bf16 v[102:105], v[130:133], v[216:219], v[102:105]
	v_mfma_f32_16x16x32_bf16 v[98:101], v[154:157], v[216:219], v[98:101]
	v_mfma_f32_16x16x32_bf16 v[126:129], v[134:137], v[196:199], v[126:129]
	v_mfma_f32_16x16x32_bf16 v[122:125], v[158:161], v[196:199], v[122:125]
	v_mfma_f32_16x16x32_bf16 v[118:121], v[134:137], v[204:207], v[118:121]
	v_mfma_f32_16x16x32_bf16 v[114:117], v[158:161], v[204:207], v[114:117]
	v_mfma_f32_16x16x32_bf16 v[110:113], v[134:137], v[212:215], v[110:113]
	v_mfma_f32_16x16x32_bf16 v[106:109], v[158:161], v[212:215], v[106:109]
	v_mfma_f32_16x16x32_bf16 v[102:105], v[134:137], v[220:223], v[102:105]
	v_mfma_f32_16x16x32_bf16 v[98:101], v[158:161], v[220:223], v[98:101]
	s_setprio 0
	s_setprio 1
	v_mfma_f32_16x16x32_bf16 v[60:63], v[162:165], v[180:183], v[60:63]
	v_mfma_f32_16x16x32_bf16 v[56:59], v[170:173], v[180:183], v[56:59]
	v_mfma_f32_16x16x32_bf16 v[52:55], v[162:165], v[200:203], v[52:55]
	v_mfma_f32_16x16x32_bf16 v[48:51], v[170:173], v[200:203], v[48:51]
	v_mfma_f32_16x16x32_bf16 v[44:47], v[162:165], v[208:211], v[44:47]
	v_mfma_f32_16x16x32_bf16 v[40:43], v[170:173], v[208:211], v[40:43]
	v_mfma_f32_16x16x32_bf16 v[36:39], v[162:165], v[216:219], v[36:39]
	v_mfma_f32_16x16x32_bf16 v[32:35], v[170:173], v[216:219], v[32:35]
	v_mfma_f32_16x16x32_bf16 v[60:63], v[166:169], v[196:199], v[60:63]
	v_mfma_f32_16x16x32_bf16 v[56:59], v[174:177], v[196:199], v[56:59]
	v_mfma_f32_16x16x32_bf16 v[52:55], v[166:169], v[204:207], v[52:55]
	v_mfma_f32_16x16x32_bf16 v[48:51], v[174:177], v[204:207], v[48:51]
	v_mfma_f32_16x16x32_bf16 v[44:47], v[166:169], v[212:215], v[44:47]
	v_mfma_f32_16x16x32_bf16 v[40:43], v[174:177], v[212:215], v[40:43]
	v_mfma_f32_16x16x32_bf16 v[36:39], v[166:169], v[220:223], v[36:39]
	v_mfma_f32_16x16x32_bf16 v[32:35], v[174:177], v[220:223], v[32:35]
	s_setprio 0
	s_barrier
	s_add_i32 s10, s10, s41
	s_mov_b32 m0, s10
	ds_read_b128 v[180:183], v149 offset:49152
	ds_read_b128 v[196:199], v149 offset:50176
	ds_read_b128 v[200:203], v149 offset:51200
	ds_read_b128 v[204:207], v149 offset:52224
	ds_read_b128 v[208:211], v149 offset:53248
	ds_read_b128 v[212:215], v149 offset:54272
	ds_read_b128 v[216:219], v149 offset:55296
	ds_read_b128 v[220:223], v149 offset:56320
	global_load_lds_dwordx4 v189, s[78:79]
	s_add_i32 m0, s10, 0x2000
	s_add_i32 s10, s11, s41
	global_load_lds_dwordx4 v194, s[78:79]
	s_mov_b32 m0, s10
	s_nop 0
	global_load_lds_dwordx4 v195, s[78:79]
	s_add_i32 m0, s10, 0x2000
	s_nop 0
	global_load_lds_dwordx4 v224, s[78:79]
	s_mov_b32 m0, s81
	s_nop 0
	global_load_lds_dwordx4 v225, s[22:23]
	s_mov_b32 m0, s82
	s_nop 0
	global_load_lds_dwordx4 v226, s[22:23]
	s_waitcnt vmcnt(8)
	s_waitcnt lgkmcnt(0)
	s_barrier
	s_setprio 1
	s_waitcnt lgkmcnt(0)
	v_mfma_f32_16x16x32_bf16 v[92:95], v[130:133], v[180:183], v[92:95]
	v_mfma_f32_16x16x32_bf16 v[88:91], v[154:157], v[180:183], v[88:91]
	v_mfma_f32_16x16x32_bf16 v[84:87], v[130:133], v[200:203], v[84:87]
	v_mfma_f32_16x16x32_bf16 v[80:83], v[154:157], v[200:203], v[80:83]
	v_mfma_f32_16x16x32_bf16 v[76:79], v[130:133], v[208:211], v[76:79]
	v_mfma_f32_16x16x32_bf16 v[72:75], v[154:157], v[208:211], v[72:75]
	v_mfma_f32_16x16x32_bf16 v[68:71], v[130:133], v[216:219], v[68:71]
	v_mfma_f32_16x16x32_bf16 v[64:67], v[154:157], v[216:219], v[64:67]
	v_mfma_f32_16x16x32_bf16 v[92:95], v[134:137], v[196:199], v[92:95]
	v_mfma_f32_16x16x32_bf16 v[88:91], v[158:161], v[196:199], v[88:91]
	v_mfma_f32_16x16x32_bf16 v[84:87], v[134:137], v[204:207], v[84:87]
	v_mfma_f32_16x16x32_bf16 v[80:83], v[158:161], v[204:207], v[80:83]
	v_mfma_f32_16x16x32_bf16 v[76:79], v[134:137], v[212:215], v[76:79]
	v_mfma_f32_16x16x32_bf16 v[72:75], v[158:161], v[212:215], v[72:75]
	v_mfma_f32_16x16x32_bf16 v[68:71], v[134:137], v[220:223], v[68:71]
	v_mfma_f32_16x16x32_bf16 v[64:67], v[158:161], v[220:223], v[64:67]
	s_setprio 0
	s_setprio 1
	v_mfma_f32_16x16x32_bf16 v[28:31], v[162:165], v[180:183], v[28:31]
	v_mfma_f32_16x16x32_bf16 v[24:27], v[170:173], v[180:183], v[24:27]
	v_mfma_f32_16x16x32_bf16 v[20:23], v[162:165], v[200:203], v[20:23]
	v_mfma_f32_16x16x32_bf16 v[16:19], v[170:173], v[200:203], v[16:19]
	v_mfma_f32_16x16x32_bf16 v[12:15], v[162:165], v[208:211], v[12:15]
	v_mfma_f32_16x16x32_bf16 v[8:11], v[170:173], v[208:211], v[8:11]
	v_mfma_f32_16x16x32_bf16 v[4:7], v[162:165], v[216:219], v[4:7]
	v_mfma_f32_16x16x32_bf16 v[0:3], v[170:173], v[216:219], v[0:3]
	v_mfma_f32_16x16x32_bf16 v[28:31], v[166:169], v[196:199], v[28:31]
	v_mfma_f32_16x16x32_bf16 v[24:27], v[174:177], v[196:199], v[24:27]
	v_mfma_f32_16x16x32_bf16 v[20:23], v[166:169], v[204:207], v[20:23]
	v_mfma_f32_16x16x32_bf16 v[16:19], v[174:177], v[204:207], v[16:19]
	v_mfma_f32_16x16x32_bf16 v[12:15], v[166:169], v[212:215], v[12:15]
	v_mfma_f32_16x16x32_bf16 v[8:11], v[174:177], v[212:215], v[8:11]
	v_mfma_f32_16x16x32_bf16 v[4:7], v[166:169], v[220:223], v[4:7]
	v_mfma_f32_16x16x32_bf16 v[0:3], v[174:177], v[220:223], v[0:3]
	s_setprio 0
	s_barrier
	s_add_u32 s90, s90, 0x100
	s_addc_u32 s91, s91, 0
	s_add_u32 s20, s20, 0x100
	s_addc_u32 s21, s21, 0
	s_cmp_ge_i32 vcc_lo, s80
	s_mov_b32 s22, vcc_lo
	s_cbranch_scc0 .LBB0_1393
